# GEMM mainloop heads aligned to 64 bytes with s_nop padding ahead of each peeled first iteration
# baseline (speedup 1.0000x reference)
; DEVI size_t gemm_offB(const Gemm& g, const Unit& u) { return (g.split ? (size_t)(u.b >> 2) * g.sB + (size_t)(u.b & 3) * g.sB_lo : (size_t)u.b * g.sB) + (size_t)(u.pm >> g.pmsh) * g.sBpm; }
; #define PG8_STAGE(bufoff, gbase, voff) do { _Pragma("unroll") for (int _i = 0; _i < 2; ++_i) \
;         __builtin_amdgcn_global_load_lds((const unsigned*)((const char*)(gbase) + (voff)[_i]), (LAS unsigned*)(lds + (bufoff) + ldsw + _i * 8192), 16, 0, 0); } while (0)
; #define PG8_LDA(dst, b, h) do { _Pragma("unroll") for (int m = 0; m < 4; ++m) _Pragma("unroll") for (int k = 0; k < 2; ++k) dst[m][k] = *(const LAS bf16x8*)(lds + PG8_SA(b, h) + aoff + m * 2048 + k * 1024); } while (0)
; #define PG8_LDB(dst, b, h) do { _Pragma("unroll") for (int n = 0; n < 2; ++n) _Pragma("unroll") for (int k = 0; k < 2; ++k) dst[n][k] = *(const LAS bf16x8*)(lds + PG8_SB(b, h) + boff + n * 2048 + k * 1024); } while (0)
; #define PG8_WAIT_V(n) asm volatile("s_waitcnt vmcnt(" #n ")" ::: "memory")
; #define PG8_BAR __builtin_amdgcn_s_barrier()
; template <class Epi>
; DEVI void gemm_phase(LAS unsigned char* lds, const Gemm g, const Epi& E) {
;     ...
;         const bool has_next = unit_next(g, ui + 1, nxt);
;         const char* nA = has_next ? (const char*)g.A + gemm_offA(g, nxt) * 2 + (size_t)nxt.pm * tstepA : cA;
;         const char* nB = has_next ? (const char*)g.Bt + gemm_offB(g, nxt) * 2 + (size_t)nxt.pn * tstepB : cB;
;         for (int t = 0; t < nt; t += 2) {
;             const bool last = (t == nt - 2);
;             const char* a1 = cA + (size_t)(t + 1) * kstep;
;             const char* a2 = last ? nA : cA + (size_t)(t + 2) * kstep; const char* b2 = last ? nB : cB + (size_t)(t + 2) * kstep;
;             const char* a3 = a2 + kstep; const char* b3 = b2 + kstep;
;             PG8_LDB(B0, 0, 0); PG8_SCHED; PG8_LDA(At, 0, 0); PG8_STAGE(PG8_SA(1, 1), a1 + hstepA, voffA);
;             PG8_WAIT_L(8); PG8_BAR; PG8_WAIT_L(0); PG8_MMA(0, 0, At, B0); PG8_BAR; PG8_SCHED;
;             PG8_LDB(B1, 0, 1); PG8_STAGE(PG8_SB(0, 0), b2, voffB);
;             PG8_BAR; PG8_WAIT_L(0); PG8_MMA(0, 1, At, B1); PG8_BAR;
;             PG8_LDA(At, 0, 1); PG8_STAGE(PG8_SA(0, 0), a2, voffA);
;             PG8_BAR; PG8_WAIT_L(0); PG8_MMA(1, 0, At, B0); PG8_BAR; PG8_SCHED;
;             PG8_STAGE(PG8_SB(0, 1), b2 + hstepB, voffB);
;             PG8_WAIT_V(6); PG8_BAR; PG8_MMA(1, 1, At, B1); PG8_BAR;
.LBB0_186:
	s_ashr_i32 s17, s16, 31
	s_lshl_b64 s[24:25], s[16:17], 19
	s_add_u32 s24, s36, s24
	s_addc_u32 s25, s37, s25
	s_and_b64 s[0:1], s[0:1], exec
	s_cselect_b32 s13, s25, s27
	s_cselect_b32 s15, s24, s26
	s_add_u32 s0, s26, 0x40080
	s_addc_u32 s1, s27, 0
	s_add_u32 s17, s28, 0x100
	s_addc_u32 s49, s29, 0
	s_mov_b32 s50, -2
	s_nop 0
	s_nop 0
	s_nop 0
	s_nop 0
	s_nop 0
	ds_read_b128 v[156:159], v150
	ds_read_b128 v[160:163], v150 offset:1024
	ds_read_b128 v[164:167], v150 offset:2048
	ds_read_b128 v[168:171], v150 offset:3072
	s_add_u32 s26, s0, 0xfffc0080
	s_addc_u32 s27, s1, -1
	s_cmp_eq_u32 s50, 12
	s_cselect_b32 s29, s13, s27
	s_cselect_b32 s28, s15, s26
	s_cselect_b32 s27, s19, s49
	s_cselect_b32 s26, s18, s17
	v_lshl_add_u64 v[204:205], s[0:1], 0, v[138:139]
	s_add_i32 m0, s38, 0xc000
	ds_read_b128 v[172:175], v151
	ds_read_b128 v[176:179], v151 offset:1024
	ds_read_b128 v[180:183], v151 offset:2048
	ds_read_b128 v[184:187], v151 offset:3072
	ds_read_b128 v[188:191], v151 offset:4096
	ds_read_b128 v[192:195], v151 offset:5120
	ds_read_b128 v[196:199], v151 offset:6144
	ds_read_b128 v[200:203], v151 offset:7168
	global_load_lds_dwordx4 v[204:205], off
	s_add_i32 m0, s38, 0xe000
	v_lshl_add_u64 v[204:205], s[0:1], 0, v[140:141]
	global_load_lds_dwordx4 v[204:205], off
	s_waitcnt lgkmcnt(8)
	s_barrier
	s_waitcnt lgkmcnt(0)
	v_mfma_f32_16x16x32_bf16 v[124:127], v[156:159], v[172:175], 0
	v_mfma_f32_16x16x32_bf16 v[120:123], v[164:167], v[172:175], 0
	v_mfma_f32_16x16x32_bf16 v[116:119], v[156:159], v[180:183], 0
	v_mfma_f32_16x16x32_bf16 v[108:111], v[164:167], v[180:183], 0
	v_mfma_f32_16x16x32_bf16 v[100:103], v[156:159], v[188:191], 0
	v_mfma_f32_16x16x32_bf16 v[96:99], v[164:167], v[188:191], 0
	v_mfma_f32_16x16x32_bf16 v[84:87], v[156:159], v[196:199], 0
	v_mfma_f32_16x16x32_bf16 v[80:83], v[164:167], v[196:199], 0
	v_mfma_f32_16x16x32_bf16 v[124:127], v[160:163], v[176:179], v[124:127]
	v_mfma_f32_16x16x32_bf16 v[120:123], v[168:171], v[176:179], v[120:123]
	v_mfma_f32_16x16x32_bf16 v[116:119], v[160:163], v[184:187], v[116:119]
	v_mfma_f32_16x16x32_bf16 v[108:111], v[168:171], v[184:187], v[108:111]
	v_mfma_f32_16x16x32_bf16 v[100:103], v[160:163], v[192:195], v[100:103]
	v_mfma_f32_16x16x32_bf16 v[96:99], v[168:171], v[192:195], v[96:99]
	v_mfma_f32_16x16x32_bf16 v[84:87], v[160:163], v[200:203], v[84:87]
	v_mfma_f32_16x16x32_bf16 v[80:83], v[168:171], v[200:203], v[80:83]
	s_barrier
	s_add_i32 s51, s46, s35
	v_lshl_add_u64 v[220:221], s[26:27], 0, v[130:131]
	s_mov_b32 m0, s51
	ds_read_b128 v[204:207], v152
	ds_read_b128 v[208:211], v152 offset:1024
	ds_read_b128 v[212:215], v152 offset:2048
	ds_read_b128 v[216:219], v152 offset:3072
	global_load_lds_dwordx4 v[220:221], off
	s_add_i32 m0, s51, 0x2000
	v_lshl_add_u64 v[222:223], s[26:27], 0, v[134:135]
	global_load_lds_dwordx4 v[222:223], off
	s_barrier
	s_waitcnt lgkmcnt(0)
	v_mfma_f32_16x16x32_bf16 v[112:115], v[204:207], v[172:175], 0
	v_mfma_f32_16x16x32_bf16 v[104:107], v[212:215], v[172:175], 0
	v_mfma_f32_16x16x32_bf16 v[92:95], v[204:207], v[180:183], 0
	v_mfma_f32_16x16x32_bf16 v[88:91], v[212:215], v[180:183], 0
	v_mfma_f32_16x16x32_bf16 v[76:79], v[204:207], v[188:191], 0
	v_mfma_f32_16x16x32_bf16 v[72:75], v[212:215], v[188:191], 0
	v_mfma_f32_16x16x32_bf16 v[68:71], v[204:207], v[196:199], 0
	v_mfma_f32_16x16x32_bf16 v[64:67], v[212:215], v[196:199], 0
	v_mfma_f32_16x16x32_bf16 v[112:115], v[208:211], v[176:179], v[112:115]
	v_mfma_f32_16x16x32_bf16 v[104:107], v[216:219], v[176:179], v[104:107]
	v_mfma_f32_16x16x32_bf16 v[92:95], v[208:211], v[184:187], v[92:95]
	v_mfma_f32_16x16x32_bf16 v[88:91], v[216:219], v[184:187], v[88:91]
	v_mfma_f32_16x16x32_bf16 v[76:79], v[208:211], v[192:195], v[76:79]
	v_mfma_f32_16x16x32_bf16 v[72:75], v[216:219], v[192:195], v[72:75]
	v_mfma_f32_16x16x32_bf16 v[68:71], v[208:211], v[200:203], v[68:71]
	v_mfma_f32_16x16x32_bf16 v[64:67], v[216:219], v[200:203], v[64:67]
	s_mov_b32 m0, s38
	v_lshl_add_u64 v[224:225], s[28:29], 0, v[128:129]
	s_barrier
	ds_read_b128 v[172:175], v151 offset:16384
	ds_read_b128 v[176:179], v151 offset:17408
	ds_read_b128 v[180:183], v151 offset:18432
	ds_read_b128 v[184:187], v151 offset:19456
	ds_read_b128 v[188:191], v151 offset:20480
	ds_read_b128 v[192:195], v151 offset:21504
	ds_read_b128 v[196:199], v151 offset:22528
	ds_read_b128 v[200:203], v151 offset:23552
	global_load_lds_dwordx4 v[224:225], off
	s_mov_b32 m0, s39
	v_lshl_add_u64 v[226:227], s[28:29], 0, v[132:133]
	global_load_lds_dwordx4 v[226:227], off
	s_barrier
	s_waitcnt lgkmcnt(0)
	v_mfma_f32_16x16x32_bf16 v[60:63], v[156:159], v[172:175], 0
	v_mfma_f32_16x16x32_bf16 v[56:59], v[164:167], v[172:175], 0
	v_mfma_f32_16x16x32_bf16 v[52:55], v[156:159], v[180:183], 0
	v_mfma_f32_16x16x32_bf16 v[48:51], v[164:167], v[180:183], 0
	v_mfma_f32_16x16x32_bf16 v[36:39], v[156:159], v[188:191], 0
	v_mfma_f32_16x16x32_bf16 v[32:35], v[164:167], v[188:191], 0
	v_mfma_f32_16x16x32_bf16 v[20:23], v[156:159], v[196:199], 0
	v_mfma_f32_16x16x32_bf16 v[16:19], v[164:167], v[196:199], 0
	v_mfma_f32_16x16x32_bf16 v[60:63], v[160:163], v[176:179], v[60:63]
	v_mfma_f32_16x16x32_bf16 v[56:59], v[168:171], v[176:179], v[56:59]
	v_mfma_f32_16x16x32_bf16 v[52:55], v[160:163], v[184:187], v[52:55]
	v_mfma_f32_16x16x32_bf16 v[48:51], v[168:171], v[184:187], v[48:51]
	v_mfma_f32_16x16x32_bf16 v[36:39], v[160:163], v[192:195], v[36:39]
	v_mfma_f32_16x16x32_bf16 v[32:35], v[168:171], v[192:195], v[32:35]
	v_mfma_f32_16x16x32_bf16 v[20:23], v[160:163], v[200:203], v[20:23]
	v_mfma_f32_16x16x32_bf16 v[16:19], v[168:171], v[200:203], v[16:19]
	s_barrier
; #define PG8_STAGE(bufoff, gbase, voff) do { _Pragma("unroll") for (int _i = 0; _i < 2; ++_i) \
;         __builtin_amdgcn_global_load_lds((const unsigned*)((const char*)(gbase) + (voff)[_i]), (LAS unsigned*)(lds + (bufoff) + ldsw + _i * 8192), 16, 0, 0); } while (0)
; #define PG8_LDA(dst, b, h) do { _Pragma("unroll") for (int m = 0; m < 4; ++m) _Pragma("unroll") for (int k = 0; k < 2; ++k) dst[m][k] = *(const LAS bf16x8*)(lds + PG8_SA(b, h) + aoff + m * 2048 + k * 1024); } while (0)
; #define PG8_LDB(dst, b, h) do { _Pragma("unroll") for (int n = 0; n < 2; ++n) _Pragma("unroll") for (int k = 0; k < 2; ++k) dst[n][k] = *(const LAS bf16x8*)(lds + PG8_SB(b, h) + boff + n * 2048 + k * 1024); } while (0)
; #define PG8_MMA(ai, bj, At, Bt) do { __builtin_amdgcn_s_setprio(1); _Pragma("unroll") for (int m = 0; m < 4; ++m) _Pragma("unroll") for (int n = 0; n < 2; ++n) _Pragma("unroll") for (int k = 0; k < 2; ++k) \
;         acc[ai][bj][m][n] = __builtin_amdgcn_mfma_f32_16x16x32_bf16(Bt[n][k], At[m][k], acc[ai][bj][m][n], 0, 0, 0); __builtin_amdgcn_s_setprio(0); } while (0)
; #define PG8_WAIT_V(n) asm volatile("s_waitcnt vmcnt(" #n ")" ::: "memory")
; #define PG8_WAIT_L(n) asm volatile("s_waitcnt lgkmcnt(" #n ")" ::: "memory")
; #define PG8_BAR __builtin_amdgcn_s_barrier()
; #define PG8_SCHED __builtin_amdgcn_sched_barrier(0)
; template <class Epi>
; DEVI void gemm_phase(LAS unsigned char* lds, const Gemm g, const Epi& E) {
;     ...
;             PG8_STAGE(PG8_SB(0, 1), b2 + hstepB, voffB);
;             PG8_WAIT_V(6); PG8_BAR; PG8_MMA(1, 1, At, B1); PG8_BAR;
;             PG8_LDB(B0, 1, 0); PG8_SCHED; PG8_LDA(At, 1, 0); PG8_STAGE(PG8_SA(0, 1), a2 + hstepA, voffA);
;             PG8_WAIT_L(8); PG8_BAR; PG8_WAIT_L(0); PG8_MMA(0, 0, At, B0); PG8_BAR; PG8_SCHED;
;             PG8_LDB(B1, 1, 1); PG8_STAGE(PG8_SB(1, 0), b3, voffB);
;             PG8_BAR; PG8_WAIT_L(0); PG8_MMA(0, 1, At, B1); PG8_BAR;
;             PG8_LDA(At, 1, 1); PG8_STAGE(PG8_SA(1, 0), a3, voffA);
	s_add_u32 s52, s26, 0x40000
	s_addc_u32 s53, s27, 0
	s_add_i32 s51, s47, s35
	s_mov_b32 m0, s51
	v_lshl_add_u64 v[156:157], s[52:53], 0, v[130:131]
	global_load_lds_dwordx4 v[156:157], off
	s_add_i32 m0, s51, 0x2000
	v_lshl_add_u64 v[156:157], s[52:53], 0, v[134:135]
	global_load_lds_dwordx4 v[156:157], off
	s_waitcnt vmcnt(6)
	s_barrier
	v_mfma_f32_16x16x32_bf16 v[44:47], v[204:207], v[172:175], 0
	v_mfma_f32_16x16x32_bf16 v[40:43], v[212:215], v[172:175], 0
	v_mfma_f32_16x16x32_bf16 v[28:31], v[204:207], v[180:183], 0
	v_mfma_f32_16x16x32_bf16 v[24:27], v[212:215], v[180:183], 0
	v_mfma_f32_16x16x32_bf16 v[12:15], v[204:207], v[188:191], 0
	v_mfma_f32_16x16x32_bf16 v[8:11], v[212:215], v[188:191], 0
	v_mfma_f32_16x16x32_bf16 v[4:7], v[204:207], v[196:199], 0
	v_mfma_f32_16x16x32_bf16 v[0:3], v[212:215], v[196:199], 0
	v_mfma_f32_16x16x32_bf16 v[44:47], v[208:211], v[176:179], v[44:47]
	v_mfma_f32_16x16x32_bf16 v[40:43], v[216:219], v[176:179], v[40:43]
	v_mfma_f32_16x16x32_bf16 v[28:31], v[208:211], v[184:187], v[28:31]
	v_mfma_f32_16x16x32_bf16 v[24:27], v[216:219], v[184:187], v[24:27]
	v_mfma_f32_16x16x32_bf16 v[12:15], v[208:211], v[192:195], v[12:15]
	v_mfma_f32_16x16x32_bf16 v[8:11], v[216:219], v[192:195], v[8:11]
	v_mfma_f32_16x16x32_bf16 v[4:7], v[208:211], v[200:203], v[4:7]
	v_mfma_f32_16x16x32_bf16 v[0:3], v[216:219], v[200:203], v[0:3]
	s_add_i32 s51, 0, 0x18000
	v_add_u32_e32 v136, s51, v148
	s_barrier
	ds_read_b128 v[156:159], v136
	ds_read_b128 v[160:163], v136 offset:1024
	ds_read_b128 v[164:167], v136 offset:2048
	ds_read_b128 v[168:171], v136 offset:3072
	s_add_u32 s28, s28, 0x40000
	s_addc_u32 s29, s29, 0
	s_mov_b32 m0, s40
	v_lshl_add_u64 v[204:205], s[28:29], 0, v[128:129]
	ds_read_b128 v[172:175], v151 offset:32768
	ds_read_b128 v[176:179], v151 offset:33792
	ds_read_b128 v[180:183], v151 offset:34816
	ds_read_b128 v[184:187], v151 offset:35840
	ds_read_b128 v[188:191], v151 offset:36864
	ds_read_b128 v[192:195], v151 offset:37888
	ds_read_b128 v[196:199], v151 offset:38912
	ds_read_b128 v[200:203], v151 offset:39936
	global_load_lds_dwordx4 v[204:205], off
	s_mov_b32 m0, s41
	v_lshl_add_u64 v[204:205], s[28:29], 0, v[132:133]
	global_load_lds_dwordx4 v[204:205], off
	s_waitcnt lgkmcnt(8)
	s_barrier
	s_waitcnt lgkmcnt(0)
	v_mfma_f32_16x16x32_bf16 v[124:127], v[156:159], v[172:175], v[124:127]
	v_mfma_f32_16x16x32_bf16 v[120:123], v[164:167], v[172:175], v[120:123]
	v_mfma_f32_16x16x32_bf16 v[116:119], v[156:159], v[180:183], v[116:119]
	v_mfma_f32_16x16x32_bf16 v[108:111], v[164:167], v[180:183], v[108:111]
	v_mfma_f32_16x16x32_bf16 v[100:103], v[156:159], v[188:191], v[100:103]
	v_mfma_f32_16x16x32_bf16 v[96:99], v[164:167], v[188:191], v[96:99]
	v_mfma_f32_16x16x32_bf16 v[84:87], v[156:159], v[196:199], v[84:87]
	v_mfma_f32_16x16x32_bf16 v[80:83], v[164:167], v[196:199], v[80:83]
	v_mfma_f32_16x16x32_bf16 v[124:127], v[160:163], v[176:179], v[124:127]
	v_mfma_f32_16x16x32_bf16 v[120:123], v[168:171], v[176:179], v[120:123]
	v_mfma_f32_16x16x32_bf16 v[116:119], v[160:163], v[184:187], v[116:119]
	v_mfma_f32_16x16x32_bf16 v[108:111], v[168:171], v[184:187], v[108:111]
	v_mfma_f32_16x16x32_bf16 v[100:103], v[160:163], v[192:195], v[100:103]
	v_mfma_f32_16x16x32_bf16 v[96:99], v[168:171], v[192:195], v[96:99]
	v_mfma_f32_16x16x32_bf16 v[84:87], v[160:163], v[200:203], v[84:87]
	v_mfma_f32_16x16x32_bf16 v[80:83], v[168:171], v[200:203], v[80:83]
	s_barrier
	s_add_i32 s28, 0, 0x1c000
	s_add_i32 s29, s51, s35
	v_add_u32_e32 v136, s28, v148
	v_lshl_add_u64 v[220:221], v[220:221], 0, s[8:9]
	s_mov_b32 m0, s29
	ds_read_b128 v[204:207], v136
	ds_read_b128 v[208:211], v136 offset:1024
	ds_read_b128 v[212:215], v136 offset:2048
	ds_read_b128 v[216:219], v136 offset:3072
	global_load_lds_dwordx4 v[220:221], off
	s_add_i32 m0, s29, 0x2000
	v_lshl_add_u64 v[220:221], v[222:223], 0, s[8:9]
	global_load_lds_dwordx4 v[220:221], off
	s_barrier
; #define PG8_STAGE(bufoff, gbase, voff) do { _Pragma("unroll") for (int _i = 0; _i < 2; ++_i) \
;         __builtin_amdgcn_global_load_lds((const unsigned*)((const char*)(gbase) + (voff)[_i]), (LAS unsigned*)(lds + (bufoff) + ldsw + _i * 8192), 16, 0, 0); } while (0)
; #define PG8_LDA(dst, b, h) do { _Pragma("unroll") for (int m = 0; m < 4; ++m) _Pragma("unroll") for (int k = 0; k < 2; ++k) dst[m][k] = *(const LAS bf16x8*)(lds + PG8_SA(b, h) + aoff + m * 2048 + k * 1024); } while (0)
; #define PG8_MMA(ai, bj, At, Bt) do { __builtin_amdgcn_s_setprio(1); _Pragma("unroll") for (int m = 0; m < 4; ++m) _Pragma("unroll") for (int n = 0; n < 2; ++n) _Pragma("unroll") for (int k = 0; k < 2; ++k) \
;         acc[ai][bj][m][n] = __builtin_amdgcn_mfma_f32_16x16x32_bf16(Bt[n][k], At[m][k], acc[ai][bj][m][n], 0, 0, 0); __builtin_amdgcn_s_setprio(0); } while (0)
; #define PG8_WAIT_V(n) asm volatile("s_waitcnt vmcnt(" #n ")" ::: "memory")
; #define PG8_WAIT_L(n) asm volatile("s_waitcnt lgkmcnt(" #n ")" ::: "memory")
; #define PG8_BAR __builtin_amdgcn_s_barrier()
; #define PG8_SCHED __builtin_amdgcn_sched_barrier(0)
; template <class Epi>
; DEVI void gemm_phase(LAS unsigned char* lds, const Gemm g, const Epi& E) {
;     ...
;             PG8_BAR; PG8_WAIT_L(0); PG8_MMA(0, 1, At, B1); PG8_BAR;
;             PG8_LDA(At, 1, 1); PG8_STAGE(PG8_SA(1, 0), a3, voffA);
;             PG8_BAR; PG8_WAIT_L(0); PG8_MMA(1, 0, At, B0); PG8_BAR; PG8_SCHED;
;             PG8_STAGE(PG8_SB(1, 1), b3 + hstepB, voffB);
;             PG8_WAIT_V(6); PG8_BAR; PG8_MMA(1, 1, At, B1); PG8_BAR;
;         }
	s_waitcnt lgkmcnt(0)
	v_mfma_f32_16x16x32_bf16 v[112:115], v[204:207], v[172:175], v[112:115]
	v_mfma_f32_16x16x32_bf16 v[104:107], v[212:215], v[172:175], v[104:107]
	v_mfma_f32_16x16x32_bf16 v[92:95], v[204:207], v[180:183], v[92:95]
	v_mfma_f32_16x16x32_bf16 v[88:91], v[212:215], v[180:183], v[88:91]
	v_mfma_f32_16x16x32_bf16 v[76:79], v[204:207], v[188:191], v[76:79]
	v_mfma_f32_16x16x32_bf16 v[72:75], v[212:215], v[188:191], v[72:75]
	v_mfma_f32_16x16x32_bf16 v[68:71], v[204:207], v[196:199], v[68:71]
	v_mfma_f32_16x16x32_bf16 v[64:67], v[212:215], v[196:199], v[64:67]
	v_mfma_f32_16x16x32_bf16 v[112:115], v[208:211], v[176:179], v[112:115]
	v_mfma_f32_16x16x32_bf16 v[104:107], v[216:219], v[176:179], v[104:107]
	v_mfma_f32_16x16x32_bf16 v[92:95], v[208:211], v[184:187], v[92:95]
	v_mfma_f32_16x16x32_bf16 v[88:91], v[216:219], v[184:187], v[88:91]
	v_mfma_f32_16x16x32_bf16 v[76:79], v[208:211], v[192:195], v[76:79]
	v_mfma_f32_16x16x32_bf16 v[72:75], v[216:219], v[192:195], v[72:75]
	v_mfma_f32_16x16x32_bf16 v[68:71], v[208:211], v[200:203], v[68:71]
	v_mfma_f32_16x16x32_bf16 v[64:67], v[216:219], v[200:203], v[64:67]
	s_mov_b32 m0, s44
	v_lshl_add_u64 v[220:221], v[224:225], 0, s[8:9]
	s_barrier
	ds_read_b128 v[172:175], v151 offset:49152
	ds_read_b128 v[176:179], v151 offset:50176
	ds_read_b128 v[180:183], v151 offset:51200
	ds_read_b128 v[184:187], v151 offset:52224
	ds_read_b128 v[188:191], v151 offset:53248
	ds_read_b128 v[192:195], v151 offset:54272
	ds_read_b128 v[196:199], v151 offset:55296
	ds_read_b128 v[200:203], v151 offset:56320
	global_load_lds_dwordx4 v[220:221], off
	s_mov_b32 m0, s45
	v_lshl_add_u64 v[220:221], v[226:227], 0, s[8:9]
	global_load_lds_dwordx4 v[220:221], off
	s_barrier
	s_waitcnt lgkmcnt(0)
	v_mfma_f32_16x16x32_bf16 v[60:63], v[156:159], v[172:175], v[60:63]
	v_mfma_f32_16x16x32_bf16 v[56:59], v[164:167], v[172:175], v[56:59]
	v_mfma_f32_16x16x32_bf16 v[52:55], v[156:159], v[180:183], v[52:55]
	v_mfma_f32_16x16x32_bf16 v[48:51], v[164:167], v[180:183], v[48:51]
	v_mfma_f32_16x16x32_bf16 v[36:39], v[156:159], v[188:191], v[36:39]
	v_mfma_f32_16x16x32_bf16 v[32:35], v[164:167], v[188:191], v[32:35]
	v_mfma_f32_16x16x32_bf16 v[20:23], v[156:159], v[196:199], v[20:23]
	v_mfma_f32_16x16x32_bf16 v[16:19], v[164:167], v[196:199], v[16:19]
	v_mfma_f32_16x16x32_bf16 v[60:63], v[160:163], v[176:179], v[60:63]
	v_mfma_f32_16x16x32_bf16 v[56:59], v[168:171], v[176:179], v[56:59]
	v_mfma_f32_16x16x32_bf16 v[52:55], v[160:163], v[184:187], v[52:55]
	v_mfma_f32_16x16x32_bf16 v[48:51], v[168:171], v[184:187], v[48:51]
	v_mfma_f32_16x16x32_bf16 v[36:39], v[160:163], v[192:195], v[36:39]
	v_mfma_f32_16x16x32_bf16 v[32:35], v[168:171], v[192:195], v[32:35]
	v_mfma_f32_16x16x32_bf16 v[20:23], v[160:163], v[200:203], v[20:23]
	v_mfma_f32_16x16x32_bf16 v[16:19], v[168:171], v[200:203], v[16:19]
	s_barrier
	s_add_u32 s26, s26, 0x40080
	s_addc_u32 s27, s27, 0
	s_add_i32 s28, s28, s35
	s_mov_b32 m0, s28
	v_lshl_add_u64 v[156:157], s[26:27], 0, v[130:131]
	global_load_lds_dwordx4 v[156:157], off
	s_add_i32 m0, s28, 0x2000
	v_lshl_add_u64 v[156:157], s[26:27], 0, v[134:135]
	global_load_lds_dwordx4 v[156:157], off
	s_waitcnt vmcnt(6)
	s_barrier
	v_mfma_f32_16x16x32_bf16 v[44:47], v[204:207], v[172:175], v[44:47]
	v_mfma_f32_16x16x32_bf16 v[40:43], v[212:215], v[172:175], v[40:43]
	v_mfma_f32_16x16x32_bf16 v[28:31], v[204:207], v[180:183], v[28:31]
	v_mfma_f32_16x16x32_bf16 v[24:27], v[212:215], v[180:183], v[24:27]
	v_mfma_f32_16x16x32_bf16 v[12:15], v[204:207], v[188:191], v[12:15]
	v_mfma_f32_16x16x32_bf16 v[8:11], v[212:215], v[188:191], v[8:11]
	v_mfma_f32_16x16x32_bf16 v[4:7], v[204:207], v[196:199], v[4:7]
	v_mfma_f32_16x16x32_bf16 v[0:3], v[212:215], v[196:199], v[0:3]
	v_mfma_f32_16x16x32_bf16 v[44:47], v[208:211], v[176:179], v[44:47]
	v_mfma_f32_16x16x32_bf16 v[40:43], v[216:219], v[176:179], v[40:43]
	v_mfma_f32_16x16x32_bf16 v[28:31], v[208:211], v[184:187], v[28:31]
	v_mfma_f32_16x16x32_bf16 v[24:27], v[216:219], v[184:187], v[24:27]
	v_mfma_f32_16x16x32_bf16 v[12:15], v[208:211], v[192:195], v[12:15]
	v_mfma_f32_16x16x32_bf16 v[8:11], v[216:219], v[192:195], v[8:11]
	v_mfma_f32_16x16x32_bf16 v[4:7], v[208:211], v[200:203], v[4:7]
	v_mfma_f32_16x16x32_bf16 v[0:3], v[216:219], v[200:203], v[0:3]
	s_add_i32 s50, s50, 2
	s_add_u32 s0, s0, 0x100
	s_addc_u32 s1, s1, 0
	s_add_u32 s17, s17, 0x100
	s_addc_u32 s49, s49, 0
	s_cmp_gt_u32 s50, 13
	s_barrier

; DEVI size_t gemm_offB(const Gemm& g, const Unit& u) { return (g.split ? (size_t)(u.b >> 2) * g.sB + (size_t)(u.b & 3) * g.sB_lo : (size_t)u.b * g.sB) + (size_t)(u.pm >> g.pmsh) * g.sBpm; }
; #define PG8_STAGE(bufoff, gbase, voff) do { _Pragma("unroll") for (int _i = 0; _i < 2; ++_i) \
;         __builtin_amdgcn_global_load_lds((const unsigned*)((const char*)(gbase) + (voff)[_i]), (LAS unsigned*)(lds + (bufoff) + ldsw + _i * 8192), 16, 0, 0); } while (0)
; #define PG8_LDA(dst, b, h) do { _Pragma("unroll") for (int m = 0; m < 4; ++m) _Pragma("unroll") for (int k = 0; k < 2; ++k) dst[m][k] = *(const LAS bf16x8*)(lds + PG8_SA(b, h) + aoff + m * 2048 + k * 1024); } while (0)
; #define PG8_LDB(dst, b, h) do { _Pragma("unroll") for (int n = 0; n < 2; ++n) _Pragma("unroll") for (int k = 0; k < 2; ++k) dst[n][k] = *(const LAS bf16x8*)(lds + PG8_SB(b, h) + boff + n * 2048 + k * 1024); } while (0)
; #define PG8_WAIT_L(n) asm volatile("s_waitcnt lgkmcnt(" #n ")" ::: "memory")
; #define PG8_BAR __builtin_amdgcn_s_barrier()
; #define PG8_SCHED __builtin_amdgcn_sched_barrier(0)
; template <class Epi>
; DEVI void gemm_phase(LAS unsigned char* lds, const Gemm g, const Epi& E) {
;     ...
;         const bool has_next = unit_next(g, ui + 1, nxt);
;         const char* nA = has_next ? (const char*)g.A + gemm_offA(g, nxt) * 2 + (size_t)nxt.pm * tstepA : cA;
;         const char* nB = has_next ? (const char*)g.Bt + gemm_offB(g, nxt) * 2 + (size_t)nxt.pn * tstepB : cB;
;         for (int t = 0; t < nt; t += 2) {
;             const bool last = (t == nt - 2);
;             const char* a1 = cA + (size_t)(t + 1) * kstep;
;             const char* a2 = last ? nA : cA + (size_t)(t + 2) * kstep; const char* b2 = last ? nB : cB + (size_t)(t + 2) * kstep;
;             const char* a3 = a2 + kstep; const char* b3 = b2 + kstep;
;             PG8_LDB(B0, 0, 0); PG8_SCHED; PG8_LDA(At, 0, 0); PG8_STAGE(PG8_SA(1, 1), a1 + hstepA, voffA);
;             PG8_WAIT_L(8); PG8_BAR; PG8_WAIT_L(0); PG8_MMA(0, 0, At, B0); PG8_BAR; PG8_SCHED;
;             PG8_LDB(B1, 0, 1); PG8_STAGE(PG8_SB(0, 0), b2, voffB);
;             PG8_BAR; PG8_WAIT_L(0); PG8_MMA(0, 1, At, B1); PG8_BAR;
;     ...
;                 for (int i = 0; i < 8; ++i) q4[i] = *(const f32x4*)(E.ssq_in + (size_t)(row0 + (i >> 2) * HALF + (i & 3) * 16) * 4);
.LBB0_275:
	s_ashr_i32 s13, s12, 31
	v_mov_b64_e32 v[0:1], 0x680
	s_lshl_b64 s[0:1], s[12:13], 19
	v_cmp_lt_i64_e32 vcc, s[16:17], v[0:1]
	s_add_u32 s16, s24, s0
	s_addc_u32 s17, s25, s1
	s_and_b64 s[0:1], vcc, exec
	s_cselect_b32 s0, s17, s9
	s_cselect_b32 s1, s16, s8
	s_ashr_i32 s15, s14, 31
	s_lshl_b64 s[18:19], s[14:15], 19
	s_add_u32 s36, s40, s18
	s_addc_u32 s37, s41, s19
	s_and_b64 s[18:19], vcc, exec
	s_cselect_b32 s5, s37, s47
	s_cselect_b32 s7, s36, s46
	s_add_u32 s8, s8, 0x40080
	s_addc_u32 s9, s9, 0
	s_add_u32 s13, s46, 0x100
	s_addc_u32 s15, s47, 0
	s_mov_b32 s18, -2
	s_cmp_eq_u32 s4, 12
	s_cbranch_scc1 .Lip13l_a_in
	v_and_b32_e32 v248, 0xff, v154
	v_lshlrev_b32_e32 v248, 4, v248
	v_add_u32_e32 v249, 0x21000, v248
	v_lshl_add_u32 v248, s6, 12, v248
	global_load_dwordx4 v[244:247], v248, s[76:77]
	s_nop 0
	s_nop 0
	s_add_u32 s19, s8, 0xfffc0080
	s_addc_u32 s26, s9, -1
	s_add_i32 s27, 0, 0x10000
	v_add_u32_e32 v8, s27, v214
	ds_read_b128 v[130:133], v8
	ds_read_b128 v[134:137], v8 offset:1024
	ds_read_b128 v[138:141], v8 offset:2048
	ds_read_b128 v[142:145], v8 offset:3072
	s_cmp_eq_u32 s18, 12
	s_cselect_b32 s69, s0, s26
	s_cselect_b32 s68, s1, s19
	s_cselect_b32 s47, s5, s15
	s_cselect_b32 s46, s7, s13
	v_lshl_add_u64 v[208:209], s[8:9], 0, v[184:185]
	s_add_i32 m0, s81, 0xc000
	ds_read_b128 v[146:149], v216
	ds_read_b128 v[150:153], v216 offset:1024
	ds_read_b128 v[188:191], v216 offset:2048
	ds_read_b128 v[192:195], v216 offset:3072
	ds_read_b128 v[196:199], v216 offset:4096
	ds_read_b128 v[200:203], v216 offset:5120
	ds_read_b128 v[204:207], v216 offset:6144
	ds_read_b128 v[218:221], v216 offset:7168
	global_load_lds_dwordx4 v[208:209], off
	s_add_i32 m0, s81, 0xe000
	v_lshl_add_u64 v[208:209], s[8:9], 0, v[186:187]
	global_load_lds_dwordx4 v[208:209], off
	s_waitcnt lgkmcnt(8)
	s_barrier
	s_waitcnt lgkmcnt(0)
	v_mfma_f32_16x16x32_bf16 v[126:129], v[130:133], v[146:149], 0
	v_mfma_f32_16x16x32_bf16 v[122:125], v[138:141], v[146:149], 0
	v_mfma_f32_16x16x32_bf16 v[114:117], v[130:133], v[188:191], 0
	v_mfma_f32_16x16x32_bf16 v[106:109], v[138:141], v[188:191], 0
	v_mfma_f32_16x16x32_bf16 v[94:97], v[130:133], v[196:199], 0
	v_mfma_f32_16x16x32_bf16 v[90:93], v[138:141], v[196:199], 0
	v_mfma_f32_16x16x32_bf16 v[82:85], v[130:133], v[204:207], 0
	v_mfma_f32_16x16x32_bf16 v[74:77], v[138:141], v[204:207], 0
	v_mfma_f32_16x16x32_bf16 v[126:129], v[134:137], v[150:153], v[126:129]
	v_mfma_f32_16x16x32_bf16 v[122:125], v[142:145], v[150:153], v[122:125]
	v_mfma_f32_16x16x32_bf16 v[114:117], v[134:137], v[192:195], v[114:117]
	v_mfma_f32_16x16x32_bf16 v[106:109], v[142:145], v[192:195], v[106:109]
	v_mfma_f32_16x16x32_bf16 v[94:97], v[134:137], v[200:203], v[94:97]
	v_mfma_f32_16x16x32_bf16 v[90:93], v[142:145], v[200:203], v[90:93]
	v_mfma_f32_16x16x32_bf16 v[82:85], v[134:137], v[218:221], v[82:85]
	v_mfma_f32_16x16x32_bf16 v[74:77], v[142:145], v[218:221], v[74:77]
	s_barrier
	s_add_i32 s19, 0, 0x14000
	s_add_i32 s26, s27, s80
	v_add_u32_e32 v8, s19, v214
	v_lshl_add_u64 v[208:209], s[46:47], 0, v[178:179]
	s_mov_b32 m0, s26
	ds_read_b128 v[222:225], v8
	ds_read_b128 v[226:229], v8 offset:1024
	ds_read_b128 v[230:233], v8 offset:2048
	ds_read_b128 v[234:237], v8 offset:3072
	global_load_lds_dwordx4 v[208:209], off
	s_add_i32 m0, s26, 0x2000
	v_lshl_add_u64 v[238:239], s[46:47], 0, v[182:183]
	global_load_lds_dwordx4 v[238:239], off
	s_barrier
	s_waitcnt lgkmcnt(0)
	v_mfma_f32_16x16x32_bf16 v[118:121], v[222:225], v[146:149], 0
	v_mfma_f32_16x16x32_bf16 v[110:113], v[230:233], v[146:149], 0
	v_mfma_f32_16x16x32_bf16 v[102:105], v[222:225], v[188:191], 0
	v_mfma_f32_16x16x32_bf16 v[98:101], v[230:233], v[188:191], 0
	v_mfma_f32_16x16x32_bf16 v[86:89], v[222:225], v[196:199], 0
	v_mfma_f32_16x16x32_bf16 v[78:81], v[230:233], v[196:199], 0
	v_mfma_f32_16x16x32_bf16 v[62:65], v[222:225], v[204:207], 0
	v_mfma_f32_16x16x32_bf16 v[58:61], v[230:233], v[204:207], 0
	v_mfma_f32_16x16x32_bf16 v[118:121], v[226:229], v[150:153], v[118:121]
	v_mfma_f32_16x16x32_bf16 v[110:113], v[234:237], v[150:153], v[110:113]
	v_mfma_f32_16x16x32_bf16 v[102:105], v[226:229], v[192:195], v[102:105]
	v_mfma_f32_16x16x32_bf16 v[98:101], v[234:237], v[192:195], v[98:101]
	v_mfma_f32_16x16x32_bf16 v[86:89], v[226:229], v[200:203], v[86:89]
	v_mfma_f32_16x16x32_bf16 v[78:81], v[234:237], v[200:203], v[78:81]
	v_mfma_f32_16x16x32_bf16 v[62:65], v[226:229], v[218:221], v[62:65]
	v_mfma_f32_16x16x32_bf16 v[58:61], v[234:237], v[218:221], v[58:61]
	s_mov_b32 m0, s81
	v_lshl_add_u64 v[240:241], s[68:69], 0, v[176:177]
	s_barrier
	ds_read_b128 v[146:149], v216 offset:16384
	ds_read_b128 v[150:153], v216 offset:17408
	ds_read_b128 v[188:191], v216 offset:18432
	ds_read_b128 v[192:195], v216 offset:19456
	ds_read_b128 v[196:199], v216 offset:20480
	ds_read_b128 v[200:203], v216 offset:21504
	ds_read_b128 v[204:207], v216 offset:22528
	ds_read_b128 v[218:221], v216 offset:23552
	global_load_lds_dwordx4 v[240:241], off
	s_mov_b32 m0, s82
	v_lshl_add_u64 v[242:243], s[68:69], 0, v[180:181]
	global_load_lds_dwordx4 v[242:243], off
	s_barrier
; #define PG8_STAGE(bufoff, gbase, voff) do { _Pragma("unroll") for (int _i = 0; _i < 2; ++_i) \
;         __builtin_amdgcn_global_load_lds((const unsigned*)((const char*)(gbase) + (voff)[_i]), (LAS unsigned*)(lds + (bufoff) + ldsw + _i * 8192), 16, 0, 0); } while (0)
; #define PG8_LDA(dst, b, h) do { _Pragma("unroll") for (int m = 0; m < 4; ++m) _Pragma("unroll") for (int k = 0; k < 2; ++k) dst[m][k] = *(const LAS bf16x8*)(lds + PG8_SA(b, h) + aoff + m * 2048 + k * 1024); } while (0)
; #define PG8_LDB(dst, b, h) do { _Pragma("unroll") for (int n = 0; n < 2; ++n) _Pragma("unroll") for (int k = 0; k < 2; ++k) dst[n][k] = *(const LAS bf16x8*)(lds + PG8_SB(b, h) + boff + n * 2048 + k * 1024); } while (0)
; #define PG8_MMA(ai, bj, At, Bt) do { __builtin_amdgcn_s_setprio(1); _Pragma("unroll") for (int m = 0; m < 4; ++m) _Pragma("unroll") for (int n = 0; n < 2; ++n) _Pragma("unroll") for (int k = 0; k < 2; ++k) \
;         acc[ai][bj][m][n] = __builtin_amdgcn_mfma_f32_16x16x32_bf16(Bt[n][k], At[m][k], acc[ai][bj][m][n], 0, 0, 0); __builtin_amdgcn_s_setprio(0); } while (0)
; #define PG8_WAIT_V(n) asm volatile("s_waitcnt vmcnt(" #n ")" ::: "memory")
; #define PG8_WAIT_L(n) asm volatile("s_waitcnt lgkmcnt(" #n ")" ::: "memory")
; #define PG8_BAR __builtin_amdgcn_s_barrier()
; #define PG8_SCHED __builtin_amdgcn_sched_barrier(0)
; template <class Epi>
; DEVI void gemm_phase(LAS unsigned char* lds, const Gemm g, const Epi& E) {
;     ...
;             PG8_LDA(At, 0, 1); PG8_STAGE(PG8_SA(0, 0), a2, voffA);
;             PG8_BAR; PG8_WAIT_L(0); PG8_MMA(1, 0, At, B0); PG8_BAR; PG8_SCHED;
;             PG8_STAGE(PG8_SB(0, 1), b2 + hstepB, voffB);
;             PG8_WAIT_V(6); PG8_BAR; PG8_MMA(1, 1, At, B1); PG8_BAR;
;             PG8_LDB(B0, 1, 0); PG8_SCHED; PG8_LDA(At, 1, 0); PG8_STAGE(PG8_SA(0, 1), a2 + hstepA, voffA);
;             PG8_WAIT_L(8); PG8_BAR; PG8_WAIT_L(0); PG8_MMA(0, 0, At, B0); PG8_BAR; PG8_SCHED;
;     ...
;                 for (int i = 0; i < 8; ++i) q4[i] = *(const f32x4*)(E.ssq_in + (size_t)(row0 + (i >> 2) * HALF + (i & 3) * 16) * 4);
	s_waitcnt lgkmcnt(0)
	v_mfma_f32_16x16x32_bf16 v[70:73], v[130:133], v[146:149], 0
	v_mfma_f32_16x16x32_bf16 v[66:69], v[138:141], v[146:149], 0
	v_mfma_f32_16x16x32_bf16 v[46:49], v[130:133], v[188:191], 0
	v_mfma_f32_16x16x32_bf16 v[42:45], v[138:141], v[188:191], 0
	v_mfma_f32_16x16x32_bf16 v[30:33], v[130:133], v[196:199], 0
	v_mfma_f32_16x16x32_bf16 v[26:29], v[138:141], v[196:199], 0
	v_mfma_f32_16x16x32_bf16 v[14:17], v[130:133], v[204:207], 0
	v_mfma_f32_16x16x32_bf16 v[10:13], v[138:141], v[204:207], 0
	v_mfma_f32_16x16x32_bf16 v[70:73], v[134:137], v[150:153], v[70:73]
	v_mfma_f32_16x16x32_bf16 v[66:69], v[142:145], v[150:153], v[66:69]
	v_mfma_f32_16x16x32_bf16 v[46:49], v[134:137], v[192:195], v[46:49]
	v_mfma_f32_16x16x32_bf16 v[42:45], v[142:145], v[192:195], v[42:45]
	v_mfma_f32_16x16x32_bf16 v[30:33], v[134:137], v[200:203], v[30:33]
	v_mfma_f32_16x16x32_bf16 v[26:29], v[142:145], v[200:203], v[26:29]
	v_mfma_f32_16x16x32_bf16 v[14:17], v[134:137], v[218:221], v[14:17]
	v_mfma_f32_16x16x32_bf16 v[10:13], v[142:145], v[218:221], v[10:13]
	s_barrier
	s_add_u32 s26, s46, 0x40000
	s_addc_u32 s27, s47, 0
	s_add_i32 s19, s19, s80
	s_mov_b32 m0, s19
	v_lshl_add_u64 v[130:131], s[26:27], 0, v[178:179]
	global_load_lds_dwordx4 v[130:131], off
	s_add_i32 m0, s19, 0x2000
	v_lshl_add_u64 v[130:131], s[26:27], 0, v[182:183]
	global_load_lds_dwordx4 v[130:131], off
	s_waitcnt vmcnt(6)
	ds_write_b128 v249, v[244:247]
	s_barrier
	v_mfma_f32_16x16x32_bf16 v[50:53], v[222:225], v[146:149], 0
	v_mfma_f32_16x16x32_bf16 v[54:57], v[230:233], v[146:149], 0
	v_mfma_f32_16x16x32_bf16 v[34:37], v[222:225], v[188:191], 0
	v_mfma_f32_16x16x32_bf16 v[38:41], v[230:233], v[188:191], 0
	v_mfma_f32_16x16x32_bf16 v[18:21], v[222:225], v[196:199], 0
	v_mfma_f32_16x16x32_bf16 v[22:25], v[230:233], v[196:199], 0
	v_mfma_f32_16x16x32_bf16 v[0:3], v[222:225], v[204:207], 0
	v_mfma_f32_16x16x32_bf16 v[4:7], v[230:233], v[204:207], 0
	v_mfma_f32_16x16x32_bf16 v[50:53], v[226:229], v[150:153], v[50:53]
	v_mfma_f32_16x16x32_bf16 v[54:57], v[234:237], v[150:153], v[54:57]
	v_mfma_f32_16x16x32_bf16 v[34:37], v[226:229], v[192:195], v[34:37]
	v_mfma_f32_16x16x32_bf16 v[38:41], v[234:237], v[192:195], v[38:41]
	v_mfma_f32_16x16x32_bf16 v[18:21], v[226:229], v[200:203], v[18:21]
	v_mfma_f32_16x16x32_bf16 v[22:25], v[234:237], v[200:203], v[22:25]
	v_mfma_f32_16x16x32_bf16 v[0:3], v[226:229], v[218:221], v[0:3]
	v_mfma_f32_16x16x32_bf16 v[4:7], v[234:237], v[218:221], v[4:7]
	s_add_i32 s19, 0, 0x18000
	v_add_u32_e32 v8, s19, v214
	s_barrier
	ds_read_b128 v[130:133], v8
	ds_read_b128 v[134:137], v8 offset:1024
	ds_read_b128 v[138:141], v8 offset:2048
	ds_read_b128 v[142:145], v8 offset:3072
	s_add_u32 s26, s68, 0x40000
	s_addc_u32 s27, s69, 0
	s_mov_b32 m0, s83
	v_lshl_add_u64 v[222:223], s[26:27], 0, v[176:177]
	ds_read_b128 v[146:149], v216 offset:32768
	ds_read_b128 v[150:153], v216 offset:33792
	ds_read_b128 v[188:191], v216 offset:34816
	ds_read_b128 v[192:195], v216 offset:35840
	ds_read_b128 v[196:199], v216 offset:36864
	ds_read_b128 v[200:203], v216 offset:37888
	ds_read_b128 v[204:207], v216 offset:38912
	ds_read_b128 v[218:221], v216 offset:39936
	global_load_lds_dwordx4 v[222:223], off
	s_mov_b32 m0, s84
	v_lshl_add_u64 v[222:223], s[26:27], 0, v[180:181]
	global_load_lds_dwordx4 v[222:223], off
	s_waitcnt lgkmcnt(8)
	s_barrier
	s_waitcnt lgkmcnt(0)
	v_mfma_f32_16x16x32_bf16 v[126:129], v[130:133], v[146:149], v[126:129]
	v_mfma_f32_16x16x32_bf16 v[122:125], v[138:141], v[146:149], v[122:125]
	v_mfma_f32_16x16x32_bf16 v[114:117], v[130:133], v[188:191], v[114:117]
	v_mfma_f32_16x16x32_bf16 v[106:109], v[138:141], v[188:191], v[106:109]
	v_mfma_f32_16x16x32_bf16 v[94:97], v[130:133], v[196:199], v[94:97]
	v_mfma_f32_16x16x32_bf16 v[90:93], v[138:141], v[196:199], v[90:93]
	v_mfma_f32_16x16x32_bf16 v[82:85], v[130:133], v[204:207], v[82:85]
	v_mfma_f32_16x16x32_bf16 v[74:77], v[138:141], v[204:207], v[74:77]
	v_mfma_f32_16x16x32_bf16 v[126:129], v[134:137], v[150:153], v[126:129]
	v_mfma_f32_16x16x32_bf16 v[122:125], v[142:145], v[150:153], v[122:125]
	v_mfma_f32_16x16x32_bf16 v[114:117], v[134:137], v[192:195], v[114:117]
	v_mfma_f32_16x16x32_bf16 v[106:109], v[142:145], v[192:195], v[106:109]
	v_mfma_f32_16x16x32_bf16 v[94:97], v[134:137], v[200:203], v[94:97]
	v_mfma_f32_16x16x32_bf16 v[90:93], v[142:145], v[200:203], v[90:93]
	v_mfma_f32_16x16x32_bf16 v[82:85], v[134:137], v[218:221], v[82:85]
	v_mfma_f32_16x16x32_bf16 v[74:77], v[142:145], v[218:221], v[74:77]
	s_barrier
; #define PG8_STAGE(bufoff, gbase, voff) do { _Pragma("unroll") for (int _i = 0; _i < 2; ++_i) \
;         __builtin_amdgcn_global_load_lds((const unsigned*)((const char*)(gbase) + (voff)[_i]), (LAS unsigned*)(lds + (bufoff) + ldsw + _i * 8192), 16, 0, 0); } while (0)
; #define PG8_LDA(dst, b, h) do { _Pragma("unroll") for (int m = 0; m < 4; ++m) _Pragma("unroll") for (int k = 0; k < 2; ++k) dst[m][k] = *(const LAS bf16x8*)(lds + PG8_SA(b, h) + aoff + m * 2048 + k * 1024); } while (0)
; #define PG8_LDB(dst, b, h) do { _Pragma("unroll") for (int n = 0; n < 2; ++n) _Pragma("unroll") for (int k = 0; k < 2; ++k) dst[n][k] = *(const LAS bf16x8*)(lds + PG8_SB(b, h) + boff + n * 2048 + k * 1024); } while (0)
; #define PG8_MMA(ai, bj, At, Bt) do { __builtin_amdgcn_s_setprio(1); _Pragma("unroll") for (int m = 0; m < 4; ++m) _Pragma("unroll") for (int n = 0; n < 2; ++n) _Pragma("unroll") for (int k = 0; k < 2; ++k) \
;         acc[ai][bj][m][n] = __builtin_amdgcn_mfma_f32_16x16x32_bf16(Bt[n][k], At[m][k], acc[ai][bj][m][n], 0, 0, 0); __builtin_amdgcn_s_setprio(0); } while (0)
; #define PG8_WAIT_V(n) asm volatile("s_waitcnt vmcnt(" #n ")" ::: "memory")
; #define PG8_WAIT_L(n) asm volatile("s_waitcnt lgkmcnt(" #n ")" ::: "memory")
; #define PG8_BAR __builtin_amdgcn_s_barrier()
; #define PG8_SCHED __builtin_amdgcn_sched_barrier(0)
; template <class Epi>
; DEVI void gemm_phase(LAS unsigned char* lds, const Gemm g, const Epi& E) {
;     ...
;             PG8_LDB(B1, 1, 1); PG8_STAGE(PG8_SB(1, 0), b3, voffB);
;             PG8_BAR; PG8_WAIT_L(0); PG8_MMA(0, 1, At, B1); PG8_BAR;
;             PG8_LDA(At, 1, 1); PG8_STAGE(PG8_SA(1, 0), a3, voffA);
;             PG8_BAR; PG8_WAIT_L(0); PG8_MMA(1, 0, At, B0); PG8_BAR; PG8_SCHED;
;             PG8_STAGE(PG8_SB(1, 1), b3 + hstepB, voffB);
;             PG8_WAIT_V(6); PG8_BAR; PG8_MMA(1, 1, At, B1); PG8_BAR;
;         }
	s_add_i32 s38, 0, 0x1c000
	s_add_i32 s19, s19, s80
	v_add_u32_e32 v8, s38, v214
	v_lshl_add_u64 v[208:209], v[208:209], 0, s[70:71]
	s_mov_b32 m0, s19
	ds_read_b128 v[222:225], v8
	ds_read_b128 v[226:229], v8 offset:1024
	ds_read_b128 v[230:233], v8 offset:2048
	ds_read_b128 v[234:237], v8 offset:3072
	global_load_lds_dwordx4 v[208:209], off
	s_add_i32 m0, s19, 0x2000
	v_lshl_add_u64 v[208:209], v[238:239], 0, s[70:71]
	global_load_lds_dwordx4 v[208:209], off
	s_barrier
	s_waitcnt lgkmcnt(0)
	v_mfma_f32_16x16x32_bf16 v[118:121], v[222:225], v[146:149], v[118:121]
	v_mfma_f32_16x16x32_bf16 v[110:113], v[230:233], v[146:149], v[110:113]
	v_mfma_f32_16x16x32_bf16 v[102:105], v[222:225], v[188:191], v[102:105]
	v_mfma_f32_16x16x32_bf16 v[98:101], v[230:233], v[188:191], v[98:101]
	v_mfma_f32_16x16x32_bf16 v[86:89], v[222:225], v[196:199], v[86:89]
	v_mfma_f32_16x16x32_bf16 v[78:81], v[230:233], v[196:199], v[78:81]
	v_mfma_f32_16x16x32_bf16 v[62:65], v[222:225], v[204:207], v[62:65]
	v_mfma_f32_16x16x32_bf16 v[58:61], v[230:233], v[204:207], v[58:61]
	v_mfma_f32_16x16x32_bf16 v[118:121], v[226:229], v[150:153], v[118:121]
	v_mfma_f32_16x16x32_bf16 v[110:113], v[234:237], v[150:153], v[110:113]
	v_mfma_f32_16x16x32_bf16 v[102:105], v[226:229], v[192:195], v[102:105]
	v_mfma_f32_16x16x32_bf16 v[98:101], v[234:237], v[192:195], v[98:101]
	v_mfma_f32_16x16x32_bf16 v[86:89], v[226:229], v[200:203], v[86:89]
	v_mfma_f32_16x16x32_bf16 v[78:81], v[234:237], v[200:203], v[78:81]
	v_mfma_f32_16x16x32_bf16 v[62:65], v[226:229], v[218:221], v[62:65]
	v_mfma_f32_16x16x32_bf16 v[58:61], v[234:237], v[218:221], v[58:61]
	s_mov_b32 m0, s85
	v_lshl_add_u64 v[208:209], v[240:241], 0, s[70:71]
	s_barrier
	ds_read_b128 v[146:149], v216 offset:49152
	ds_read_b128 v[150:153], v216 offset:50176
	ds_read_b128 v[188:191], v216 offset:51200
	ds_read_b128 v[192:195], v216 offset:52224
	ds_read_b128 v[196:199], v216 offset:53248
	ds_read_b128 v[200:203], v216 offset:54272
	ds_read_b128 v[204:207], v216 offset:55296
	ds_read_b128 v[218:221], v216 offset:56320
	global_load_lds_dwordx4 v[208:209], off
	s_mov_b32 m0, s86
	v_lshl_add_u64 v[208:209], v[242:243], 0, s[70:71]
	global_load_lds_dwordx4 v[208:209], off
	s_barrier
	s_waitcnt lgkmcnt(0)
	v_mfma_f32_16x16x32_bf16 v[70:73], v[130:133], v[146:149], v[70:73]
	v_mfma_f32_16x16x32_bf16 v[66:69], v[138:141], v[146:149], v[66:69]
	v_mfma_f32_16x16x32_bf16 v[46:49], v[130:133], v[188:191], v[46:49]
	v_mfma_f32_16x16x32_bf16 v[42:45], v[138:141], v[188:191], v[42:45]
	v_mfma_f32_16x16x32_bf16 v[30:33], v[130:133], v[196:199], v[30:33]
	v_mfma_f32_16x16x32_bf16 v[26:29], v[138:141], v[196:199], v[26:29]
	v_mfma_f32_16x16x32_bf16 v[14:17], v[130:133], v[204:207], v[14:17]
	v_mfma_f32_16x16x32_bf16 v[10:13], v[138:141], v[204:207], v[10:13]
	v_mfma_f32_16x16x32_bf16 v[70:73], v[134:137], v[150:153], v[70:73]
	v_mfma_f32_16x16x32_bf16 v[66:69], v[142:145], v[150:153], v[66:69]
	v_mfma_f32_16x16x32_bf16 v[46:49], v[134:137], v[192:195], v[46:49]
	v_mfma_f32_16x16x32_bf16 v[42:45], v[142:145], v[192:195], v[42:45]
	v_mfma_f32_16x16x32_bf16 v[30:33], v[134:137], v[200:203], v[30:33]
	v_mfma_f32_16x16x32_bf16 v[26:29], v[142:145], v[200:203], v[26:29]
	v_mfma_f32_16x16x32_bf16 v[14:17], v[134:137], v[218:221], v[14:17]
	v_mfma_f32_16x16x32_bf16 v[10:13], v[142:145], v[218:221], v[10:13]
	s_barrier
	s_add_u32 s26, s46, 0x40080
	s_addc_u32 s27, s47, 0
	s_add_i32 s19, s38, s80
	s_mov_b32 m0, s19
	v_lshl_add_u64 v[130:131], s[26:27], 0, v[178:179]
	global_load_lds_dwordx4 v[130:131], off
	s_add_i32 m0, s19, 0x2000
	v_lshl_add_u64 v[130:131], s[26:27], 0, v[182:183]
	global_load_lds_dwordx4 v[130:131], off
	s_waitcnt vmcnt(6)
	s_barrier
	v_mfma_f32_16x16x32_bf16 v[50:53], v[222:225], v[146:149], v[50:53]
	v_mfma_f32_16x16x32_bf16 v[54:57], v[230:233], v[146:149], v[54:57]
	v_mfma_f32_16x16x32_bf16 v[34:37], v[222:225], v[188:191], v[34:37]
	v_mfma_f32_16x16x32_bf16 v[38:41], v[230:233], v[188:191], v[38:41]
	v_mfma_f32_16x16x32_bf16 v[18:21], v[222:225], v[196:199], v[18:21]
	v_mfma_f32_16x16x32_bf16 v[22:25], v[230:233], v[196:199], v[22:25]
	v_mfma_f32_16x16x32_bf16 v[0:3], v[222:225], v[204:207], v[0:3]
	v_mfma_f32_16x16x32_bf16 v[4:7], v[230:233], v[204:207], v[4:7]
	v_mfma_f32_16x16x32_bf16 v[50:53], v[226:229], v[150:153], v[50:53]
	v_mfma_f32_16x16x32_bf16 v[54:57], v[234:237], v[150:153], v[54:57]
	v_mfma_f32_16x16x32_bf16 v[34:37], v[226:229], v[192:195], v[34:37]
	v_mfma_f32_16x16x32_bf16 v[38:41], v[234:237], v[192:195], v[38:41]
	v_mfma_f32_16x16x32_bf16 v[18:21], v[226:229], v[200:203], v[18:21]
	v_mfma_f32_16x16x32_bf16 v[22:25], v[234:237], v[200:203], v[22:25]
	v_mfma_f32_16x16x32_bf16 v[0:3], v[226:229], v[218:221], v[0:3]
	v_mfma_f32_16x16x32_bf16 v[4:7], v[234:237], v[218:221], v[4:7]
	s_add_i32 s18, s18, 2
	s_add_u32 s8, s8, 0x100
	s_addc_u32 s9, s9, 0
	s_add_u32 s13, s13, 0x100
	s_addc_u32 s15, s15, 0
	s_cmp_gt_u32 s18, 13
	s_barrier

; #define PG8_STAGE(bufoff, gbase, voff) do { _Pragma("unroll") for (int _i = 0; _i < 2; ++_i) \
;         __builtin_amdgcn_global_load_lds((const unsigned*)((const char*)(gbase) + (voff)[_i]), (LAS unsigned*)(lds + (bufoff) + ldsw + _i * 8192), 16, 0, 0); } while (0)
; #define PG8_LDA(dst, b, h) do { _Pragma("unroll") for (int m = 0; m < 4; ++m) _Pragma("unroll") for (int k = 0; k < 2; ++k) dst[m][k] = *(const LAS bf16x8*)(lds + PG8_SA(b, h) + aoff + m * 2048 + k * 1024); } while (0)
; #define PG8_LDB(dst, b, h) do { _Pragma("unroll") for (int n = 0; n < 2; ++n) _Pragma("unroll") for (int k = 0; k < 2; ++k) dst[n][k] = *(const LAS bf16x8*)(lds + PG8_SB(b, h) + boff + n * 2048 + k * 1024); } while (0)
; #define PG8_MMA(ai, bj, At, Bt) do { __builtin_amdgcn_s_setprio(1); _Pragma("unroll") for (int m = 0; m < 4; ++m) _Pragma("unroll") for (int n = 0; n < 2; ++n) _Pragma("unroll") for (int k = 0; k < 2; ++k) \
;         acc[ai][bj][m][n] = __builtin_amdgcn_mfma_f32_16x16x32_bf16(Bt[n][k], At[m][k], acc[ai][bj][m][n], 0, 0, 0); __builtin_amdgcn_s_setprio(0); } while (0)
; #define PG8_WAIT_L(n) asm volatile("s_waitcnt lgkmcnt(" #n ")" ::: "memory")
; #define PG8_BAR __builtin_amdgcn_s_barrier()
; #define PG8_SCHED __builtin_amdgcn_sched_barrier(0)
; template <class Epi>
; DEVI void gemm_phase(LAS unsigned char* lds, const Gemm g, const Epi& E) {
;     ...
;             PG8_LDB(B0, 0, 0); PG8_SCHED; PG8_LDA(At, 0, 0); PG8_STAGE(PG8_SA(1, 1), a1 + hstepA, voffA);
;             PG8_WAIT_L(8); PG8_BAR; PG8_WAIT_L(0); PG8_MMA(0, 0, At, B0); PG8_BAR; PG8_SCHED;
;     ...
;                 for (int i = 0; i < 8; ++i) q4[i] = *(const f32x4*)(E.ssq_in + (size_t)(row0 + (i >> 2) * HALF + (i & 3) * 16) * 4);
.Lip13l_a_in:
	s_and_b32 s101, s66, 0xc0
	s_mov_b32 s100, 1
	s_cmp_lg_u32 s101, 0
	s_cselect_b32 s101, 1, 0
	v_and_b32_e32 v248, 0xff, v154
	v_lshlrev_b32_e32 v248, 4, v248
	v_add_u32_e32 v249, 0x21000, v248
	v_lshl_add_u32 v248, s6, 12, v248
	global_load_dwordx4 v[244:247], v248, s[76:77]
	s_nop 0
	s_nop 0
	s_nop 0
	s_nop 0
	s_nop 0
	s_nop 0
	s_nop 0
	s_nop 0
	s_nop 0
	s_nop 0
	s_nop 0
	s_nop 0
	s_add_u32 s19, s8, 0xfffc0080
	s_addc_u32 s26, s9, -1
	s_add_i32 s27, 0, 0x10000
	v_add_u32_e32 v8, s27, v214
	ds_read_b128 v[130:133], v8
	ds_read_b128 v[134:137], v8 offset:1024
	ds_read_b128 v[138:141], v8 offset:2048
	ds_read_b128 v[142:145], v8 offset:3072
	s_cmp_eq_u32 s18, 12
	s_cselect_b32 s69, s0, s26
	s_cselect_b32 s68, s1, s19
	s_cselect_b32 s47, s5, s15
	s_cselect_b32 s46, s7, s13
	v_lshl_add_u64 v[208:209], s[8:9], 0, v[184:185]
	s_add_i32 m0, s81, 0xc000
	ds_read_b128 v[146:149], v216
	ds_read_b128 v[150:153], v216 offset:1024
	ds_read_b128 v[188:191], v216 offset:2048
	ds_read_b128 v[192:195], v216 offset:3072
	ds_read_b128 v[196:199], v216 offset:4096
	ds_read_b128 v[200:203], v216 offset:5120
	ds_read_b128 v[204:207], v216 offset:6144
	ds_read_b128 v[218:221], v216 offset:7168
	global_load_lds_dwordx4 v[208:209], off
	s_add_i32 m0, s81, 0xe000
	v_lshl_add_u64 v[208:209], s[8:9], 0, v[186:187]
	global_load_lds_dwordx4 v[208:209], off
	s_waitcnt lgkmcnt(8)
	s_barrier
	s_waitcnt lgkmcnt(0)
	s_cmp_lg_u32 s101, 0
	s_cbranch_scc1 .Lip13l_a_0
	v_mfma_f32_16x16x32_bf16 v[126:129], v[130:133], v[146:149], 0
	v_mfma_f32_16x16x32_bf16 v[122:125], v[138:141], v[146:149], 0
	v_mfma_f32_16x16x32_bf16 v[114:117], v[130:133], v[188:191], 0
	v_mfma_f32_16x16x32_bf16 v[106:109], v[138:141], v[188:191], 0
	v_mfma_f32_16x16x32_bf16 v[94:97], v[130:133], v[196:199], 0
	v_mfma_f32_16x16x32_bf16 v[90:93], v[138:141], v[196:199], 0
	v_mfma_f32_16x16x32_bf16 v[82:85], v[130:133], v[204:207], 0
	v_mfma_f32_16x16x32_bf16 v[74:77], v[138:141], v[204:207], 0
	v_mfma_f32_16x16x32_bf16 v[126:129], v[134:137], v[150:153], v[126:129]
	v_mfma_f32_16x16x32_bf16 v[122:125], v[142:145], v[150:153], v[122:125]
	v_mfma_f32_16x16x32_bf16 v[114:117], v[134:137], v[192:195], v[114:117]
	v_mfma_f32_16x16x32_bf16 v[106:109], v[142:145], v[192:195], v[106:109]
	v_mfma_f32_16x16x32_bf16 v[94:97], v[134:137], v[200:203], v[94:97]
	v_mfma_f32_16x16x32_bf16 v[90:93], v[142:145], v[200:203], v[90:93]
	v_mfma_f32_16x16x32_bf16 v[82:85], v[134:137], v[218:221], v[82:85]
	v_mfma_f32_16x16x32_bf16 v[74:77], v[142:145], v[218:221], v[74:77]

; DEVI size_t gemm_offB(const Gemm& g, const Unit& u) { return (g.split ? (size_t)(u.b >> 2) * g.sB + (size_t)(u.b & 3) * g.sB_lo : (size_t)u.b * g.sB) + (size_t)(u.pm >> g.pmsh) * g.sBpm; }
; #define PG8_STAGE(bufoff, gbase, voff) do { _Pragma("unroll") for (int _i = 0; _i < 2; ++_i) \
;         __builtin_amdgcn_global_load_lds((const unsigned*)((const char*)(gbase) + (voff)[_i]), (LAS unsigned*)(lds + (bufoff) + ldsw + _i * 8192), 16, 0, 0); } while (0)
; #define PG8_LDA(dst, b, h) do { _Pragma("unroll") for (int m = 0; m < 4; ++m) _Pragma("unroll") for (int k = 0; k < 2; ++k) dst[m][k] = *(const LAS bf16x8*)(lds + PG8_SA(b, h) + aoff + m * 2048 + k * 1024); } while (0)
; #define PG8_LDB(dst, b, h) do { _Pragma("unroll") for (int n = 0; n < 2; ++n) _Pragma("unroll") for (int k = 0; k < 2; ++k) dst[n][k] = *(const LAS bf16x8*)(lds + PG8_SB(b, h) + boff + n * 2048 + k * 1024); } while (0)
; #define PG8_WAIT_L(n) asm volatile("s_waitcnt lgkmcnt(" #n ")" ::: "memory")
; #define PG8_BAR __builtin_amdgcn_s_barrier()
; #define PG8_SCHED __builtin_amdgcn_sched_barrier(0)
; template <class Epi>
; DEVI void gemm_phase(LAS unsigned char* lds, const Gemm g, const Epi& E) {
;     ...
;         const bool has_next = unit_next(g, ui + 1, nxt);
;         const char* nA = has_next ? (const char*)g.A + gemm_offA(g, nxt) * 2 + (size_t)nxt.pm * tstepA : cA;
;         const char* nB = has_next ? (const char*)g.Bt + gemm_offB(g, nxt) * 2 + (size_t)nxt.pn * tstepB : cB;
;         for (int t = 0; t < nt; t += 2) {
;             const bool last = (t == nt - 2);
;             const char* a1 = cA + (size_t)(t + 1) * kstep;
;             const char* a2 = last ? nA : cA + (size_t)(t + 2) * kstep; const char* b2 = last ? nB : cB + (size_t)(t + 2) * kstep;
;             const char* a3 = a2 + kstep; const char* b3 = b2 + kstep;
;             PG8_LDB(B0, 0, 0); PG8_SCHED; PG8_LDA(At, 0, 0); PG8_STAGE(PG8_SA(1, 1), a1 + hstepA, voffA);
;             PG8_WAIT_L(8); PG8_BAR; PG8_WAIT_L(0); PG8_MMA(0, 0, At, B0); PG8_BAR; PG8_SCHED;
;             PG8_LDB(B1, 0, 1); PG8_STAGE(PG8_SB(0, 0), b2, voffB);
;             PG8_BAR; PG8_WAIT_L(0); PG8_MMA(0, 1, At, B1); PG8_BAR;
;     ...
;                 for (int i = 0; i < 8; ++i) q4[i] = *(const f32x4*)(E.ssq_in + (size_t)(row0 + (i >> 2) * HALF + (i & 3) * 16) * 4);
.LBB0_355:
	s_ashr_i32 s11, s10, 31
	v_mov_b64_e32 v[0:1], 0x680
	s_lshl_b64 s[0:1], s[10:11], 19
	v_cmp_lt_i64_e32 vcc, s[14:15], v[0:1]
	s_add_u32 s14, s24, s0
	s_addc_u32 s15, s25, s1
	s_and_b64 s[0:1], vcc, exec
	s_cselect_b32 s0, s15, s9
	s_cselect_b32 s1, s14, s8
	s_ashr_i32 s13, s12, 31
	s_lshl_b64 s[16:17], s[12:13], 19
	s_add_u32 s16, s82, s16
	s_addc_u32 s17, s83, s17
	s_and_b64 s[18:19], vcc, exec
	s_cselect_b32 s5, s17, s47
	s_cselect_b32 s7, s16, s46
	s_add_u32 s8, s8, 0x40080
	s_addc_u32 s9, s9, 0
	s_add_u32 s11, s46, 0x100
	s_addc_u32 s13, s47, 0
	s_mov_b32 s18, -2
	s_cmp_eq_u32 s4, 12
	s_cbranch_scc1 .Lip13l_b_in
	v_and_b32_e32 v248, 0xff, v154
	v_lshlrev_b32_e32 v248, 4, v248
	v_add_u32_e32 v249, 0x21000, v248
	v_lshl_add_u32 v248, s6, 12, v248
	global_load_dwordx4 v[244:247], v248, s[76:77]
	s_nop 0
	s_nop 0
	s_nop 0
	s_nop 0
	s_nop 0
	s_nop 0
	s_nop 0
	s_add_u32 s19, s8, 0xfffc0080
	s_addc_u32 s26, s9, -1
	s_add_i32 s27, 0, 0x10000
	v_add_u32_e32 v142, s27, v209
	ds_read_b128 v[130:133], v142
	ds_read_b128 v[134:137], v142 offset:1024
	ds_read_b128 v[138:141], v142 offset:2048
	ds_read_b128 v[142:145], v142 offset:3072
	s_cmp_eq_u32 s18, 12
	s_cselect_b32 s69, s0, s26
	s_cselect_b32 s68, s1, s19
	s_cselect_b32 s47, s5, s13
	s_cselect_b32 s46, s7, s11
	v_lshl_add_u64 v[206:207], s[8:9], 0, v[182:183]
	s_add_i32 m0, s85, 0xc000
	ds_read_b128 v[146:149], v214
	ds_read_b128 v[150:153], v214 offset:1024
	ds_read_b128 v[186:189], v214 offset:2048
	ds_read_b128 v[190:193], v214 offset:3072
	ds_read_b128 v[194:197], v214 offset:4096
	ds_read_b128 v[198:201], v214 offset:5120
	ds_read_b128 v[202:205], v214 offset:6144
	ds_read_b128 v[216:219], v214 offset:7168
	global_load_lds_dwordx4 v[206:207], off
	s_add_i32 m0, s85, 0xe000
	v_lshl_add_u64 v[206:207], s[8:9], 0, v[184:185]
	global_load_lds_dwordx4 v[206:207], off
	s_waitcnt lgkmcnt(8)
	s_barrier
	s_waitcnt lgkmcnt(0)
	v_mfma_f32_16x16x32_bf16 v[126:129], v[130:133], v[146:149], 0
	v_mfma_f32_16x16x32_bf16 v[122:125], v[138:141], v[146:149], 0
	v_mfma_f32_16x16x32_bf16 v[114:117], v[130:133], v[186:189], 0
	v_mfma_f32_16x16x32_bf16 v[106:109], v[138:141], v[186:189], 0
	v_mfma_f32_16x16x32_bf16 v[94:97], v[130:133], v[194:197], 0
	v_mfma_f32_16x16x32_bf16 v[90:93], v[138:141], v[194:197], 0
	v_mfma_f32_16x16x32_bf16 v[82:85], v[130:133], v[202:205], 0
	v_mfma_f32_16x16x32_bf16 v[74:77], v[138:141], v[202:205], 0
	v_mfma_f32_16x16x32_bf16 v[126:129], v[134:137], v[150:153], v[126:129]
	v_mfma_f32_16x16x32_bf16 v[122:125], v[142:145], v[150:153], v[122:125]
	v_mfma_f32_16x16x32_bf16 v[114:117], v[134:137], v[190:193], v[114:117]
	v_mfma_f32_16x16x32_bf16 v[106:109], v[142:145], v[190:193], v[106:109]
	v_mfma_f32_16x16x32_bf16 v[94:97], v[134:137], v[198:201], v[94:97]
	v_mfma_f32_16x16x32_bf16 v[90:93], v[142:145], v[198:201], v[90:93]
	v_mfma_f32_16x16x32_bf16 v[82:85], v[134:137], v[216:219], v[82:85]
	v_mfma_f32_16x16x32_bf16 v[74:77], v[142:145], v[216:219], v[74:77]
	s_barrier
	s_add_i32 s19, 0, 0x14000
	s_add_i32 s26, s27, s84
	v_add_u32_e32 v162, s19, v209
	v_lshl_add_u64 v[206:207], s[46:47], 0, v[8:9]
	s_mov_b32 m0, s26
	ds_read_b128 v[220:223], v162
	ds_read_b128 v[224:227], v162 offset:1024
	ds_read_b128 v[228:231], v162 offset:2048
	ds_read_b128 v[232:235], v162 offset:3072
	global_load_lds_dwordx4 v[206:207], off
	s_add_i32 m0, s26, 0x2000
	v_lshl_add_u64 v[236:237], s[46:47], 0, v[180:181]
	global_load_lds_dwordx4 v[236:237], off
	s_barrier
	s_waitcnt lgkmcnt(0)
	v_mfma_f32_16x16x32_bf16 v[118:121], v[220:223], v[146:149], 0
	v_mfma_f32_16x16x32_bf16 v[110:113], v[228:231], v[146:149], 0
	v_mfma_f32_16x16x32_bf16 v[102:105], v[220:223], v[186:189], 0
	v_mfma_f32_16x16x32_bf16 v[98:101], v[228:231], v[186:189], 0
	v_mfma_f32_16x16x32_bf16 v[86:89], v[220:223], v[194:197], 0
	v_mfma_f32_16x16x32_bf16 v[78:81], v[228:231], v[194:197], 0
	v_mfma_f32_16x16x32_bf16 v[62:65], v[220:223], v[202:205], 0
	v_mfma_f32_16x16x32_bf16 v[58:61], v[228:231], v[202:205], 0
	v_mfma_f32_16x16x32_bf16 v[118:121], v[224:227], v[150:153], v[118:121]
	v_mfma_f32_16x16x32_bf16 v[110:113], v[232:235], v[150:153], v[110:113]
	v_mfma_f32_16x16x32_bf16 v[102:105], v[224:227], v[190:193], v[102:105]
	v_mfma_f32_16x16x32_bf16 v[98:101], v[232:235], v[190:193], v[98:101]
	v_mfma_f32_16x16x32_bf16 v[86:89], v[224:227], v[198:201], v[86:89]
	v_mfma_f32_16x16x32_bf16 v[78:81], v[232:235], v[198:201], v[78:81]
	v_mfma_f32_16x16x32_bf16 v[62:65], v[224:227], v[216:219], v[62:65]
	v_mfma_f32_16x16x32_bf16 v[58:61], v[232:235], v[216:219], v[58:61]
	s_mov_b32 m0, s85
	v_lshl_add_u64 v[238:239], s[68:69], 0, v[176:177]
	s_barrier
	ds_read_b128 v[146:149], v214 offset:16384
	ds_read_b128 v[150:153], v214 offset:17408
	ds_read_b128 v[186:189], v214 offset:18432
	ds_read_b128 v[190:193], v214 offset:19456
	ds_read_b128 v[194:197], v214 offset:20480
	ds_read_b128 v[198:201], v214 offset:21504
	ds_read_b128 v[202:205], v214 offset:22528
	ds_read_b128 v[216:219], v214 offset:23552
	global_load_lds_dwordx4 v[238:239], off
	s_mov_b32 m0, s86
	v_lshl_add_u64 v[240:241], s[68:69], 0, v[178:179]
	global_load_lds_dwordx4 v[240:241], off
	s_barrier
; #define PG8_STAGE(bufoff, gbase, voff) do { _Pragma("unroll") for (int _i = 0; _i < 2; ++_i) \
;         __builtin_amdgcn_global_load_lds((const unsigned*)((const char*)(gbase) + (voff)[_i]), (LAS unsigned*)(lds + (bufoff) + ldsw + _i * 8192), 16, 0, 0); } while (0)
; #define PG8_LDA(dst, b, h) do { _Pragma("unroll") for (int m = 0; m < 4; ++m) _Pragma("unroll") for (int k = 0; k < 2; ++k) dst[m][k] = *(const LAS bf16x8*)(lds + PG8_SA(b, h) + aoff + m * 2048 + k * 1024); } while (0)
; #define PG8_LDB(dst, b, h) do { _Pragma("unroll") for (int n = 0; n < 2; ++n) _Pragma("unroll") for (int k = 0; k < 2; ++k) dst[n][k] = *(const LAS bf16x8*)(lds + PG8_SB(b, h) + boff + n * 2048 + k * 1024); } while (0)
; #define PG8_MMA(ai, bj, At, Bt) do { __builtin_amdgcn_s_setprio(1); _Pragma("unroll") for (int m = 0; m < 4; ++m) _Pragma("unroll") for (int n = 0; n < 2; ++n) _Pragma("unroll") for (int k = 0; k < 2; ++k) \
;         acc[ai][bj][m][n] = __builtin_amdgcn_mfma_f32_16x16x32_bf16(Bt[n][k], At[m][k], acc[ai][bj][m][n], 0, 0, 0); __builtin_amdgcn_s_setprio(0); } while (0)
; #define PG8_WAIT_V(n) asm volatile("s_waitcnt vmcnt(" #n ")" ::: "memory")
; #define PG8_WAIT_L(n) asm volatile("s_waitcnt lgkmcnt(" #n ")" ::: "memory")
; #define PG8_BAR __builtin_amdgcn_s_barrier()
; #define PG8_SCHED __builtin_amdgcn_sched_barrier(0)
; template <class Epi>
; DEVI void gemm_phase(LAS unsigned char* lds, const Gemm g, const Epi& E) {
;     ...
;             PG8_LDA(At, 0, 1); PG8_STAGE(PG8_SA(0, 0), a2, voffA);
;             PG8_BAR; PG8_WAIT_L(0); PG8_MMA(1, 0, At, B0); PG8_BAR; PG8_SCHED;
;             PG8_STAGE(PG8_SB(0, 1), b2 + hstepB, voffB);
;             PG8_WAIT_V(6); PG8_BAR; PG8_MMA(1, 1, At, B1); PG8_BAR;
;             PG8_LDB(B0, 1, 0); PG8_SCHED; PG8_LDA(At, 1, 0); PG8_STAGE(PG8_SA(0, 1), a2 + hstepA, voffA);
;             PG8_WAIT_L(8); PG8_BAR; PG8_WAIT_L(0); PG8_MMA(0, 0, At, B0); PG8_BAR; PG8_SCHED;
;     ...
;                 for (int i = 0; i < 8; ++i) q4[i] = *(const f32x4*)(E.ssq_in + (size_t)(row0 + (i >> 2) * HALF + (i & 3) * 16) * 4);
	s_waitcnt lgkmcnt(0)
	v_mfma_f32_16x16x32_bf16 v[70:73], v[130:133], v[146:149], 0
	v_mfma_f32_16x16x32_bf16 v[66:69], v[138:141], v[146:149], 0
	v_mfma_f32_16x16x32_bf16 v[46:49], v[130:133], v[186:189], 0
	v_mfma_f32_16x16x32_bf16 v[42:45], v[138:141], v[186:189], 0
	v_mfma_f32_16x16x32_bf16 v[30:33], v[130:133], v[194:197], 0
	v_mfma_f32_16x16x32_bf16 v[26:29], v[138:141], v[194:197], 0
	v_mfma_f32_16x16x32_bf16 v[14:17], v[130:133], v[202:205], 0
	v_mfma_f32_16x16x32_bf16 v[10:13], v[138:141], v[202:205], 0
	v_mfma_f32_16x16x32_bf16 v[70:73], v[134:137], v[150:153], v[70:73]
	v_mfma_f32_16x16x32_bf16 v[66:69], v[142:145], v[150:153], v[66:69]
	v_mfma_f32_16x16x32_bf16 v[46:49], v[134:137], v[190:193], v[46:49]
	v_mfma_f32_16x16x32_bf16 v[42:45], v[142:145], v[190:193], v[42:45]
	v_mfma_f32_16x16x32_bf16 v[30:33], v[134:137], v[198:201], v[30:33]
	v_mfma_f32_16x16x32_bf16 v[26:29], v[142:145], v[198:201], v[26:29]
	v_mfma_f32_16x16x32_bf16 v[14:17], v[134:137], v[216:219], v[14:17]
	v_mfma_f32_16x16x32_bf16 v[10:13], v[142:145], v[216:219], v[10:13]
	s_barrier
	s_add_u32 s26, s46, 0x40000
	s_addc_u32 s27, s47, 0
	s_add_i32 s19, s19, s84
	s_mov_b32 m0, s19
	v_lshl_add_u64 v[130:131], s[26:27], 0, v[8:9]
	global_load_lds_dwordx4 v[130:131], off
	s_add_i32 m0, s19, 0x2000
	v_lshl_add_u64 v[130:131], s[26:27], 0, v[180:181]
	global_load_lds_dwordx4 v[130:131], off
	s_waitcnt vmcnt(6)
	ds_write_b128 v249, v[244:247]
	s_barrier
	v_mfma_f32_16x16x32_bf16 v[50:53], v[220:223], v[146:149], 0
	v_mfma_f32_16x16x32_bf16 v[54:57], v[228:231], v[146:149], 0
	v_mfma_f32_16x16x32_bf16 v[34:37], v[220:223], v[186:189], 0
	v_mfma_f32_16x16x32_bf16 v[38:41], v[228:231], v[186:189], 0
	v_mfma_f32_16x16x32_bf16 v[18:21], v[220:223], v[194:197], 0
	v_mfma_f32_16x16x32_bf16 v[22:25], v[228:231], v[194:197], 0
	v_mfma_f32_16x16x32_bf16 v[0:3], v[220:223], v[202:205], 0
	v_mfma_f32_16x16x32_bf16 v[4:7], v[228:231], v[202:205], 0
	v_mfma_f32_16x16x32_bf16 v[50:53], v[224:227], v[150:153], v[50:53]
	v_mfma_f32_16x16x32_bf16 v[54:57], v[232:235], v[150:153], v[54:57]
	v_mfma_f32_16x16x32_bf16 v[34:37], v[224:227], v[190:193], v[34:37]
	v_mfma_f32_16x16x32_bf16 v[38:41], v[232:235], v[190:193], v[38:41]
	v_mfma_f32_16x16x32_bf16 v[18:21], v[224:227], v[198:201], v[18:21]
	v_mfma_f32_16x16x32_bf16 v[22:25], v[232:235], v[198:201], v[22:25]
	v_mfma_f32_16x16x32_bf16 v[0:3], v[224:227], v[216:219], v[0:3]
	v_mfma_f32_16x16x32_bf16 v[4:7], v[232:235], v[216:219], v[4:7]
	s_add_i32 s19, 0, 0x18000
	v_add_u32_e32 v142, s19, v209
	s_barrier
	ds_read_b128 v[130:133], v142
	ds_read_b128 v[134:137], v142 offset:1024
	ds_read_b128 v[138:141], v142 offset:2048
	ds_read_b128 v[142:145], v142 offset:3072
	s_add_u32 s26, s68, 0x40000
	s_addc_u32 s27, s69, 0
	s_mov_b32 m0, s87
	v_lshl_add_u64 v[220:221], s[26:27], 0, v[176:177]
	ds_read_b128 v[146:149], v214 offset:32768
	ds_read_b128 v[150:153], v214 offset:33792
	ds_read_b128 v[186:189], v214 offset:34816
	ds_read_b128 v[190:193], v214 offset:35840
	ds_read_b128 v[194:197], v214 offset:36864
	ds_read_b128 v[198:201], v214 offset:37888
	ds_read_b128 v[202:205], v214 offset:38912
	ds_read_b128 v[216:219], v214 offset:39936
	global_load_lds_dwordx4 v[220:221], off
	s_mov_b32 m0, s88
	v_lshl_add_u64 v[220:221], s[26:27], 0, v[178:179]
	global_load_lds_dwordx4 v[220:221], off
	s_waitcnt lgkmcnt(8)
	s_barrier
	s_waitcnt lgkmcnt(0)
	v_mfma_f32_16x16x32_bf16 v[126:129], v[130:133], v[146:149], v[126:129]
	v_mfma_f32_16x16x32_bf16 v[122:125], v[138:141], v[146:149], v[122:125]
	v_mfma_f32_16x16x32_bf16 v[114:117], v[130:133], v[186:189], v[114:117]
	v_mfma_f32_16x16x32_bf16 v[106:109], v[138:141], v[186:189], v[106:109]
	v_mfma_f32_16x16x32_bf16 v[94:97], v[130:133], v[194:197], v[94:97]
	v_mfma_f32_16x16x32_bf16 v[90:93], v[138:141], v[194:197], v[90:93]
	v_mfma_f32_16x16x32_bf16 v[82:85], v[130:133], v[202:205], v[82:85]
	v_mfma_f32_16x16x32_bf16 v[74:77], v[138:141], v[202:205], v[74:77]
	v_mfma_f32_16x16x32_bf16 v[126:129], v[134:137], v[150:153], v[126:129]
	v_mfma_f32_16x16x32_bf16 v[122:125], v[142:145], v[150:153], v[122:125]
	v_mfma_f32_16x16x32_bf16 v[114:117], v[134:137], v[190:193], v[114:117]
	v_mfma_f32_16x16x32_bf16 v[106:109], v[142:145], v[190:193], v[106:109]
	v_mfma_f32_16x16x32_bf16 v[94:97], v[134:137], v[198:201], v[94:97]
	v_mfma_f32_16x16x32_bf16 v[90:93], v[142:145], v[198:201], v[90:93]
	v_mfma_f32_16x16x32_bf16 v[82:85], v[134:137], v[216:219], v[82:85]
	v_mfma_f32_16x16x32_bf16 v[74:77], v[142:145], v[216:219], v[74:77]
	s_barrier
; #define PG8_STAGE(bufoff, gbase, voff) do { _Pragma("unroll") for (int _i = 0; _i < 2; ++_i) \
;         __builtin_amdgcn_global_load_lds((const unsigned*)((const char*)(gbase) + (voff)[_i]), (LAS unsigned*)(lds + (bufoff) + ldsw + _i * 8192), 16, 0, 0); } while (0)
; #define PG8_LDA(dst, b, h) do { _Pragma("unroll") for (int m = 0; m < 4; ++m) _Pragma("unroll") for (int k = 0; k < 2; ++k) dst[m][k] = *(const LAS bf16x8*)(lds + PG8_SA(b, h) + aoff + m * 2048 + k * 1024); } while (0)
; #define PG8_LDB(dst, b, h) do { _Pragma("unroll") for (int n = 0; n < 2; ++n) _Pragma("unroll") for (int k = 0; k < 2; ++k) dst[n][k] = *(const LAS bf16x8*)(lds + PG8_SB(b, h) + boff + n * 2048 + k * 1024); } while (0)
; #define PG8_MMA(ai, bj, At, Bt) do { __builtin_amdgcn_s_setprio(1); _Pragma("unroll") for (int m = 0; m < 4; ++m) _Pragma("unroll") for (int n = 0; n < 2; ++n) _Pragma("unroll") for (int k = 0; k < 2; ++k) \
;         acc[ai][bj][m][n] = __builtin_amdgcn_mfma_f32_16x16x32_bf16(Bt[n][k], At[m][k], acc[ai][bj][m][n], 0, 0, 0); __builtin_amdgcn_s_setprio(0); } while (0)
; #define PG8_WAIT_V(n) asm volatile("s_waitcnt vmcnt(" #n ")" ::: "memory")
; #define PG8_WAIT_L(n) asm volatile("s_waitcnt lgkmcnt(" #n ")" ::: "memory")
; #define PG8_BAR __builtin_amdgcn_s_barrier()
; #define PG8_SCHED __builtin_amdgcn_sched_barrier(0)
; template <class Epi>
; DEVI void gemm_phase(LAS unsigned char* lds, const Gemm g, const Epi& E) {
;     ...
;             PG8_LDB(B1, 1, 1); PG8_STAGE(PG8_SB(1, 0), b3, voffB);
;             PG8_BAR; PG8_WAIT_L(0); PG8_MMA(0, 1, At, B1); PG8_BAR;
;             PG8_LDA(At, 1, 1); PG8_STAGE(PG8_SA(1, 0), a3, voffA);
;             PG8_BAR; PG8_WAIT_L(0); PG8_MMA(1, 0, At, B0); PG8_BAR; PG8_SCHED;
;             PG8_STAGE(PG8_SB(1, 1), b3 + hstepB, voffB);
;             PG8_WAIT_V(6); PG8_BAR; PG8_MMA(1, 1, At, B1); PG8_BAR;
;         }
	s_add_i32 s38, 0, 0x1c000
	s_add_i32 s19, s19, s84
	v_add_u32_e32 v162, s38, v209
	v_lshl_add_u64 v[206:207], v[206:207], 0, s[70:71]
	s_mov_b32 m0, s19
	ds_read_b128 v[220:223], v162
	ds_read_b128 v[224:227], v162 offset:1024
	ds_read_b128 v[228:231], v162 offset:2048
	ds_read_b128 v[232:235], v162 offset:3072
	global_load_lds_dwordx4 v[206:207], off
	s_add_i32 m0, s19, 0x2000
	v_lshl_add_u64 v[206:207], v[236:237], 0, s[70:71]
	global_load_lds_dwordx4 v[206:207], off
	s_barrier
	s_waitcnt lgkmcnt(0)
	v_mfma_f32_16x16x32_bf16 v[118:121], v[220:223], v[146:149], v[118:121]
	v_mfma_f32_16x16x32_bf16 v[110:113], v[228:231], v[146:149], v[110:113]
	v_mfma_f32_16x16x32_bf16 v[102:105], v[220:223], v[186:189], v[102:105]
	v_mfma_f32_16x16x32_bf16 v[98:101], v[228:231], v[186:189], v[98:101]
	v_mfma_f32_16x16x32_bf16 v[86:89], v[220:223], v[194:197], v[86:89]
	v_mfma_f32_16x16x32_bf16 v[78:81], v[228:231], v[194:197], v[78:81]
	v_mfma_f32_16x16x32_bf16 v[62:65], v[220:223], v[202:205], v[62:65]
	v_mfma_f32_16x16x32_bf16 v[58:61], v[228:231], v[202:205], v[58:61]
	v_mfma_f32_16x16x32_bf16 v[118:121], v[224:227], v[150:153], v[118:121]
	v_mfma_f32_16x16x32_bf16 v[110:113], v[232:235], v[150:153], v[110:113]
	v_mfma_f32_16x16x32_bf16 v[102:105], v[224:227], v[190:193], v[102:105]
	v_mfma_f32_16x16x32_bf16 v[98:101], v[232:235], v[190:193], v[98:101]
	v_mfma_f32_16x16x32_bf16 v[86:89], v[224:227], v[198:201], v[86:89]
	v_mfma_f32_16x16x32_bf16 v[78:81], v[232:235], v[198:201], v[78:81]
	v_mfma_f32_16x16x32_bf16 v[62:65], v[224:227], v[216:219], v[62:65]
	v_mfma_f32_16x16x32_bf16 v[58:61], v[232:235], v[216:219], v[58:61]
	s_mov_b32 m0, s89
	v_lshl_add_u64 v[206:207], v[238:239], 0, s[70:71]
	s_barrier
	ds_read_b128 v[146:149], v214 offset:49152
	ds_read_b128 v[150:153], v214 offset:50176
	ds_read_b128 v[186:189], v214 offset:51200
	ds_read_b128 v[190:193], v214 offset:52224
	ds_read_b128 v[194:197], v214 offset:53248
	ds_read_b128 v[198:201], v214 offset:54272
	ds_read_b128 v[202:205], v214 offset:55296
	ds_read_b128 v[216:219], v214 offset:56320
	global_load_lds_dwordx4 v[206:207], off
	s_mov_b32 m0, s90
	v_lshl_add_u64 v[206:207], v[240:241], 0, s[70:71]
	global_load_lds_dwordx4 v[206:207], off
	s_barrier
	s_waitcnt lgkmcnt(0)
	v_mfma_f32_16x16x32_bf16 v[70:73], v[130:133], v[146:149], v[70:73]
	v_mfma_f32_16x16x32_bf16 v[66:69], v[138:141], v[146:149], v[66:69]
	v_mfma_f32_16x16x32_bf16 v[46:49], v[130:133], v[186:189], v[46:49]
	v_mfma_f32_16x16x32_bf16 v[42:45], v[138:141], v[186:189], v[42:45]
	v_mfma_f32_16x16x32_bf16 v[30:33], v[130:133], v[194:197], v[30:33]
	v_mfma_f32_16x16x32_bf16 v[26:29], v[138:141], v[194:197], v[26:29]
	v_mfma_f32_16x16x32_bf16 v[14:17], v[130:133], v[202:205], v[14:17]
	v_mfma_f32_16x16x32_bf16 v[10:13], v[138:141], v[202:205], v[10:13]
	v_mfma_f32_16x16x32_bf16 v[70:73], v[134:137], v[150:153], v[70:73]
	v_mfma_f32_16x16x32_bf16 v[66:69], v[142:145], v[150:153], v[66:69]
	v_mfma_f32_16x16x32_bf16 v[46:49], v[134:137], v[190:193], v[46:49]
	v_mfma_f32_16x16x32_bf16 v[42:45], v[142:145], v[190:193], v[42:45]
	v_mfma_f32_16x16x32_bf16 v[30:33], v[134:137], v[198:201], v[30:33]
	v_mfma_f32_16x16x32_bf16 v[26:29], v[142:145], v[198:201], v[26:29]
	v_mfma_f32_16x16x32_bf16 v[14:17], v[134:137], v[216:219], v[14:17]
	v_mfma_f32_16x16x32_bf16 v[10:13], v[142:145], v[216:219], v[10:13]
	s_barrier
	s_add_u32 s26, s46, 0x40080
	s_addc_u32 s27, s47, 0
	s_add_i32 s19, s38, s84
	s_mov_b32 m0, s19
	v_lshl_add_u64 v[130:131], s[26:27], 0, v[8:9]
	global_load_lds_dwordx4 v[130:131], off
	s_add_i32 m0, s19, 0x2000
	v_lshl_add_u64 v[130:131], s[26:27], 0, v[180:181]
	global_load_lds_dwordx4 v[130:131], off
	s_waitcnt vmcnt(6)
	s_barrier
	v_mfma_f32_16x16x32_bf16 v[50:53], v[220:223], v[146:149], v[50:53]
	v_mfma_f32_16x16x32_bf16 v[54:57], v[228:231], v[146:149], v[54:57]
	v_mfma_f32_16x16x32_bf16 v[34:37], v[220:223], v[186:189], v[34:37]
	v_mfma_f32_16x16x32_bf16 v[38:41], v[228:231], v[186:189], v[38:41]
	v_mfma_f32_16x16x32_bf16 v[18:21], v[220:223], v[194:197], v[18:21]
	v_mfma_f32_16x16x32_bf16 v[22:25], v[228:231], v[194:197], v[22:25]
	v_mfma_f32_16x16x32_bf16 v[0:3], v[220:223], v[202:205], v[0:3]
	v_mfma_f32_16x16x32_bf16 v[4:7], v[228:231], v[202:205], v[4:7]
	v_mfma_f32_16x16x32_bf16 v[50:53], v[224:227], v[150:153], v[50:53]
	v_mfma_f32_16x16x32_bf16 v[54:57], v[232:235], v[150:153], v[54:57]
	v_mfma_f32_16x16x32_bf16 v[34:37], v[224:227], v[190:193], v[34:37]
	v_mfma_f32_16x16x32_bf16 v[38:41], v[232:235], v[190:193], v[38:41]
	v_mfma_f32_16x16x32_bf16 v[18:21], v[224:227], v[198:201], v[18:21]
	v_mfma_f32_16x16x32_bf16 v[22:25], v[232:235], v[198:201], v[22:25]
	v_mfma_f32_16x16x32_bf16 v[0:3], v[224:227], v[216:219], v[0:3]
	v_mfma_f32_16x16x32_bf16 v[4:7], v[232:235], v[216:219], v[4:7]
	s_add_i32 s18, s18, 2
	s_add_u32 s8, s8, 0x100
	s_addc_u32 s9, s9, 0
	s_add_u32 s11, s11, 0x100
	s_addc_u32 s13, s13, 0
	s_cmp_gt_u32 s18, 13
	s_barrier

; #define PG8_STAGE(bufoff, gbase, voff) do { _Pragma("unroll") for (int _i = 0; _i < 2; ++_i) \
;         __builtin_amdgcn_global_load_lds((const unsigned*)((const char*)(gbase) + (voff)[_i]), (LAS unsigned*)(lds + (bufoff) + ldsw + _i * 8192), 16, 0, 0); } while (0)
; #define PG8_LDA(dst, b, h) do { _Pragma("unroll") for (int m = 0; m < 4; ++m) _Pragma("unroll") for (int k = 0; k < 2; ++k) dst[m][k] = *(const LAS bf16x8*)(lds + PG8_SA(b, h) + aoff + m * 2048 + k * 1024); } while (0)
; #define PG8_LDB(dst, b, h) do { _Pragma("unroll") for (int n = 0; n < 2; ++n) _Pragma("unroll") for (int k = 0; k < 2; ++k) dst[n][k] = *(const LAS bf16x8*)(lds + PG8_SB(b, h) + boff + n * 2048 + k * 1024); } while (0)
; #define PG8_MMA(ai, bj, At, Bt) do { __builtin_amdgcn_s_setprio(1); _Pragma("unroll") for (int m = 0; m < 4; ++m) _Pragma("unroll") for (int n = 0; n < 2; ++n) _Pragma("unroll") for (int k = 0; k < 2; ++k) \
;         acc[ai][bj][m][n] = __builtin_amdgcn_mfma_f32_16x16x32_bf16(Bt[n][k], At[m][k], acc[ai][bj][m][n], 0, 0, 0); __builtin_amdgcn_s_setprio(0); } while (0)
; #define PG8_WAIT_L(n) asm volatile("s_waitcnt lgkmcnt(" #n ")" ::: "memory")
; #define PG8_BAR __builtin_amdgcn_s_barrier()
; #define PG8_SCHED __builtin_amdgcn_sched_barrier(0)
; template <class Epi>
; DEVI void gemm_phase(LAS unsigned char* lds, const Gemm g, const Epi& E) {
;     ...
;             PG8_LDB(B0, 0, 0); PG8_SCHED; PG8_LDA(At, 0, 0); PG8_STAGE(PG8_SA(1, 1), a1 + hstepA, voffA);
;             PG8_WAIT_L(8); PG8_BAR; PG8_WAIT_L(0); PG8_MMA(0, 0, At, B0); PG8_BAR; PG8_SCHED;
;     ...
;                 for (int i = 0; i < 8; ++i) q4[i] = *(const f32x4*)(E.ssq_in + (size_t)(row0 + (i >> 2) * HALF + (i & 3) * 16) * 4);
.Lip13l_b_in:
	s_and_b32 s101, s66, 0xc0
	s_mov_b32 s100, 1
	s_cmp_lg_u32 s101, 0
	s_cselect_b32 s101, 1, 0
	v_and_b32_e32 v248, 0xff, v154
	v_lshlrev_b32_e32 v248, 4, v248
	v_add_u32_e32 v249, 0x21000, v248
	v_lshl_add_u32 v248, s6, 12, v248
	global_load_dwordx4 v[244:247], v248, s[76:77]
	s_nop 0
	s_nop 0
	s_nop 0
	s_nop 0
	s_nop 0
	s_nop 0
	s_nop 0
	s_nop 0
	s_nop 0
	s_nop 0
	s_nop 0
	s_nop 0
	s_add_u32 s19, s8, 0xfffc0080
	s_addc_u32 s26, s9, -1
	s_add_i32 s27, 0, 0x10000
	v_add_u32_e32 v142, s27, v209
	ds_read_b128 v[130:133], v142
	ds_read_b128 v[134:137], v142 offset:1024
	ds_read_b128 v[138:141], v142 offset:2048
	ds_read_b128 v[142:145], v142 offset:3072
	s_cmp_eq_u32 s18, 12
	s_cselect_b32 s69, s0, s26
	s_cselect_b32 s68, s1, s19
	s_cselect_b32 s47, s5, s13
	s_cselect_b32 s46, s7, s11
	v_lshl_add_u64 v[206:207], s[8:9], 0, v[182:183]
	s_add_i32 m0, s85, 0xc000
	ds_read_b128 v[146:149], v214
	ds_read_b128 v[150:153], v214 offset:1024
	ds_read_b128 v[186:189], v214 offset:2048
	ds_read_b128 v[190:193], v214 offset:3072
	ds_read_b128 v[194:197], v214 offset:4096
	ds_read_b128 v[198:201], v214 offset:5120
	ds_read_b128 v[202:205], v214 offset:6144
	ds_read_b128 v[216:219], v214 offset:7168
	global_load_lds_dwordx4 v[206:207], off
	s_add_i32 m0, s85, 0xe000
	v_lshl_add_u64 v[206:207], s[8:9], 0, v[184:185]
	global_load_lds_dwordx4 v[206:207], off
	s_waitcnt lgkmcnt(8)
	s_barrier
	s_waitcnt lgkmcnt(0)
	s_cmp_lg_u32 s101, 0
	s_cbranch_scc1 .Lip13l_b_0
	v_mfma_f32_16x16x32_bf16 v[126:129], v[130:133], v[146:149], 0
	v_mfma_f32_16x16x32_bf16 v[122:125], v[138:141], v[146:149], 0
	v_mfma_f32_16x16x32_bf16 v[114:117], v[130:133], v[186:189], 0
	v_mfma_f32_16x16x32_bf16 v[106:109], v[138:141], v[186:189], 0
	v_mfma_f32_16x16x32_bf16 v[94:97], v[130:133], v[194:197], 0
	v_mfma_f32_16x16x32_bf16 v[90:93], v[138:141], v[194:197], 0
	v_mfma_f32_16x16x32_bf16 v[82:85], v[130:133], v[202:205], 0
	v_mfma_f32_16x16x32_bf16 v[74:77], v[138:141], v[202:205], 0
	v_mfma_f32_16x16x32_bf16 v[126:129], v[134:137], v[150:153], v[126:129]
	v_mfma_f32_16x16x32_bf16 v[122:125], v[142:145], v[150:153], v[122:125]
	v_mfma_f32_16x16x32_bf16 v[114:117], v[134:137], v[190:193], v[114:117]
	v_mfma_f32_16x16x32_bf16 v[106:109], v[142:145], v[190:193], v[106:109]
	v_mfma_f32_16x16x32_bf16 v[94:97], v[134:137], v[198:201], v[94:97]
	v_mfma_f32_16x16x32_bf16 v[90:93], v[142:145], v[198:201], v[90:93]
	v_mfma_f32_16x16x32_bf16 v[82:85], v[134:137], v[216:219], v[82:85]
	v_mfma_f32_16x16x32_bf16 v[74:77], v[142:145], v[216:219], v[74:77]

; DEVI size_t gemm_offB(const Gemm& g, const Unit& u) { return (g.split ? (size_t)(u.b >> 2) * g.sB + (size_t)(u.b & 3) * g.sB_lo : (size_t)u.b * g.sB) + (size_t)(u.pm >> g.pmsh) * g.sBpm; }
; #define PG8_STAGE(bufoff, gbase, voff) do { _Pragma("unroll") for (int _i = 0; _i < 2; ++_i) \
;         __builtin_amdgcn_global_load_lds((const unsigned*)((const char*)(gbase) + (voff)[_i]), (LAS unsigned*)(lds + (bufoff) + ldsw + _i * 8192), 16, 0, 0); } while (0)
; #define PG8_LDA(dst, b, h) do { _Pragma("unroll") for (int m = 0; m < 4; ++m) _Pragma("unroll") for (int k = 0; k < 2; ++k) dst[m][k] = *(const LAS bf16x8*)(lds + PG8_SA(b, h) + aoff + m * 2048 + k * 1024); } while (0)
; #define PG8_LDB(dst, b, h) do { _Pragma("unroll") for (int n = 0; n < 2; ++n) _Pragma("unroll") for (int k = 0; k < 2; ++k) dst[n][k] = *(const LAS bf16x8*)(lds + PG8_SB(b, h) + boff + n * 2048 + k * 1024); } while (0)
; #define PG8_WAIT_L(n) asm volatile("s_waitcnt lgkmcnt(" #n ")" ::: "memory")
; #define PG8_BAR __builtin_amdgcn_s_barrier()
; #define PG8_SCHED __builtin_amdgcn_sched_barrier(0)
; template <class Epi>
; DEVI void gemm_phase(LAS unsigned char* lds, const Gemm g, const Epi& E) {
;     ...
;         const bool has_next = unit_next(g, ui + 1, nxt);
;         const char* nA = has_next ? (const char*)g.A + gemm_offA(g, nxt) * 2 + (size_t)nxt.pm * tstepA : cA;
;         const char* nB = has_next ? (const char*)g.Bt + gemm_offB(g, nxt) * 2 + (size_t)nxt.pn * tstepB : cB;
;         for (int t = 0; t < nt; t += 2) {
;             const bool last = (t == nt - 2);
;             const char* a1 = cA + (size_t)(t + 1) * kstep;
;             const char* a2 = last ? nA : cA + (size_t)(t + 2) * kstep; const char* b2 = last ? nB : cB + (size_t)(t + 2) * kstep;
;             const char* a3 = a2 + kstep; const char* b3 = b2 + kstep;
;             PG8_LDB(B0, 0, 0); PG8_SCHED; PG8_LDA(At, 0, 0); PG8_STAGE(PG8_SA(1, 1), a1 + hstepA, voffA);
;             PG8_WAIT_L(8); PG8_BAR; PG8_WAIT_L(0); PG8_MMA(0, 0, At, B0); PG8_BAR; PG8_SCHED;
;             PG8_LDB(B1, 0, 1); PG8_STAGE(PG8_SB(0, 0), b2, voffB);
;             PG8_BAR; PG8_WAIT_L(0); PG8_MMA(0, 1, At, B1); PG8_BAR;
;             PG8_LDA(At, 0, 1); PG8_STAGE(PG8_SA(0, 0), a2, voffA);
;             PG8_BAR; PG8_WAIT_L(0); PG8_MMA(1, 0, At, B0); PG8_BAR; PG8_SCHED;
.LBB0_967:
	s_ashr_i32 s13, s12, 31
	s_lshl_b64 s[0:1], s[12:13], 19
	v_cmp_lt_i64_e32 vcc, s[16:17], v[168:169]
	s_add_u32 s16, s24, s0
	s_addc_u32 s17, s25, s1
	s_and_b64 s[0:1], vcc, exec
	s_cselect_b32 s0, s17, s69
	s_cselect_b32 s1, s16, s68
	s_ashr_i32 s15, s14, 31
	s_lshl_b64 s[18:19], s[14:15], 19
	v_readlane_b32 s26, v254, 9
	v_readlane_b32 s27, v254, 10
	s_add_u32 s36, s26, s18
	s_addc_u32 s37, s27, s19
	s_and_b64 s[18:19], vcc, exec
	s_cselect_b32 s9, s37, s81
	s_cselect_b32 s13, s36, s80
	s_add_u32 s68, s68, 0x40080
	s_addc_u32 s69, s69, 0
	s_add_u32 s15, s80, 0x100
	s_addc_u32 s18, s81, 0
	s_mov_b32 s19, -2
	s_waitcnt lgkmcnt(0)
	s_nop 0
	s_nop 0
	s_nop 0
	s_nop 0
	s_nop 0
	s_nop 0
	s_nop 0
	s_nop 0
	s_nop 0
	s_nop 0
	s_nop 0
	s_add_u32 s26, s68, 0xfffc0080
	s_addc_u32 s27, s69, -1
	s_add_i32 s38, 0, 0x10000
	v_add_u32_e32 v142, s38, v193
	ds_read_b128 v[130:133], v142
	ds_read_b128 v[134:137], v142 offset:1024
	ds_read_b128 v[138:141], v142 offset:2048
	ds_read_b128 v[142:145], v142 offset:3072
	s_cmp_eq_u32 s19, 12
	s_cselect_b32 s83, s0, s27
	s_cselect_b32 s82, s1, s26
	s_cselect_b32 s81, s9, s18
	s_cselect_b32 s80, s13, s15
	v_lshl_add_u64 v[162:163], s[68:69], 0, v[178:179]
	s_add_i32 m0, s85, 0xc000
	ds_read_b128 v[146:149], v198
	ds_read_b128 v[182:185], v198 offset:1024
	ds_read_b128 v[186:189], v198 offset:2048
	ds_read_b128 v[200:203], v198 offset:3072
	ds_read_b128 v[204:207], v198 offset:4096
	ds_read_b128 v[214:217], v198 offset:5120
	ds_read_b128 v[218:221], v198 offset:6144
	ds_read_b128 v[222:225], v198 offset:7168
	global_load_lds_dwordx4 v[162:163], off
	s_add_i32 m0, s85, 0xe000
	v_lshl_add_u64 v[162:163], s[68:69], 0, v[180:181]
	global_load_lds_dwordx4 v[162:163], off
	s_waitcnt lgkmcnt(8)
	s_barrier
	s_waitcnt lgkmcnt(0)
	v_mfma_f32_16x16x32_bf16 v[126:129], v[130:133], v[146:149], 0
	v_mfma_f32_16x16x32_bf16 v[122:125], v[138:141], v[146:149], 0
	v_mfma_f32_16x16x32_bf16 v[110:113], v[130:133], v[186:189], 0
	v_mfma_f32_16x16x32_bf16 v[106:109], v[138:141], v[186:189], 0
	v_mfma_f32_16x16x32_bf16 v[94:97], v[130:133], v[204:207], 0
	v_mfma_f32_16x16x32_bf16 v[90:93], v[138:141], v[204:207], 0
	v_mfma_f32_16x16x32_bf16 v[78:81], v[130:133], v[218:221], 0
	v_mfma_f32_16x16x32_bf16 v[74:77], v[138:141], v[218:221], 0
	v_mfma_f32_16x16x32_bf16 v[126:129], v[134:137], v[182:185], v[126:129]
	v_mfma_f32_16x16x32_bf16 v[122:125], v[142:145], v[182:185], v[122:125]
	v_mfma_f32_16x16x32_bf16 v[110:113], v[134:137], v[200:203], v[110:113]
	v_mfma_f32_16x16x32_bf16 v[106:109], v[142:145], v[200:203], v[106:109]
	v_mfma_f32_16x16x32_bf16 v[94:97], v[134:137], v[214:217], v[94:97]
	v_mfma_f32_16x16x32_bf16 v[90:93], v[142:145], v[214:217], v[90:93]
	v_mfma_f32_16x16x32_bf16 v[78:81], v[134:137], v[222:225], v[78:81]
	v_mfma_f32_16x16x32_bf16 v[74:77], v[142:145], v[222:225], v[74:77]
	s_barrier
	s_add_i32 s39, 0, 0x14000
	v_add_u32_e32 v162, s39, v193
	s_add_i32 s26, s38, s84
	ds_read_b128 v[226:229], v162
	ds_read_b128 v[230:233], v162 offset:1024
	ds_read_b128 v[234:237], v162 offset:2048
	ds_read_b128 v[238:241], v162 offset:3072
	v_lshl_add_u64 v[162:163], s[80:81], 0, v[8:9]
	s_mov_b32 m0, s26
	v_lshl_add_u64 v[164:165], s[80:81], 0, v[176:177]
	global_load_lds_dwordx4 v[162:163], off
	s_add_i32 m0, s26, 0x2000
	s_nop 0
	global_load_lds_dwordx4 v[164:165], off
	s_barrier
	s_waitcnt lgkmcnt(0)
	v_mfma_f32_16x16x32_bf16 v[118:121], v[226:229], v[146:149], 0
	v_mfma_f32_16x16x32_bf16 v[114:117], v[234:237], v[146:149], 0
	v_mfma_f32_16x16x32_bf16 v[102:105], v[226:229], v[186:189], 0
	v_mfma_f32_16x16x32_bf16 v[98:101], v[234:237], v[186:189], 0
	v_mfma_f32_16x16x32_bf16 v[86:89], v[226:229], v[204:207], 0
	v_mfma_f32_16x16x32_bf16 v[82:85], v[234:237], v[204:207], 0
	v_mfma_f32_16x16x32_bf16 v[70:73], v[226:229], v[218:221], 0
	v_mfma_f32_16x16x32_bf16 v[66:69], v[234:237], v[218:221], 0
	v_mfma_f32_16x16x32_bf16 v[118:121], v[230:233], v[182:185], v[118:121]
	v_mfma_f32_16x16x32_bf16 v[114:117], v[238:241], v[182:185], v[114:117]
	v_mfma_f32_16x16x32_bf16 v[102:105], v[230:233], v[200:203], v[102:105]
	v_mfma_f32_16x16x32_bf16 v[98:101], v[238:241], v[200:203], v[98:101]
	v_mfma_f32_16x16x32_bf16 v[86:89], v[230:233], v[214:217], v[86:89]
	v_mfma_f32_16x16x32_bf16 v[82:85], v[238:241], v[214:217], v[82:85]
	v_mfma_f32_16x16x32_bf16 v[70:73], v[230:233], v[222:225], v[70:73]
	v_mfma_f32_16x16x32_bf16 v[66:69], v[238:241], v[222:225], v[66:69]
	s_mov_b32 m0, s85
	v_lshl_add_u64 v[190:191], s[82:83], 0, v[150:151]
	s_barrier
	ds_read_b128 v[146:149], v198 offset:16384
	ds_read_b128 v[182:185], v198 offset:17408
	ds_read_b128 v[186:189], v198 offset:18432
	ds_read_b128 v[200:203], v198 offset:19456
	ds_read_b128 v[204:207], v198 offset:20480
	ds_read_b128 v[214:217], v198 offset:21504
	ds_read_b128 v[218:221], v198 offset:22528
	ds_read_b128 v[222:225], v198 offset:23552
	global_load_lds_dwordx4 v[190:191], off
	s_mov_b32 m0, s86
	v_lshl_add_u64 v[208:209], s[82:83], 0, v[152:153]
	global_load_lds_dwordx4 v[208:209], off
	s_barrier
	s_waitcnt lgkmcnt(0)
	v_mfma_f32_16x16x32_bf16 v[62:65], v[130:133], v[146:149], 0
	v_mfma_f32_16x16x32_bf16 v[58:61], v[138:141], v[146:149], 0
	v_mfma_f32_16x16x32_bf16 v[46:49], v[130:133], v[186:189], 0
	v_mfma_f32_16x16x32_bf16 v[42:45], v[138:141], v[186:189], 0
	v_mfma_f32_16x16x32_bf16 v[30:33], v[130:133], v[204:207], 0
	v_mfma_f32_16x16x32_bf16 v[26:29], v[138:141], v[204:207], 0
	v_mfma_f32_16x16x32_bf16 v[14:17], v[130:133], v[218:221], 0
	v_mfma_f32_16x16x32_bf16 v[10:13], v[138:141], v[218:221], 0
	v_mfma_f32_16x16x32_bf16 v[62:65], v[134:137], v[182:185], v[62:65]
	v_mfma_f32_16x16x32_bf16 v[58:61], v[142:145], v[182:185], v[58:61]
	v_mfma_f32_16x16x32_bf16 v[46:49], v[134:137], v[200:203], v[46:49]
	v_mfma_f32_16x16x32_bf16 v[42:45], v[142:145], v[200:203], v[42:45]
	v_mfma_f32_16x16x32_bf16 v[30:33], v[134:137], v[214:217], v[30:33]
	v_mfma_f32_16x16x32_bf16 v[26:29], v[142:145], v[214:217], v[26:29]
	v_mfma_f32_16x16x32_bf16 v[14:17], v[134:137], v[222:225], v[14:17]
	v_mfma_f32_16x16x32_bf16 v[10:13], v[142:145], v[222:225], v[10:13]
	s_barrier
; #define PG8_STAGE(bufoff, gbase, voff) do { _Pragma("unroll") for (int _i = 0; _i < 2; ++_i) \
;         __builtin_amdgcn_global_load_lds((const unsigned*)((const char*)(gbase) + (voff)[_i]), (LAS unsigned*)(lds + (bufoff) + ldsw + _i * 8192), 16, 0, 0); } while (0)
; #define PG8_LDA(dst, b, h) do { _Pragma("unroll") for (int m = 0; m < 4; ++m) _Pragma("unroll") for (int k = 0; k < 2; ++k) dst[m][k] = *(const LAS bf16x8*)(lds + PG8_SA(b, h) + aoff + m * 2048 + k * 1024); } while (0)
; #define PG8_LDB(dst, b, h) do { _Pragma("unroll") for (int n = 0; n < 2; ++n) _Pragma("unroll") for (int k = 0; k < 2; ++k) dst[n][k] = *(const LAS bf16x8*)(lds + PG8_SB(b, h) + boff + n * 2048 + k * 1024); } while (0)
; #define PG8_MMA(ai, bj, At, Bt) do { __builtin_amdgcn_s_setprio(1); _Pragma("unroll") for (int m = 0; m < 4; ++m) _Pragma("unroll") for (int n = 0; n < 2; ++n) _Pragma("unroll") for (int k = 0; k < 2; ++k) \
;         acc[ai][bj][m][n] = __builtin_amdgcn_mfma_f32_16x16x32_bf16(Bt[n][k], At[m][k], acc[ai][bj][m][n], 0, 0, 0); __builtin_amdgcn_s_setprio(0); } while (0)
; #define PG8_WAIT_V(n) asm volatile("s_waitcnt vmcnt(" #n ")" ::: "memory")
; #define PG8_WAIT_L(n) asm volatile("s_waitcnt lgkmcnt(" #n ")" ::: "memory")
; #define PG8_BAR __builtin_amdgcn_s_barrier()
; #define PG8_SCHED __builtin_amdgcn_sched_barrier(0)
; template <class Epi>
; DEVI void gemm_phase(LAS unsigned char* lds, const Gemm g, const Epi& E) {
;     ...
;             PG8_STAGE(PG8_SB(0, 1), b2 + hstepB, voffB);
;             PG8_WAIT_V(6); PG8_BAR; PG8_MMA(1, 1, At, B1); PG8_BAR;
;             PG8_LDB(B0, 1, 0); PG8_SCHED; PG8_LDA(At, 1, 0); PG8_STAGE(PG8_SA(0, 1), a2 + hstepA, voffA);
;             PG8_WAIT_L(8); PG8_BAR; PG8_WAIT_L(0); PG8_MMA(0, 0, At, B0); PG8_BAR; PG8_SCHED;
;             PG8_LDB(B1, 1, 1); PG8_STAGE(PG8_SB(1, 0), b3, voffB);
	s_add_u32 s26, s80, 0x40000
	s_addc_u32 s27, s81, 0
	s_add_i32 s38, s39, s84
	s_mov_b32 m0, s38
	v_lshl_add_u64 v[130:131], s[26:27], 0, v[8:9]
	global_load_lds_dwordx4 v[130:131], off
	s_add_i32 m0, s38, 0x2000
	v_lshl_add_u64 v[130:131], s[26:27], 0, v[176:177]
	global_load_lds_dwordx4 v[130:131], off
	s_waitcnt vmcnt(6)
	s_barrier
	v_mfma_f32_16x16x32_bf16 v[54:57], v[226:229], v[146:149], 0
	v_mfma_f32_16x16x32_bf16 v[50:53], v[234:237], v[146:149], 0
	v_mfma_f32_16x16x32_bf16 v[38:41], v[226:229], v[186:189], 0
	v_mfma_f32_16x16x32_bf16 v[34:37], v[234:237], v[186:189], 0
	v_mfma_f32_16x16x32_bf16 v[22:25], v[226:229], v[204:207], 0
	v_mfma_f32_16x16x32_bf16 v[18:21], v[234:237], v[204:207], 0
	v_mfma_f32_16x16x32_bf16 v[4:7], v[226:229], v[218:221], 0
	v_mfma_f32_16x16x32_bf16 v[0:3], v[234:237], v[218:221], 0
	v_mfma_f32_16x16x32_bf16 v[54:57], v[230:233], v[182:185], v[54:57]
	v_mfma_f32_16x16x32_bf16 v[50:53], v[238:241], v[182:185], v[50:53]
	v_mfma_f32_16x16x32_bf16 v[38:41], v[230:233], v[200:203], v[38:41]
	v_mfma_f32_16x16x32_bf16 v[34:37], v[238:241], v[200:203], v[34:37]
	v_mfma_f32_16x16x32_bf16 v[22:25], v[230:233], v[214:217], v[22:25]
	v_mfma_f32_16x16x32_bf16 v[18:21], v[238:241], v[214:217], v[18:21]
	v_mfma_f32_16x16x32_bf16 v[4:7], v[230:233], v[222:225], v[4:7]
	v_mfma_f32_16x16x32_bf16 v[0:3], v[238:241], v[222:225], v[0:3]
	s_add_i32 s38, 0, 0x18000
	v_add_u32_e32 v142, s38, v193
	s_barrier
	ds_read_b128 v[130:133], v142
	ds_read_b128 v[134:137], v142 offset:1024
	ds_read_b128 v[138:141], v142 offset:2048
	ds_read_b128 v[142:145], v142 offset:3072
	s_add_u32 s26, s82, 0x40000
	s_addc_u32 s27, s83, 0
	s_mov_b32 m0, s87
	v_lshl_add_u64 v[226:227], s[26:27], 0, v[150:151]
	ds_read_b128 v[146:149], v198 offset:32768
	ds_read_b128 v[182:185], v198 offset:33792
	ds_read_b128 v[186:189], v198 offset:34816
	ds_read_b128 v[200:203], v198 offset:35840
	ds_read_b128 v[204:207], v198 offset:36864
	ds_read_b128 v[214:217], v198 offset:37888
	ds_read_b128 v[218:221], v198 offset:38912
	ds_read_b128 v[222:225], v198 offset:39936
	global_load_lds_dwordx4 v[226:227], off
	s_mov_b32 m0, s88
	v_lshl_add_u64 v[226:227], s[26:27], 0, v[152:153]
	global_load_lds_dwordx4 v[226:227], off
	s_waitcnt lgkmcnt(8)
	s_barrier
	s_waitcnt lgkmcnt(0)
	v_mfma_f32_16x16x32_bf16 v[126:129], v[130:133], v[146:149], v[126:129]
	v_mfma_f32_16x16x32_bf16 v[122:125], v[138:141], v[146:149], v[122:125]
	v_mfma_f32_16x16x32_bf16 v[110:113], v[130:133], v[186:189], v[110:113]
	v_mfma_f32_16x16x32_bf16 v[106:109], v[138:141], v[186:189], v[106:109]
	v_mfma_f32_16x16x32_bf16 v[94:97], v[130:133], v[204:207], v[94:97]
	v_mfma_f32_16x16x32_bf16 v[90:93], v[138:141], v[204:207], v[90:93]
	v_mfma_f32_16x16x32_bf16 v[78:81], v[130:133], v[218:221], v[78:81]
	v_mfma_f32_16x16x32_bf16 v[74:77], v[138:141], v[218:221], v[74:77]
	v_mfma_f32_16x16x32_bf16 v[126:129], v[134:137], v[182:185], v[126:129]
	v_mfma_f32_16x16x32_bf16 v[122:125], v[142:145], v[182:185], v[122:125]
	v_mfma_f32_16x16x32_bf16 v[110:113], v[134:137], v[200:203], v[110:113]
	v_mfma_f32_16x16x32_bf16 v[106:109], v[142:145], v[200:203], v[106:109]
	v_mfma_f32_16x16x32_bf16 v[94:97], v[134:137], v[214:217], v[94:97]
	v_mfma_f32_16x16x32_bf16 v[90:93], v[142:145], v[214:217], v[90:93]
	v_mfma_f32_16x16x32_bf16 v[78:81], v[134:137], v[222:225], v[78:81]
	v_mfma_f32_16x16x32_bf16 v[74:77], v[142:145], v[222:225], v[74:77]
	s_barrier
	s_add_i32 s39, 0, 0x1c000
	s_add_i32 s26, s38, s84
	v_add_u32_e32 v199, s39, v193
	v_lshl_add_u64 v[162:163], v[162:163], 0, s[70:71]
	s_mov_b32 m0, s26
	ds_read_b128 v[226:229], v199
	ds_read_b128 v[230:233], v199 offset:1024
	ds_read_b128 v[234:237], v199 offset:2048
	ds_read_b128 v[238:241], v199 offset:3072
	global_load_lds_dwordx4 v[162:163], off
	s_add_i32 m0, s26, 0x2000
	v_lshl_add_u64 v[162:163], v[164:165], 0, s[70:71]
	global_load_lds_dwordx4 v[162:163], off
	s_barrier
; #define PG8_STAGE(bufoff, gbase, voff) do { _Pragma("unroll") for (int _i = 0; _i < 2; ++_i) \
;         __builtin_amdgcn_global_load_lds((const unsigned*)((const char*)(gbase) + (voff)[_i]), (LAS unsigned*)(lds + (bufoff) + ldsw + _i * 8192), 16, 0, 0); } while (0)
; #define PG8_LDA(dst, b, h) do { _Pragma("unroll") for (int m = 0; m < 4; ++m) _Pragma("unroll") for (int k = 0; k < 2; ++k) dst[m][k] = *(const LAS bf16x8*)(lds + PG8_SA(b, h) + aoff + m * 2048 + k * 1024); } while (0)
; #define PG8_MMA(ai, bj, At, Bt) do { __builtin_amdgcn_s_setprio(1); _Pragma("unroll") for (int m = 0; m < 4; ++m) _Pragma("unroll") for (int n = 0; n < 2; ++n) _Pragma("unroll") for (int k = 0; k < 2; ++k) \
;         acc[ai][bj][m][n] = __builtin_amdgcn_mfma_f32_16x16x32_bf16(Bt[n][k], At[m][k], acc[ai][bj][m][n], 0, 0, 0); __builtin_amdgcn_s_setprio(0); } while (0)
; #define PG8_WAIT_V(n) asm volatile("s_waitcnt vmcnt(" #n ")" ::: "memory")
; #define PG8_WAIT_L(n) asm volatile("s_waitcnt lgkmcnt(" #n ")" ::: "memory")
; #define PG8_BAR __builtin_amdgcn_s_barrier()
; #define PG8_SCHED __builtin_amdgcn_sched_barrier(0)
; template <class Epi>
; DEVI void gemm_phase(LAS unsigned char* lds, const Gemm g, const Epi& E) {
;     ...
;             PG8_BAR; PG8_WAIT_L(0); PG8_MMA(0, 1, At, B1); PG8_BAR;
;             PG8_LDA(At, 1, 1); PG8_STAGE(PG8_SA(1, 0), a3, voffA);
;             PG8_BAR; PG8_WAIT_L(0); PG8_MMA(1, 0, At, B0); PG8_BAR; PG8_SCHED;
;             PG8_STAGE(PG8_SB(1, 1), b3 + hstepB, voffB);
;             PG8_WAIT_V(6); PG8_BAR; PG8_MMA(1, 1, At, B1); PG8_BAR;
;         }
	s_waitcnt lgkmcnt(0)
	v_mfma_f32_16x16x32_bf16 v[118:121], v[226:229], v[146:149], v[118:121]
	v_mfma_f32_16x16x32_bf16 v[114:117], v[234:237], v[146:149], v[114:117]
	v_mfma_f32_16x16x32_bf16 v[102:105], v[226:229], v[186:189], v[102:105]
	v_mfma_f32_16x16x32_bf16 v[98:101], v[234:237], v[186:189], v[98:101]
	v_mfma_f32_16x16x32_bf16 v[86:89], v[226:229], v[204:207], v[86:89]
	v_mfma_f32_16x16x32_bf16 v[82:85], v[234:237], v[204:207], v[82:85]
	v_mfma_f32_16x16x32_bf16 v[70:73], v[226:229], v[218:221], v[70:73]
	v_mfma_f32_16x16x32_bf16 v[66:69], v[234:237], v[218:221], v[66:69]
	v_mfma_f32_16x16x32_bf16 v[118:121], v[230:233], v[182:185], v[118:121]
	v_mfma_f32_16x16x32_bf16 v[114:117], v[238:241], v[182:185], v[114:117]
	v_mfma_f32_16x16x32_bf16 v[102:105], v[230:233], v[200:203], v[102:105]
	v_mfma_f32_16x16x32_bf16 v[98:101], v[238:241], v[200:203], v[98:101]
	v_mfma_f32_16x16x32_bf16 v[86:89], v[230:233], v[214:217], v[86:89]
	v_mfma_f32_16x16x32_bf16 v[82:85], v[238:241], v[214:217], v[82:85]
	v_mfma_f32_16x16x32_bf16 v[70:73], v[230:233], v[222:225], v[70:73]
	v_mfma_f32_16x16x32_bf16 v[66:69], v[238:241], v[222:225], v[66:69]
	s_mov_b32 m0, s89
	v_lshl_add_u64 v[162:163], v[190:191], 0, s[70:71]
	s_barrier
	ds_read_b128 v[146:149], v198 offset:49152
	ds_read_b128 v[182:185], v198 offset:50176
	ds_read_b128 v[186:189], v198 offset:51200
	ds_read_b128 v[200:203], v198 offset:52224
	ds_read_b128 v[204:207], v198 offset:53248
	ds_read_b128 v[214:217], v198 offset:54272
	ds_read_b128 v[218:221], v198 offset:55296
	ds_read_b128 v[222:225], v198 offset:56320
	global_load_lds_dwordx4 v[162:163], off
	s_mov_b32 m0, s90
	v_lshl_add_u64 v[162:163], v[208:209], 0, s[70:71]
	global_load_lds_dwordx4 v[162:163], off
	s_barrier
	s_waitcnt lgkmcnt(0)
	v_mfma_f32_16x16x32_bf16 v[62:65], v[130:133], v[146:149], v[62:65]
	v_mfma_f32_16x16x32_bf16 v[58:61], v[138:141], v[146:149], v[58:61]
	v_mfma_f32_16x16x32_bf16 v[46:49], v[130:133], v[186:189], v[46:49]
	v_mfma_f32_16x16x32_bf16 v[42:45], v[138:141], v[186:189], v[42:45]
	v_mfma_f32_16x16x32_bf16 v[30:33], v[130:133], v[204:207], v[30:33]
	v_mfma_f32_16x16x32_bf16 v[26:29], v[138:141], v[204:207], v[26:29]
	v_mfma_f32_16x16x32_bf16 v[14:17], v[130:133], v[218:221], v[14:17]
	v_mfma_f32_16x16x32_bf16 v[10:13], v[138:141], v[218:221], v[10:13]
	v_mfma_f32_16x16x32_bf16 v[62:65], v[134:137], v[182:185], v[62:65]
	v_mfma_f32_16x16x32_bf16 v[58:61], v[142:145], v[182:185], v[58:61]
	v_mfma_f32_16x16x32_bf16 v[46:49], v[134:137], v[200:203], v[46:49]
	v_mfma_f32_16x16x32_bf16 v[42:45], v[142:145], v[200:203], v[42:45]
	v_mfma_f32_16x16x32_bf16 v[30:33], v[134:137], v[214:217], v[30:33]
	v_mfma_f32_16x16x32_bf16 v[26:29], v[142:145], v[214:217], v[26:29]
	v_mfma_f32_16x16x32_bf16 v[14:17], v[134:137], v[222:225], v[14:17]
	v_mfma_f32_16x16x32_bf16 v[10:13], v[142:145], v[222:225], v[10:13]
	s_barrier
	s_add_u32 s26, s80, 0x40080
	s_addc_u32 s27, s81, 0
	s_add_i32 s38, s39, s84
	s_mov_b32 m0, s38
	v_lshl_add_u64 v[130:131], s[26:27], 0, v[8:9]
	global_load_lds_dwordx4 v[130:131], off
	s_add_i32 m0, s38, 0x2000
	v_lshl_add_u64 v[130:131], s[26:27], 0, v[176:177]
	global_load_lds_dwordx4 v[130:131], off
	s_waitcnt vmcnt(6)
	s_barrier
	v_mfma_f32_16x16x32_bf16 v[54:57], v[226:229], v[146:149], v[54:57]
	v_mfma_f32_16x16x32_bf16 v[50:53], v[234:237], v[146:149], v[50:53]
	v_mfma_f32_16x16x32_bf16 v[38:41], v[226:229], v[186:189], v[38:41]
	v_mfma_f32_16x16x32_bf16 v[34:37], v[234:237], v[186:189], v[34:37]
	v_mfma_f32_16x16x32_bf16 v[22:25], v[226:229], v[204:207], v[22:25]
	v_mfma_f32_16x16x32_bf16 v[18:21], v[234:237], v[204:207], v[18:21]
	v_mfma_f32_16x16x32_bf16 v[4:7], v[226:229], v[218:221], v[4:7]
	v_mfma_f32_16x16x32_bf16 v[0:3], v[234:237], v[218:221], v[0:3]
	v_mfma_f32_16x16x32_bf16 v[54:57], v[230:233], v[182:185], v[54:57]
	v_mfma_f32_16x16x32_bf16 v[50:53], v[238:241], v[182:185], v[50:53]
	v_mfma_f32_16x16x32_bf16 v[38:41], v[230:233], v[200:203], v[38:41]
	v_mfma_f32_16x16x32_bf16 v[34:37], v[238:241], v[200:203], v[34:37]
	v_mfma_f32_16x16x32_bf16 v[22:25], v[230:233], v[214:217], v[22:25]
	v_mfma_f32_16x16x32_bf16 v[18:21], v[238:241], v[214:217], v[18:21]
	v_mfma_f32_16x16x32_bf16 v[4:7], v[230:233], v[222:225], v[4:7]
	v_mfma_f32_16x16x32_bf16 v[0:3], v[238:241], v[222:225], v[0:3]
	s_add_i32 s19, s19, 2
	s_add_u32 s68, s68, 0x100
	s_addc_u32 s69, s69, 0
	s_add_u32 s15, s15, 0x100
	s_addc_u32 s18, s18, 0
	s_cmp_gt_u32 s19, 13
	s_barrier

; DEVI size_t gemm_offB(const Gemm& g, const Unit& u) { return (g.split ? (size_t)(u.b >> 2) * g.sB + (size_t)(u.b & 3) * g.sB_lo : (size_t)u.b * g.sB) + (size_t)(u.pm >> g.pmsh) * g.sBpm; }
; #define PG8_STAGE(bufoff, gbase, voff) do { _Pragma("unroll") for (int _i = 0; _i < 2; ++_i) \
;         __builtin_amdgcn_global_load_lds((const unsigned*)((const char*)(gbase) + (voff)[_i]), (LAS unsigned*)(lds + (bufoff) + ldsw + _i * 8192), 16, 0, 0); } while (0)
; #define PG8_LDA(dst, b, h) do { _Pragma("unroll") for (int m = 0; m < 4; ++m) _Pragma("unroll") for (int k = 0; k < 2; ++k) dst[m][k] = *(const LAS bf16x8*)(lds + PG8_SA(b, h) + aoff + m * 2048 + k * 1024); } while (0)
; #define PG8_LDB(dst, b, h) do { _Pragma("unroll") for (int n = 0; n < 2; ++n) _Pragma("unroll") for (int k = 0; k < 2; ++k) dst[n][k] = *(const LAS bf16x8*)(lds + PG8_SB(b, h) + boff + n * 2048 + k * 1024); } while (0)
; #define PG8_WAIT_L(n) asm volatile("s_waitcnt lgkmcnt(" #n ")" ::: "memory")
; #define PG8_BAR __builtin_amdgcn_s_barrier()
; #define PG8_SCHED __builtin_amdgcn_sched_barrier(0)
; template <class Epi>
; DEVI void gemm_phase(LAS unsigned char* lds, const Gemm g, const Epi& E) {
;     ...
;         const bool has_next = unit_next(g, ui + 1, nxt);
;         const char* nA = has_next ? (const char*)g.A + gemm_offA(g, nxt) * 2 + (size_t)nxt.pm * tstepA : cA;
;         const char* nB = has_next ? (const char*)g.Bt + gemm_offB(g, nxt) * 2 + (size_t)nxt.pn * tstepB : cB;
;         for (int t = 0; t < nt; t += 2) {
;             const bool last = (t == nt - 2);
;             const char* a1 = cA + (size_t)(t + 1) * kstep;
;             const char* a2 = last ? nA : cA + (size_t)(t + 2) * kstep; const char* b2 = last ? nB : cB + (size_t)(t + 2) * kstep;
;             const char* a3 = a2 + kstep; const char* b3 = b2 + kstep;
;             PG8_LDB(B0, 0, 0); PG8_SCHED; PG8_LDA(At, 0, 0); PG8_STAGE(PG8_SA(1, 1), a1 + hstepA, voffA);
;             PG8_WAIT_L(8); PG8_BAR; PG8_WAIT_L(0); PG8_MMA(0, 0, At, B0); PG8_BAR; PG8_SCHED;
;             PG8_LDB(B1, 0, 1); PG8_STAGE(PG8_SB(0, 0), b2, voffB);
;             PG8_BAR; PG8_WAIT_L(0); PG8_MMA(0, 1, At, B1); PG8_BAR;
;             PG8_LDA(At, 0, 1); PG8_STAGE(PG8_SA(0, 0), a2, voffA);
;             PG8_BAR; PG8_WAIT_L(0); PG8_MMA(1, 0, At, B0); PG8_BAR; PG8_SCHED;
.LBB0_1006:
	s_ashr_i32 s7, s6, 31
	s_lshl_b64 s[0:1], s[6:7], 19
	v_cmp_lt_i64_e32 vcc, s[10:11], v[168:169]
	s_add_u32 s10, s24, s0
	s_addc_u32 s11, s25, s1
	s_and_b64 s[0:1], vcc, exec
	s_cselect_b32 s0, s11, s15
	s_cselect_b32 s1, s10, s14
	s_ashr_i32 s9, s8, 31
	s_lshl_b64 s[12:13], s[8:9], 19
	v_readlane_b32 s18, v251, 60
	v_readlane_b32 s19, v251, 61
	s_add_u32 s12, s18, s12
	s_addc_u32 s13, s19, s13
	s_and_b64 s[18:19], vcc, exec
	s_cselect_b32 s5, s13, s17
	s_cselect_b32 s7, s12, s16
	s_add_u32 s14, s14, 0x40080
	s_addc_u32 s15, s15, 0
	s_add_u32 s9, s16, 0x100
	s_addc_u32 s18, s17, 0
	s_mov_b32 s19, -2
	s_nop 0
	s_add_u32 s16, s14, 0xfffc0080
	s_addc_u32 s17, s15, -1
	s_add_i32 s26, 0, 0x10000
	v_add_u32_e32 v8, s26, v199
	ds_read_b128 v[130:133], v8
	ds_read_b128 v[134:137], v8 offset:1024
	ds_read_b128 v[138:141], v8 offset:2048
	ds_read_b128 v[142:145], v8 offset:3072
	s_cmp_eq_u32 s19, 12
	s_cselect_b32 s37, s0, s17
	s_cselect_b32 s36, s1, s16
	s_cselect_b32 s17, s5, s18
	s_cselect_b32 s16, s7, s9
	v_lshl_add_u64 v[162:163], s[14:15], 0, v[180:181]
	s_add_i32 m0, s66, 0xc000
	ds_read_b128 v[184:187], v204
	ds_read_b128 v[188:191], v204 offset:1024
	ds_read_b128 v[192:195], v204 offset:2048
	ds_read_b128 v[206:209], v204 offset:3072
	ds_read_b128 v[214:217], v204 offset:4096
	ds_read_b128 v[218:221], v204 offset:5120
	ds_read_b128 v[222:225], v204 offset:6144
	ds_read_b128 v[226:229], v204 offset:7168
	global_load_lds_dwordx4 v[162:163], off
	s_add_i32 m0, s66, 0xe000
	v_lshl_add_u64 v[162:163], s[14:15], 0, v[182:183]
	global_load_lds_dwordx4 v[162:163], off
	s_waitcnt lgkmcnt(8)
	s_barrier
	s_waitcnt lgkmcnt(0)
	v_mfma_f32_16x16x32_bf16 v[126:129], v[130:133], v[184:187], 0
	v_mfma_f32_16x16x32_bf16 v[122:125], v[138:141], v[184:187], 0
	v_mfma_f32_16x16x32_bf16 v[114:117], v[130:133], v[192:195], 0
	v_mfma_f32_16x16x32_bf16 v[106:109], v[138:141], v[192:195], 0
	v_mfma_f32_16x16x32_bf16 v[102:105], v[130:133], v[214:217], 0
	v_mfma_f32_16x16x32_bf16 v[94:97], v[138:141], v[214:217], 0
	v_mfma_f32_16x16x32_bf16 v[82:85], v[130:133], v[222:225], 0
	v_mfma_f32_16x16x32_bf16 v[74:77], v[138:141], v[222:225], 0
	v_mfma_f32_16x16x32_bf16 v[126:129], v[134:137], v[188:191], v[126:129]
	v_mfma_f32_16x16x32_bf16 v[122:125], v[142:145], v[188:191], v[122:125]
	v_mfma_f32_16x16x32_bf16 v[114:117], v[134:137], v[206:209], v[114:117]
	v_mfma_f32_16x16x32_bf16 v[106:109], v[142:145], v[206:209], v[106:109]
	v_mfma_f32_16x16x32_bf16 v[102:105], v[134:137], v[218:221], v[102:105]
	v_mfma_f32_16x16x32_bf16 v[94:97], v[142:145], v[218:221], v[94:97]
	v_mfma_f32_16x16x32_bf16 v[82:85], v[134:137], v[226:229], v[82:85]
	v_mfma_f32_16x16x32_bf16 v[74:77], v[142:145], v[226:229], v[74:77]
	s_barrier
	s_add_i32 s38, 0, 0x14000
	s_add_i32 s26, s26, s47
	v_add_u32_e32 v8, s38, v199
	v_lshl_add_u64 v[162:163], s[16:17], 0, v[148:149]
	s_mov_b32 m0, s26
	ds_read_b128 v[230:233], v8
	ds_read_b128 v[234:237], v8 offset:1024
	ds_read_b128 v[238:241], v8 offset:2048
	ds_read_b128 v[242:245], v8 offset:3072
	global_load_lds_dwordx4 v[162:163], off
	s_add_i32 m0, s26, 0x2000
	v_lshl_add_u64 v[164:165], s[16:17], 0, v[152:153]
	global_load_lds_dwordx4 v[164:165], off
	s_barrier
	s_waitcnt lgkmcnt(0)
	v_mfma_f32_16x16x32_bf16 v[118:121], v[230:233], v[184:187], 0
	v_mfma_f32_16x16x32_bf16 v[110:113], v[238:241], v[184:187], 0
	v_mfma_f32_16x16x32_bf16 v[98:101], v[230:233], v[192:195], 0
	v_mfma_f32_16x16x32_bf16 v[90:93], v[238:241], v[192:195], 0
	v_mfma_f32_16x16x32_bf16 v[86:89], v[230:233], v[214:217], 0
	v_mfma_f32_16x16x32_bf16 v[78:81], v[238:241], v[214:217], 0
	v_mfma_f32_16x16x32_bf16 v[54:57], v[230:233], v[222:225], 0
	v_mfma_f32_16x16x32_bf16 v[34:37], v[238:241], v[222:225], 0
	v_mfma_f32_16x16x32_bf16 v[118:121], v[234:237], v[188:191], v[118:121]
	v_mfma_f32_16x16x32_bf16 v[110:113], v[242:245], v[188:191], v[110:113]
	v_mfma_f32_16x16x32_bf16 v[98:101], v[234:237], v[206:209], v[98:101]
	v_mfma_f32_16x16x32_bf16 v[90:93], v[242:245], v[206:209], v[90:93]
	v_mfma_f32_16x16x32_bf16 v[86:89], v[234:237], v[218:221], v[86:89]
	v_mfma_f32_16x16x32_bf16 v[78:81], v[242:245], v[218:221], v[78:81]
	v_mfma_f32_16x16x32_bf16 v[54:57], v[234:237], v[226:229], v[54:57]
	v_mfma_f32_16x16x32_bf16 v[34:37], v[242:245], v[226:229], v[34:37]
	s_mov_b32 m0, s66
	v_lshl_add_u64 v[202:203], s[36:37], 0, v[146:147]
	s_barrier
	ds_read_b128 v[184:187], v204 offset:16384
	ds_read_b128 v[188:191], v204 offset:17408
	ds_read_b128 v[192:195], v204 offset:18432
	ds_read_b128 v[206:209], v204 offset:19456
	ds_read_b128 v[214:217], v204 offset:20480
	ds_read_b128 v[218:221], v204 offset:21504
	ds_read_b128 v[222:225], v204 offset:22528
	ds_read_b128 v[226:229], v204 offset:23552
	global_load_lds_dwordx4 v[202:203], off
	s_mov_b32 m0, s68
	v_lshl_add_u64 v[246:247], s[36:37], 0, v[150:151]
	global_load_lds_dwordx4 v[246:247], off
	s_barrier
	s_waitcnt lgkmcnt(0)
	v_mfma_f32_16x16x32_bf16 v[58:61], v[130:133], v[184:187], 0
	v_mfma_f32_16x16x32_bf16 v[62:65], v[138:141], v[184:187], 0
	v_mfma_f32_16x16x32_bf16 v[38:41], v[130:133], v[192:195], 0
	v_mfma_f32_16x16x32_bf16 v[42:45], v[138:141], v[192:195], 0
	v_mfma_f32_16x16x32_bf16 v[18:21], v[130:133], v[214:217], 0
	v_mfma_f32_16x16x32_bf16 v[22:25], v[138:141], v[214:217], 0
	v_mfma_f32_16x16x32_bf16 v[0:3], v[130:133], v[222:225], 0
	v_mfma_f32_16x16x32_bf16 v[4:7], v[138:141], v[222:225], 0
	v_mfma_f32_16x16x32_bf16 v[58:61], v[134:137], v[188:191], v[58:61]
	v_mfma_f32_16x16x32_bf16 v[62:65], v[142:145], v[188:191], v[62:65]
	v_mfma_f32_16x16x32_bf16 v[38:41], v[134:137], v[206:209], v[38:41]
	v_mfma_f32_16x16x32_bf16 v[42:45], v[142:145], v[206:209], v[42:45]
	v_mfma_f32_16x16x32_bf16 v[18:21], v[134:137], v[218:221], v[18:21]
	v_mfma_f32_16x16x32_bf16 v[22:25], v[142:145], v[218:221], v[22:25]
	v_mfma_f32_16x16x32_bf16 v[0:3], v[134:137], v[226:229], v[0:3]
	v_mfma_f32_16x16x32_bf16 v[4:7], v[142:145], v[226:229], v[4:7]
	s_barrier
; #define PG8_STAGE(bufoff, gbase, voff) do { _Pragma("unroll") for (int _i = 0; _i < 2; ++_i) \
;         __builtin_amdgcn_global_load_lds((const unsigned*)((const char*)(gbase) + (voff)[_i]), (LAS unsigned*)(lds + (bufoff) + ldsw + _i * 8192), 16, 0, 0); } while (0)
; #define PG8_LDA(dst, b, h) do { _Pragma("unroll") for (int m = 0; m < 4; ++m) _Pragma("unroll") for (int k = 0; k < 2; ++k) dst[m][k] = *(const LAS bf16x8*)(lds + PG8_SA(b, h) + aoff + m * 2048 + k * 1024); } while (0)
; #define PG8_LDB(dst, b, h) do { _Pragma("unroll") for (int n = 0; n < 2; ++n) _Pragma("unroll") for (int k = 0; k < 2; ++k) dst[n][k] = *(const LAS bf16x8*)(lds + PG8_SB(b, h) + boff + n * 2048 + k * 1024); } while (0)
; #define PG8_MMA(ai, bj, At, Bt) do { __builtin_amdgcn_s_setprio(1); _Pragma("unroll") for (int m = 0; m < 4; ++m) _Pragma("unroll") for (int n = 0; n < 2; ++n) _Pragma("unroll") for (int k = 0; k < 2; ++k) \
;         acc[ai][bj][m][n] = __builtin_amdgcn_mfma_f32_16x16x32_bf16(Bt[n][k], At[m][k], acc[ai][bj][m][n], 0, 0, 0); __builtin_amdgcn_s_setprio(0); } while (0)
; #define PG8_WAIT_V(n) asm volatile("s_waitcnt vmcnt(" #n ")" ::: "memory")
; #define PG8_WAIT_L(n) asm volatile("s_waitcnt lgkmcnt(" #n ")" ::: "memory")
; #define PG8_BAR __builtin_amdgcn_s_barrier()
; #define PG8_SCHED __builtin_amdgcn_sched_barrier(0)
; template <class Epi>
; DEVI void gemm_phase(LAS unsigned char* lds, const Gemm g, const Epi& E) {
;     ...
;             PG8_STAGE(PG8_SB(0, 1), b2 + hstepB, voffB);
;             PG8_WAIT_V(6); PG8_BAR; PG8_MMA(1, 1, At, B1); PG8_BAR;
;             PG8_LDB(B0, 1, 0); PG8_SCHED; PG8_LDA(At, 1, 0); PG8_STAGE(PG8_SA(0, 1), a2 + hstepA, voffA);
;             PG8_WAIT_L(8); PG8_BAR; PG8_WAIT_L(0); PG8_MMA(0, 0, At, B0); PG8_BAR; PG8_SCHED;
;             PG8_LDB(B1, 1, 1); PG8_STAGE(PG8_SB(1, 0), b3, voffB);
	s_add_u32 s26, s16, 0x40000
	s_addc_u32 s27, s17, 0
	s_add_i32 s38, s38, s47
	s_mov_b32 m0, s38
	v_lshl_add_u64 v[130:131], s[26:27], 0, v[148:149]
	global_load_lds_dwordx4 v[130:131], off
	s_add_i32 m0, s38, 0x2000
	v_lshl_add_u64 v[130:131], s[26:27], 0, v[152:153]
	global_load_lds_dwordx4 v[130:131], off
	s_waitcnt vmcnt(6)
	s_barrier
	v_mfma_f32_16x16x32_bf16 v[66:69], v[230:233], v[184:187], 0
	v_mfma_f32_16x16x32_bf16 v[70:73], v[238:241], v[184:187], 0
	v_mfma_f32_16x16x32_bf16 v[46:49], v[230:233], v[192:195], 0
	v_mfma_f32_16x16x32_bf16 v[50:53], v[238:241], v[192:195], 0
	v_mfma_f32_16x16x32_bf16 v[26:29], v[230:233], v[214:217], 0
	v_mfma_f32_16x16x32_bf16 v[30:33], v[238:241], v[214:217], 0
	v_mfma_f32_16x16x32_bf16 v[10:13], v[230:233], v[222:225], 0
	v_mfma_f32_16x16x32_bf16 v[14:17], v[238:241], v[222:225], 0
	v_mfma_f32_16x16x32_bf16 v[66:69], v[234:237], v[188:191], v[66:69]
	v_mfma_f32_16x16x32_bf16 v[70:73], v[242:245], v[188:191], v[70:73]
	v_mfma_f32_16x16x32_bf16 v[46:49], v[234:237], v[206:209], v[46:49]
	v_mfma_f32_16x16x32_bf16 v[50:53], v[242:245], v[206:209], v[50:53]
	v_mfma_f32_16x16x32_bf16 v[26:29], v[234:237], v[218:221], v[26:29]
	v_mfma_f32_16x16x32_bf16 v[30:33], v[242:245], v[218:221], v[30:33]
	v_mfma_f32_16x16x32_bf16 v[10:13], v[234:237], v[226:229], v[10:13]
	v_mfma_f32_16x16x32_bf16 v[14:17], v[242:245], v[226:229], v[14:17]
	s_add_i32 s38, 0, 0x18000
	v_add_u32_e32 v8, s38, v199
	s_barrier
	ds_read_b128 v[130:133], v8
	ds_read_b128 v[134:137], v8 offset:1024
	ds_read_b128 v[138:141], v8 offset:2048
	ds_read_b128 v[142:145], v8 offset:3072
	s_add_u32 s26, s36, 0x40000
	s_addc_u32 s27, s37, 0
	s_mov_b32 m0, s69
	v_lshl_add_u64 v[230:231], s[26:27], 0, v[146:147]
	ds_read_b128 v[184:187], v204 offset:32768
	ds_read_b128 v[188:191], v204 offset:33792
	ds_read_b128 v[192:195], v204 offset:34816
	ds_read_b128 v[206:209], v204 offset:35840
	ds_read_b128 v[214:217], v204 offset:36864
	ds_read_b128 v[218:221], v204 offset:37888
	ds_read_b128 v[222:225], v204 offset:38912
	ds_read_b128 v[226:229], v204 offset:39936
	global_load_lds_dwordx4 v[230:231], off
	s_mov_b32 m0, s80
	v_lshl_add_u64 v[230:231], s[26:27], 0, v[150:151]
	global_load_lds_dwordx4 v[230:231], off
	s_waitcnt lgkmcnt(8)
	s_barrier
	s_waitcnt lgkmcnt(0)
	v_mfma_f32_16x16x32_bf16 v[126:129], v[130:133], v[184:187], v[126:129]
	v_mfma_f32_16x16x32_bf16 v[122:125], v[138:141], v[184:187], v[122:125]
	v_mfma_f32_16x16x32_bf16 v[114:117], v[130:133], v[192:195], v[114:117]
	v_mfma_f32_16x16x32_bf16 v[106:109], v[138:141], v[192:195], v[106:109]
	v_mfma_f32_16x16x32_bf16 v[102:105], v[130:133], v[214:217], v[102:105]
	v_mfma_f32_16x16x32_bf16 v[94:97], v[138:141], v[214:217], v[94:97]
	v_mfma_f32_16x16x32_bf16 v[82:85], v[130:133], v[222:225], v[82:85]
	v_mfma_f32_16x16x32_bf16 v[74:77], v[138:141], v[222:225], v[74:77]
	v_mfma_f32_16x16x32_bf16 v[126:129], v[134:137], v[188:191], v[126:129]
	v_mfma_f32_16x16x32_bf16 v[122:125], v[142:145], v[188:191], v[122:125]
	v_mfma_f32_16x16x32_bf16 v[114:117], v[134:137], v[206:209], v[114:117]
	v_mfma_f32_16x16x32_bf16 v[106:109], v[142:145], v[206:209], v[106:109]
	v_mfma_f32_16x16x32_bf16 v[102:105], v[134:137], v[218:221], v[102:105]
	v_mfma_f32_16x16x32_bf16 v[94:97], v[142:145], v[218:221], v[94:97]
	v_mfma_f32_16x16x32_bf16 v[82:85], v[134:137], v[226:229], v[82:85]
	v_mfma_f32_16x16x32_bf16 v[74:77], v[142:145], v[226:229], v[74:77]
	s_barrier
	s_add_i32 s26, 0, 0x1c000
	s_add_i32 s27, s38, s47
	v_add_u32_e32 v8, s26, v199
	v_lshl_add_u64 v[162:163], v[162:163], 0, s[70:71]
	s_mov_b32 m0, s27
	ds_read_b128 v[230:233], v8
	ds_read_b128 v[234:237], v8 offset:1024
	ds_read_b128 v[238:241], v8 offset:2048
	ds_read_b128 v[242:245], v8 offset:3072
	global_load_lds_dwordx4 v[162:163], off
	s_add_i32 m0, s27, 0x2000
	v_lshl_add_u64 v[162:163], v[164:165], 0, s[70:71]
	global_load_lds_dwordx4 v[162:163], off
	s_barrier
; #define PG8_STAGE(bufoff, gbase, voff) do { _Pragma("unroll") for (int _i = 0; _i < 2; ++_i) \
;         __builtin_amdgcn_global_load_lds((const unsigned*)((const char*)(gbase) + (voff)[_i]), (LAS unsigned*)(lds + (bufoff) + ldsw + _i * 8192), 16, 0, 0); } while (0)
; #define PG8_LDA(dst, b, h) do { _Pragma("unroll") for (int m = 0; m < 4; ++m) _Pragma("unroll") for (int k = 0; k < 2; ++k) dst[m][k] = *(const LAS bf16x8*)(lds + PG8_SA(b, h) + aoff + m * 2048 + k * 1024); } while (0)
; #define PG8_MMA(ai, bj, At, Bt) do { __builtin_amdgcn_s_setprio(1); _Pragma("unroll") for (int m = 0; m < 4; ++m) _Pragma("unroll") for (int n = 0; n < 2; ++n) _Pragma("unroll") for (int k = 0; k < 2; ++k) \
;         acc[ai][bj][m][n] = __builtin_amdgcn_mfma_f32_16x16x32_bf16(Bt[n][k], At[m][k], acc[ai][bj][m][n], 0, 0, 0); __builtin_amdgcn_s_setprio(0); } while (0)
; #define PG8_WAIT_V(n) asm volatile("s_waitcnt vmcnt(" #n ")" ::: "memory")
; #define PG8_WAIT_L(n) asm volatile("s_waitcnt lgkmcnt(" #n ")" ::: "memory")
; #define PG8_BAR __builtin_amdgcn_s_barrier()
; #define PG8_SCHED __builtin_amdgcn_sched_barrier(0)
; template <class Epi>
; DEVI void gemm_phase(LAS unsigned char* lds, const Gemm g, const Epi& E) {
;     ...
;             PG8_BAR; PG8_WAIT_L(0); PG8_MMA(0, 1, At, B1); PG8_BAR;
;             PG8_LDA(At, 1, 1); PG8_STAGE(PG8_SA(1, 0), a3, voffA);
;             PG8_BAR; PG8_WAIT_L(0); PG8_MMA(1, 0, At, B0); PG8_BAR; PG8_SCHED;
;             PG8_STAGE(PG8_SB(1, 1), b3 + hstepB, voffB);
;             PG8_WAIT_V(6); PG8_BAR; PG8_MMA(1, 1, At, B1); PG8_BAR;
;         }
	s_waitcnt lgkmcnt(0)
	v_mfma_f32_16x16x32_bf16 v[118:121], v[230:233], v[184:187], v[118:121]
	v_mfma_f32_16x16x32_bf16 v[110:113], v[238:241], v[184:187], v[110:113]
	v_mfma_f32_16x16x32_bf16 v[98:101], v[230:233], v[192:195], v[98:101]
	v_mfma_f32_16x16x32_bf16 v[90:93], v[238:241], v[192:195], v[90:93]
	v_mfma_f32_16x16x32_bf16 v[86:89], v[230:233], v[214:217], v[86:89]
	v_mfma_f32_16x16x32_bf16 v[78:81], v[238:241], v[214:217], v[78:81]
	v_mfma_f32_16x16x32_bf16 v[54:57], v[230:233], v[222:225], v[54:57]
	v_mfma_f32_16x16x32_bf16 v[34:37], v[238:241], v[222:225], v[34:37]
	v_mfma_f32_16x16x32_bf16 v[118:121], v[234:237], v[188:191], v[118:121]
	v_mfma_f32_16x16x32_bf16 v[110:113], v[242:245], v[188:191], v[110:113]
	v_mfma_f32_16x16x32_bf16 v[98:101], v[234:237], v[206:209], v[98:101]
	v_mfma_f32_16x16x32_bf16 v[90:93], v[242:245], v[206:209], v[90:93]
	v_mfma_f32_16x16x32_bf16 v[86:89], v[234:237], v[218:221], v[86:89]
	v_mfma_f32_16x16x32_bf16 v[78:81], v[242:245], v[218:221], v[78:81]
	v_mfma_f32_16x16x32_bf16 v[54:57], v[234:237], v[226:229], v[54:57]
	v_mfma_f32_16x16x32_bf16 v[34:37], v[242:245], v[226:229], v[34:37]
	s_mov_b32 m0, s81
	v_lshl_add_u64 v[162:163], v[202:203], 0, s[70:71]
	s_barrier
	ds_read_b128 v[184:187], v204 offset:49152
	ds_read_b128 v[188:191], v204 offset:50176
	ds_read_b128 v[192:195], v204 offset:51200
	ds_read_b128 v[206:209], v204 offset:52224
	ds_read_b128 v[214:217], v204 offset:53248
	ds_read_b128 v[218:221], v204 offset:54272
	ds_read_b128 v[222:225], v204 offset:55296
	ds_read_b128 v[226:229], v204 offset:56320
	global_load_lds_dwordx4 v[162:163], off
	s_mov_b32 m0, s82
	v_lshl_add_u64 v[162:163], v[246:247], 0, s[70:71]
	global_load_lds_dwordx4 v[162:163], off
	s_barrier
	s_waitcnt lgkmcnt(0)
	v_mfma_f32_16x16x32_bf16 v[58:61], v[130:133], v[184:187], v[58:61]
	v_mfma_f32_16x16x32_bf16 v[62:65], v[138:141], v[184:187], v[62:65]
	v_mfma_f32_16x16x32_bf16 v[38:41], v[130:133], v[192:195], v[38:41]
	v_mfma_f32_16x16x32_bf16 v[42:45], v[138:141], v[192:195], v[42:45]
	v_mfma_f32_16x16x32_bf16 v[18:21], v[130:133], v[214:217], v[18:21]
	v_mfma_f32_16x16x32_bf16 v[22:25], v[138:141], v[214:217], v[22:25]
	v_mfma_f32_16x16x32_bf16 v[0:3], v[130:133], v[222:225], v[0:3]
	v_mfma_f32_16x16x32_bf16 v[4:7], v[138:141], v[222:225], v[4:7]
	v_mfma_f32_16x16x32_bf16 v[58:61], v[134:137], v[188:191], v[58:61]
	v_mfma_f32_16x16x32_bf16 v[62:65], v[142:145], v[188:191], v[62:65]
	v_mfma_f32_16x16x32_bf16 v[38:41], v[134:137], v[206:209], v[38:41]
	v_mfma_f32_16x16x32_bf16 v[42:45], v[142:145], v[206:209], v[42:45]
	v_mfma_f32_16x16x32_bf16 v[18:21], v[134:137], v[218:221], v[18:21]
	v_mfma_f32_16x16x32_bf16 v[22:25], v[142:145], v[218:221], v[22:25]
	v_mfma_f32_16x16x32_bf16 v[0:3], v[134:137], v[226:229], v[0:3]
	v_mfma_f32_16x16x32_bf16 v[4:7], v[142:145], v[226:229], v[4:7]
	s_barrier
	s_add_u32 s16, s16, 0x40080
	s_addc_u32 s17, s17, 0
	s_add_i32 s26, s26, s47
	s_mov_b32 m0, s26
	v_lshl_add_u64 v[130:131], s[16:17], 0, v[148:149]
	global_load_lds_dwordx4 v[130:131], off
	s_add_i32 m0, s26, 0x2000
	v_lshl_add_u64 v[130:131], s[16:17], 0, v[152:153]
	global_load_lds_dwordx4 v[130:131], off
	s_waitcnt vmcnt(6)
	s_barrier
	v_mfma_f32_16x16x32_bf16 v[66:69], v[230:233], v[184:187], v[66:69]
	v_mfma_f32_16x16x32_bf16 v[70:73], v[238:241], v[184:187], v[70:73]
	v_mfma_f32_16x16x32_bf16 v[46:49], v[230:233], v[192:195], v[46:49]
	v_mfma_f32_16x16x32_bf16 v[50:53], v[238:241], v[192:195], v[50:53]
	v_mfma_f32_16x16x32_bf16 v[26:29], v[230:233], v[214:217], v[26:29]
	v_mfma_f32_16x16x32_bf16 v[30:33], v[238:241], v[214:217], v[30:33]
	v_mfma_f32_16x16x32_bf16 v[10:13], v[230:233], v[222:225], v[10:13]
	v_mfma_f32_16x16x32_bf16 v[14:17], v[238:241], v[222:225], v[14:17]
	v_mfma_f32_16x16x32_bf16 v[66:69], v[234:237], v[188:191], v[66:69]
	v_mfma_f32_16x16x32_bf16 v[70:73], v[242:245], v[188:191], v[70:73]
	v_mfma_f32_16x16x32_bf16 v[46:49], v[234:237], v[206:209], v[46:49]
	v_mfma_f32_16x16x32_bf16 v[50:53], v[242:245], v[206:209], v[50:53]
	v_mfma_f32_16x16x32_bf16 v[26:29], v[234:237], v[218:221], v[26:29]
	v_mfma_f32_16x16x32_bf16 v[30:33], v[242:245], v[218:221], v[30:33]
	v_mfma_f32_16x16x32_bf16 v[10:13], v[234:237], v[226:229], v[10:13]
	v_mfma_f32_16x16x32_bf16 v[14:17], v[242:245], v[226:229], v[14:17]
	s_add_i32 s19, s19, 2
	s_add_u32 s14, s14, 0x100
	s_addc_u32 s15, s15, 0
	s_add_u32 s9, s9, 0x100
	s_addc_u32 s18, s18, 0
	s_cmp_gt_u32 s19, 13
	s_barrier

; DEVI size_t gemm_offB(const Gemm& g, const Unit& u) { return (g.split ? (size_t)(u.b >> 2) * g.sB + (size_t)(u.b & 3) * g.sB_lo : (size_t)u.b * g.sB) + (size_t)(u.pm >> g.pmsh) * g.sBpm; }
; #define PG8_STAGE(bufoff, gbase, voff) do { _Pragma("unroll") for (int _i = 0; _i < 2; ++_i) \
;         __builtin_amdgcn_global_load_lds((const unsigned*)((const char*)(gbase) + (voff)[_i]), (LAS unsigned*)(lds + (bufoff) + ldsw + _i * 8192), 16, 0, 0); } while (0)
; #define PG8_LDA(dst, b, h) do { _Pragma("unroll") for (int m = 0; m < 4; ++m) _Pragma("unroll") for (int k = 0; k < 2; ++k) dst[m][k] = *(const LAS bf16x8*)(lds + PG8_SA(b, h) + aoff + m * 2048 + k * 1024); } while (0)
; #define PG8_LDB(dst, b, h) do { _Pragma("unroll") for (int n = 0; n < 2; ++n) _Pragma("unroll") for (int k = 0; k < 2; ++k) dst[n][k] = *(const LAS bf16x8*)(lds + PG8_SB(b, h) + boff + n * 2048 + k * 1024); } while (0)
; #define PG8_WAIT_V(n) asm volatile("s_waitcnt vmcnt(" #n ")" ::: "memory")
; #define PG8_BAR __builtin_amdgcn_s_barrier()
; template <class Epi>
; DEVI void gemm_phase(LAS unsigned char* lds, const Gemm g, const Epi& E) {
;     ...
;         const bool has_next = unit_next(g, ui + 1, nxt);
;         const char* nA = has_next ? (const char*)g.A + gemm_offA(g, nxt) * 2 + (size_t)nxt.pm * tstepA : cA;
;         const char* nB = has_next ? (const char*)g.Bt + gemm_offB(g, nxt) * 2 + (size_t)nxt.pn * tstepB : cB;
;         for (int t = 0; t < nt; t += 2) {
;             const bool last = (t == nt - 2);
;             const char* a1 = cA + (size_t)(t + 1) * kstep;
;             const char* a2 = last ? nA : cA + (size_t)(t + 2) * kstep; const char* b2 = last ? nB : cB + (size_t)(t + 2) * kstep;
;             const char* a3 = a2 + kstep; const char* b3 = b2 + kstep;
;             PG8_LDB(B0, 0, 0); PG8_SCHED; PG8_LDA(At, 0, 0); PG8_STAGE(PG8_SA(1, 1), a1 + hstepA, voffA);
;             PG8_WAIT_L(8); PG8_BAR; PG8_WAIT_L(0); PG8_MMA(0, 0, At, B0); PG8_BAR; PG8_SCHED;
;             PG8_LDB(B1, 0, 1); PG8_STAGE(PG8_SB(0, 0), b2, voffB);
;             PG8_BAR; PG8_WAIT_L(0); PG8_MMA(0, 1, At, B1); PG8_BAR;
;             PG8_LDA(At, 0, 1); PG8_STAGE(PG8_SA(0, 0), a2, voffA);
;             PG8_BAR; PG8_WAIT_L(0); PG8_MMA(1, 0, At, B0); PG8_BAR; PG8_SCHED;
;             PG8_STAGE(PG8_SB(0, 1), b2 + hstepB, voffB);
;             PG8_WAIT_V(6); PG8_BAR; PG8_MMA(1, 1, At, B1); PG8_BAR;
.LBB0_1126:
	v_cmp_lt_i64_e32 vcc, s[10:11], v[170:171]
	s_lshl_b64 s[10:11], s[6:7], 18
	v_readlane_b32 s16, v253, 48
	v_readlane_b32 s17, v253, 49
	s_add_u32 s5, s16, s10
	s_addc_u32 s7, s17, s11
	s_and_b64 s[10:11], vcc, exec
	s_cselect_b32 s11, s7, s15
	s_cselect_b32 s10, s5, s14
	s_add_u32 s5, s14, 0x100
	s_addc_u32 s7, s15, 0
	s_mov_b32 s47, -2
	s_nop 0
	s_add_u32 s14, s12, 0x100
	s_addc_u32 s15, s13, 0
	s_add_i32 s48, 0, 0x10000
	v_add_u32_e32 v81, s48, v79
	ds_read_b128 v[82:85], v81
	ds_read_b128 v[86:89], v81 offset:1024
	ds_read_b128 v[90:93], v81 offset:2048
	ds_read_b128 v[94:97], v81 offset:3072
	s_cmp_eq_u32 s47, 4
	s_cselect_b32 s37, s9, s15
	s_cselect_b32 s36, s8, s14
	s_cselect_b32 s17, s11, s7
	s_cselect_b32 s16, s10, s5
	v_lshl_add_u64 v[130:131], s[12:13], 0, v[74:75]
	s_add_i32 m0, s18, 0xc000
	ds_read_b128 v[98:101], v80
	ds_read_b128 v[102:105], v80 offset:1024
	ds_read_b128 v[106:109], v80 offset:2048
	ds_read_b128 v[110:113], v80 offset:3072
	ds_read_b128 v[114:117], v80 offset:4096
	ds_read_b128 v[118:121], v80 offset:5120
	ds_read_b128 v[122:125], v80 offset:6144
	ds_read_b128 v[126:129], v80 offset:7168
	global_load_lds_dwordx4 v[130:131], off
	s_add_i32 m0, s18, 0xe000
	v_lshl_add_u64 v[130:131], s[12:13], 0, v[76:77]
	global_load_lds_dwordx4 v[130:131], off
	s_waitcnt lgkmcnt(8)
	s_barrier
	s_waitcnt lgkmcnt(0)
	v_mfma_f32_16x16x32_bf16 v[62:65], v[82:85], v[98:101], 0
	v_mfma_f32_16x16x32_bf16 v[58:61], v[90:93], v[98:101], 0
	v_mfma_f32_16x16x32_bf16 v[54:57], v[82:85], v[106:109], 0
	v_mfma_f32_16x16x32_bf16 v[50:53], v[90:93], v[106:109], 0
	v_mfma_f32_16x16x32_bf16 v[46:49], v[82:85], v[114:117], 0
	v_mfma_f32_16x16x32_bf16 v[42:45], v[90:93], v[114:117], 0
	v_mfma_f32_16x16x32_bf16 v[38:41], v[82:85], v[122:125], 0
	v_mfma_f32_16x16x32_bf16 v[34:37], v[90:93], v[122:125], 0
	v_mfma_f32_16x16x32_bf16 v[62:65], v[86:89], v[102:105], v[62:65]
	v_mfma_f32_16x16x32_bf16 v[58:61], v[94:97], v[102:105], v[58:61]
	v_mfma_f32_16x16x32_bf16 v[54:57], v[86:89], v[110:113], v[54:57]
	v_mfma_f32_16x16x32_bf16 v[50:53], v[94:97], v[110:113], v[50:53]
	v_mfma_f32_16x16x32_bf16 v[46:49], v[86:89], v[118:121], v[46:49]
	v_mfma_f32_16x16x32_bf16 v[42:45], v[94:97], v[118:121], v[42:45]
	v_mfma_f32_16x16x32_bf16 v[38:41], v[86:89], v[126:129], v[38:41]
	v_mfma_f32_16x16x32_bf16 v[34:37], v[94:97], v[126:129], v[34:37]
	s_barrier
	s_add_i32 s12, s48, s1
	v_lshl_add_u64 v[130:131], s[16:17], 0, v[70:71]
	s_mov_b32 m0, s12
	v_lshl_add_u64 v[132:133], s[16:17], 0, v[66:67]
	global_load_lds_dwordx4 v[130:131], off
	s_add_i32 m0, s12, 0x2000
	s_nop 0
	global_load_lds_dwordx4 v[132:133], off
	s_barrier
	s_waitcnt lgkmcnt(0)
	s_mov_b32 m0, s18
	v_lshl_add_u64 v[134:135], s[36:37], 0, v[72:73]
	s_barrier
	ds_read_b128 v[98:101], v80 offset:16384
	ds_read_b128 v[102:105], v80 offset:17408
	ds_read_b128 v[106:109], v80 offset:18432
	ds_read_b128 v[110:113], v80 offset:19456
	ds_read_b128 v[114:117], v80 offset:20480
	ds_read_b128 v[118:121], v80 offset:21504
	ds_read_b128 v[122:125], v80 offset:22528
	ds_read_b128 v[126:129], v80 offset:23552
	global_load_lds_dwordx4 v[134:135], off
	s_mov_b32 m0, s19
	v_lshl_add_u64 v[136:137], s[36:37], 0, v[68:69]
	global_load_lds_dwordx4 v[136:137], off
	s_barrier
	s_waitcnt lgkmcnt(0)
	v_mfma_f32_16x16x32_bf16 v[30:33], v[82:85], v[98:101], 0
	v_mfma_f32_16x16x32_bf16 v[26:29], v[90:93], v[98:101], 0
	v_mfma_f32_16x16x32_bf16 v[22:25], v[82:85], v[106:109], 0
	v_mfma_f32_16x16x32_bf16 v[18:21], v[90:93], v[106:109], 0
	v_mfma_f32_16x16x32_bf16 v[14:17], v[82:85], v[114:117], 0
	v_mfma_f32_16x16x32_bf16 v[10:13], v[90:93], v[114:117], 0
	v_mfma_f32_16x16x32_bf16 v[4:7], v[82:85], v[122:125], 0
	v_mfma_f32_16x16x32_bf16 v[0:3], v[90:93], v[122:125], 0
	v_mfma_f32_16x16x32_bf16 v[30:33], v[86:89], v[102:105], v[30:33]
	v_mfma_f32_16x16x32_bf16 v[26:29], v[94:97], v[102:105], v[26:29]
	v_mfma_f32_16x16x32_bf16 v[22:25], v[86:89], v[110:113], v[22:25]
	v_mfma_f32_16x16x32_bf16 v[18:21], v[94:97], v[110:113], v[18:21]
	v_mfma_f32_16x16x32_bf16 v[14:17], v[86:89], v[118:121], v[14:17]
	v_mfma_f32_16x16x32_bf16 v[10:13], v[94:97], v[118:121], v[10:13]
	v_mfma_f32_16x16x32_bf16 v[4:7], v[86:89], v[126:129], v[4:7]
	v_mfma_f32_16x16x32_bf16 v[0:3], v[94:97], v[126:129], v[0:3]
	s_barrier
	s_add_u32 s12, s16, 0x20000
	s_addc_u32 s13, s17, 0
	s_mov_b32 m0, s26
	v_lshl_add_u64 v[82:83], s[12:13], 0, v[70:71]
	global_load_lds_dwordx4 v[82:83], off
	s_mov_b32 m0, s27
	v_lshl_add_u64 v[82:83], s[12:13], 0, v[66:67]
	global_load_lds_dwordx4 v[82:83], off
	s_waitcnt vmcnt(6)
	s_barrier
; #define PG8_STAGE(bufoff, gbase, voff) do { _Pragma("unroll") for (int _i = 0; _i < 2; ++_i) \
;         __builtin_amdgcn_global_load_lds((const unsigned*)((const char*)(gbase) + (voff)[_i]), (LAS unsigned*)(lds + (bufoff) + ldsw + _i * 8192), 16, 0, 0); } while (0)
; #define PG8_LDA(dst, b, h) do { _Pragma("unroll") for (int m = 0; m < 4; ++m) _Pragma("unroll") for (int k = 0; k < 2; ++k) dst[m][k] = *(const LAS bf16x8*)(lds + PG8_SA(b, h) + aoff + m * 2048 + k * 1024); } while (0)
; #define PG8_LDB(dst, b, h) do { _Pragma("unroll") for (int n = 0; n < 2; ++n) _Pragma("unroll") for (int k = 0; k < 2; ++k) dst[n][k] = *(const LAS bf16x8*)(lds + PG8_SB(b, h) + boff + n * 2048 + k * 1024); } while (0)
; #define PG8_MMA(ai, bj, At, Bt) do { __builtin_amdgcn_s_setprio(1); _Pragma("unroll") for (int m = 0; m < 4; ++m) _Pragma("unroll") for (int n = 0; n < 2; ++n) _Pragma("unroll") for (int k = 0; k < 2; ++k) \
;         acc[ai][bj][m][n] = __builtin_amdgcn_mfma_f32_16x16x32_bf16(Bt[n][k], At[m][k], acc[ai][bj][m][n], 0, 0, 0); __builtin_amdgcn_s_setprio(0); } while (0)
; #define PG8_WAIT_V(n) asm volatile("s_waitcnt vmcnt(" #n ")" ::: "memory")
; #define PG8_WAIT_L(n) asm volatile("s_waitcnt lgkmcnt(" #n ")" ::: "memory")
; #define PG8_BAR __builtin_amdgcn_s_barrier()
; #define PG8_SCHED __builtin_amdgcn_sched_barrier(0)
; template <class Epi>
; DEVI void gemm_phase(LAS unsigned char* lds, const Gemm g, const Epi& E) {
;     ...
;             PG8_LDB(B0, 1, 0); PG8_SCHED; PG8_LDA(At, 1, 0); PG8_STAGE(PG8_SA(0, 1), a2 + hstepA, voffA);
;             PG8_WAIT_L(8); PG8_BAR; PG8_WAIT_L(0); PG8_MMA(0, 0, At, B0); PG8_BAR; PG8_SCHED;
;             PG8_LDB(B1, 1, 1); PG8_STAGE(PG8_SB(1, 0), b3, voffB);
;             PG8_BAR; PG8_WAIT_L(0); PG8_MMA(0, 1, At, B1); PG8_BAR;
;             PG8_LDA(At, 1, 1); PG8_STAGE(PG8_SA(1, 0), a3, voffA);
;             PG8_BAR; PG8_WAIT_L(0); PG8_MMA(1, 0, At, B0); PG8_BAR; PG8_SCHED;
;             PG8_STAGE(PG8_SB(1, 1), b3 + hstepB, voffB);
;             PG8_WAIT_V(6); PG8_BAR; PG8_MMA(1, 1, At, B1); PG8_BAR;
;         }
	s_add_i32 s48, 0, 0x18000
	v_add_u32_e32 v81, s48, v79
	s_barrier
	ds_read_b128 v[82:85], v81
	ds_read_b128 v[86:89], v81 offset:1024
	ds_read_b128 v[90:93], v81 offset:2048
	ds_read_b128 v[94:97], v81 offset:3072
	s_add_u32 s12, s36, 0x28000
	s_addc_u32 s13, s37, 0
	s_mov_b32 m0, s38
	v_lshl_add_u64 v[138:139], s[12:13], 0, v[72:73]
	ds_read_b128 v[98:101], v80 offset:32768
	ds_read_b128 v[102:105], v80 offset:33792
	ds_read_b128 v[106:109], v80 offset:34816
	ds_read_b128 v[110:113], v80 offset:35840
	ds_read_b128 v[114:117], v80 offset:36864
	ds_read_b128 v[118:121], v80 offset:37888
	ds_read_b128 v[122:125], v80 offset:38912
	ds_read_b128 v[126:129], v80 offset:39936
	global_load_lds_dwordx4 v[138:139], off
	s_mov_b32 m0, s39
	v_lshl_add_u64 v[138:139], s[12:13], 0, v[68:69]
	global_load_lds_dwordx4 v[138:139], off
	s_waitcnt lgkmcnt(8)
	s_barrier
	s_waitcnt lgkmcnt(0)
	v_mfma_f32_16x16x32_bf16 v[62:65], v[82:85], v[98:101], v[62:65]
	v_mfma_f32_16x16x32_bf16 v[58:61], v[90:93], v[98:101], v[58:61]
	v_mfma_f32_16x16x32_bf16 v[54:57], v[82:85], v[106:109], v[54:57]
	v_mfma_f32_16x16x32_bf16 v[50:53], v[90:93], v[106:109], v[50:53]
	v_mfma_f32_16x16x32_bf16 v[46:49], v[82:85], v[114:117], v[46:49]
	v_mfma_f32_16x16x32_bf16 v[42:45], v[90:93], v[114:117], v[42:45]
	v_mfma_f32_16x16x32_bf16 v[38:41], v[82:85], v[122:125], v[38:41]
	v_mfma_f32_16x16x32_bf16 v[34:37], v[90:93], v[122:125], v[34:37]
	v_mfma_f32_16x16x32_bf16 v[62:65], v[86:89], v[102:105], v[62:65]
	v_mfma_f32_16x16x32_bf16 v[58:61], v[94:97], v[102:105], v[58:61]
	v_mfma_f32_16x16x32_bf16 v[54:57], v[86:89], v[110:113], v[54:57]
	v_mfma_f32_16x16x32_bf16 v[50:53], v[94:97], v[110:113], v[50:53]
	v_mfma_f32_16x16x32_bf16 v[46:49], v[86:89], v[118:121], v[46:49]
	v_mfma_f32_16x16x32_bf16 v[42:45], v[94:97], v[118:121], v[42:45]
	v_mfma_f32_16x16x32_bf16 v[38:41], v[86:89], v[126:129], v[38:41]
	v_mfma_f32_16x16x32_bf16 v[34:37], v[94:97], v[126:129], v[34:37]
	s_barrier
	s_add_i32 s12, s48, s1
	s_mov_b32 m0, s12
	v_lshl_add_u64 v[98:99], v[130:131], 0, s[70:71]
	global_load_lds_dwordx4 v[98:99], off
	s_add_i32 m0, s12, 0x2000
	v_lshl_add_u64 v[98:99], v[132:133], 0, s[70:71]
	global_load_lds_dwordx4 v[98:99], off
	s_barrier
	s_waitcnt lgkmcnt(0)
	s_mov_b32 m0, s41
	v_lshl_add_u64 v[130:131], v[134:135], 0, s[70:71]
	s_barrier
	ds_read_b128 v[98:101], v80 offset:49152
	ds_read_b128 v[102:105], v80 offset:50176
	ds_read_b128 v[106:109], v80 offset:51200
	ds_read_b128 v[110:113], v80 offset:52224
	ds_read_b128 v[114:117], v80 offset:53248
	ds_read_b128 v[118:121], v80 offset:54272
	ds_read_b128 v[122:125], v80 offset:55296
	ds_read_b128 v[126:129], v80 offset:56320
	global_load_lds_dwordx4 v[130:131], off
	s_mov_b32 m0, s42
	v_lshl_add_u64 v[130:131], v[136:137], 0, s[70:71]
	global_load_lds_dwordx4 v[130:131], off
	s_barrier
	s_waitcnt lgkmcnt(0)
	v_mfma_f32_16x16x32_bf16 v[30:33], v[82:85], v[98:101], v[30:33]
	v_mfma_f32_16x16x32_bf16 v[26:29], v[90:93], v[98:101], v[26:29]
	v_mfma_f32_16x16x32_bf16 v[22:25], v[82:85], v[106:109], v[22:25]
	v_mfma_f32_16x16x32_bf16 v[18:21], v[90:93], v[106:109], v[18:21]
	v_mfma_f32_16x16x32_bf16 v[14:17], v[82:85], v[114:117], v[14:17]
	v_mfma_f32_16x16x32_bf16 v[10:13], v[90:93], v[114:117], v[10:13]
	v_mfma_f32_16x16x32_bf16 v[4:7], v[82:85], v[122:125], v[4:7]
	v_mfma_f32_16x16x32_bf16 v[0:3], v[90:93], v[122:125], v[0:3]
	v_mfma_f32_16x16x32_bf16 v[30:33], v[86:89], v[102:105], v[30:33]
	v_mfma_f32_16x16x32_bf16 v[26:29], v[94:97], v[102:105], v[26:29]
	v_mfma_f32_16x16x32_bf16 v[22:25], v[86:89], v[110:113], v[22:25]
	v_mfma_f32_16x16x32_bf16 v[18:21], v[94:97], v[110:113], v[18:21]
	v_mfma_f32_16x16x32_bf16 v[14:17], v[86:89], v[118:121], v[14:17]
	v_mfma_f32_16x16x32_bf16 v[10:13], v[94:97], v[118:121], v[10:13]
	v_mfma_f32_16x16x32_bf16 v[4:7], v[86:89], v[126:129], v[4:7]
	v_mfma_f32_16x16x32_bf16 v[0:3], v[94:97], v[126:129], v[0:3]
	s_barrier
	s_add_u32 s12, s16, 0x20080
	s_addc_u32 s13, s17, 0
	s_mov_b32 m0, s43
	v_lshl_add_u64 v[82:83], s[12:13], 0, v[70:71]
	global_load_lds_dwordx4 v[82:83], off
	s_mov_b32 m0, s44
	v_lshl_add_u64 v[82:83], s[12:13], 0, v[66:67]
	global_load_lds_dwordx4 v[82:83], off
	s_waitcnt vmcnt(6)
	s_barrier
	s_add_i32 s47, s47, 2
	s_add_u32 s5, s5, 0x100
	s_addc_u32 s7, s7, 0
	s_cmp_gt_u32 s47, 5
	s_mov_b64 s[12:13], s[14:15]
	s_barrier

; #define PG8_STAGE(bufoff, gbase, voff) do { _Pragma("unroll") for (int _i = 0; _i < 2; ++_i) \
;         __builtin_amdgcn_global_load_lds((const unsigned*)((const char*)(gbase) + (voff)[_i]), (LAS unsigned*)(lds + (bufoff) + ldsw + _i * 8192), 16, 0, 0); } while (0)
; #define PG8_LDA(dst, b, h) do { _Pragma("unroll") for (int m = 0; m < 4; ++m) _Pragma("unroll") for (int k = 0; k < 2; ++k) dst[m][k] = *(const LAS bf16x8*)(lds + PG8_SA(b, h) + aoff + m * 2048 + k * 1024); } while (0)
; #define PG8_LDB(dst, b, h) do { _Pragma("unroll") for (int n = 0; n < 2; ++n) _Pragma("unroll") for (int k = 0; k < 2; ++k) dst[n][k] = *(const LAS bf16x8*)(lds + PG8_SB(b, h) + boff + n * 2048 + k * 1024); } while (0)
; #define PG8_MMA(ai, bj, At, Bt) do { __builtin_amdgcn_s_setprio(1); _Pragma("unroll") for (int m = 0; m < 4; ++m) _Pragma("unroll") for (int n = 0; n < 2; ++n) _Pragma("unroll") for (int k = 0; k < 2; ++k) \
;         acc[ai][bj][m][n] = __builtin_amdgcn_mfma_f32_16x16x32_bf16(Bt[n][k], At[m][k], acc[ai][bj][m][n], 0, 0, 0); __builtin_amdgcn_s_setprio(0); } while (0)
; #define PG8_WAIT_L(n) asm volatile("s_waitcnt lgkmcnt(" #n ")" ::: "memory")
; #define PG8_BAR __builtin_amdgcn_s_barrier()
; #define PG8_SCHED __builtin_amdgcn_sched_barrier(0)
; template <class Epi>
; DEVI void gemm_phase(LAS unsigned char* lds, const Gemm g, const Epi& E) {
;     ...
;             const char* a1 = cA + (size_t)(t + 1) * kstep;
;             const char* a2 = last ? nA : cA + (size_t)(t + 2) * kstep; const char* b2 = last ? nB : cB + (size_t)(t + 2) * kstep;
;             const char* a3 = a2 + kstep; const char* b3 = b2 + kstep;
;             PG8_LDB(B0, 0, 0); PG8_SCHED; PG8_LDA(At, 0, 0); PG8_STAGE(PG8_SA(1, 1), a1 + hstepA, voffA);
;             PG8_WAIT_L(8); PG8_BAR; PG8_WAIT_L(0); PG8_MMA(0, 0, At, B0); PG8_BAR; PG8_SCHED;
;             PG8_LDB(B1, 0, 1); PG8_STAGE(PG8_SB(0, 0), b2, voffB);
;             PG8_BAR; PG8_WAIT_L(0); PG8_MMA(0, 1, At, B1); PG8_BAR;
;             PG8_LDA(At, 0, 1); PG8_STAGE(PG8_SA(0, 0), a2, voffA);
;             PG8_BAR; PG8_WAIT_L(0); PG8_MMA(1, 0, At, B0); PG8_BAR; PG8_SCHED;
.LBB0_1277:
	s_add_u32 s19, s12, 0x100
	s_addc_u32 s26, s13, 0
	s_mov_b32 s27, -2
	s_nop 0
	s_nop 0
	s_nop 0
	s_nop 0
	s_nop 0
	s_add_u32 s12, s10, 0x100
	s_addc_u32 s13, s11, 0
	s_add_i32 s38, 0, 0x10000
	v_add_u32_e32 v146, s38, v149
	ds_read_b128 v[142:145], v146
	ds_read_b128 v[176:179], v146 offset:1024
	ds_read_b128 v[180:183], v146 offset:2048
	ds_read_b128 v[184:187], v146 offset:3072
	s_cmp_eq_u32 s27, 6
	s_cselect_b32 s17, s5, s13
	s_cselect_b32 s16, s4, s12
	s_cselect_b32 s15, s7, s26
	s_cselect_b32 s14, s6, s19
	v_lshl_add_u64 v[146:147], s[10:11], 0, v[138:139]
	s_add_i32 m0, s46, 0xc000
	ds_read_b128 v[188:191], v151
	ds_read_b128 v[192:195], v151 offset:1024
	ds_read_b128 v[196:199], v151 offset:2048
	ds_read_b128 v[200:203], v151 offset:3072
	ds_read_b128 v[204:207], v151 offset:4096
	ds_read_b128 v[214:217], v151 offset:5120
	ds_read_b128 v[218:221], v151 offset:6144
	ds_read_b128 v[222:225], v151 offset:7168
	global_load_lds_dwordx4 v[146:147], off
	s_add_i32 m0, s46, 0xe000
	v_lshl_add_u64 v[146:147], s[10:11], 0, v[140:141]
	global_load_lds_dwordx4 v[146:147], off
	s_waitcnt lgkmcnt(8)
	s_barrier
	s_waitcnt lgkmcnt(0)
	v_mfma_f32_16x16x32_bf16 v[126:129], v[142:145], v[188:191], 0
	v_mfma_f32_16x16x32_bf16 v[122:125], v[180:183], v[188:191], 0
	v_mfma_f32_16x16x32_bf16 v[110:113], v[142:145], v[196:199], 0
	v_mfma_f32_16x16x32_bf16 v[106:109], v[180:183], v[196:199], 0
	v_mfma_f32_16x16x32_bf16 v[94:97], v[142:145], v[204:207], 0
	v_mfma_f32_16x16x32_bf16 v[90:93], v[180:183], v[204:207], 0
	v_mfma_f32_16x16x32_bf16 v[78:81], v[142:145], v[218:221], 0
	v_mfma_f32_16x16x32_bf16 v[74:77], v[180:183], v[218:221], 0
	v_mfma_f32_16x16x32_bf16 v[126:129], v[176:179], v[192:195], v[126:129]
	v_mfma_f32_16x16x32_bf16 v[122:125], v[184:187], v[192:195], v[122:125]
	v_mfma_f32_16x16x32_bf16 v[110:113], v[176:179], v[200:203], v[110:113]
	v_mfma_f32_16x16x32_bf16 v[106:109], v[184:187], v[200:203], v[106:109]
	v_mfma_f32_16x16x32_bf16 v[94:97], v[176:179], v[214:217], v[94:97]
	v_mfma_f32_16x16x32_bf16 v[90:93], v[184:187], v[214:217], v[90:93]
	v_mfma_f32_16x16x32_bf16 v[78:81], v[176:179], v[222:225], v[78:81]
	v_mfma_f32_16x16x32_bf16 v[74:77], v[184:187], v[222:225], v[74:77]
	s_barrier
	s_add_i32 s39, 0, 0x14000
	v_add_u32_e32 v146, s39, v149
	s_add_i32 s10, s38, s37
	ds_read_b128 v[226:229], v146
	ds_read_b128 v[230:233], v146 offset:1024
	ds_read_b128 v[234:237], v146 offset:2048
	ds_read_b128 v[238:241], v146 offset:3072
	v_lshl_add_u64 v[146:147], s[14:15], 0, v[8:9]
	s_mov_b32 m0, s10
	v_lshl_add_u64 v[152:153], s[14:15], 0, v[130:131]
	global_load_lds_dwordx4 v[146:147], off
	s_add_i32 m0, s10, 0x2000
	s_nop 0
	global_load_lds_dwordx4 v[152:153], off
	s_barrier
	s_waitcnt lgkmcnt(0)
	v_mfma_f32_16x16x32_bf16 v[118:121], v[226:229], v[188:191], 0
	v_mfma_f32_16x16x32_bf16 v[114:117], v[234:237], v[188:191], 0
	v_mfma_f32_16x16x32_bf16 v[102:105], v[226:229], v[196:199], 0
	v_mfma_f32_16x16x32_bf16 v[98:101], v[234:237], v[196:199], 0
	v_mfma_f32_16x16x32_bf16 v[86:89], v[226:229], v[204:207], 0
	v_mfma_f32_16x16x32_bf16 v[82:85], v[234:237], v[204:207], 0
	v_mfma_f32_16x16x32_bf16 v[70:73], v[226:229], v[218:221], 0
	v_mfma_f32_16x16x32_bf16 v[66:69], v[234:237], v[218:221], 0
	v_mfma_f32_16x16x32_bf16 v[118:121], v[230:233], v[192:195], v[118:121]
	v_mfma_f32_16x16x32_bf16 v[114:117], v[238:241], v[192:195], v[114:117]
	v_mfma_f32_16x16x32_bf16 v[102:105], v[230:233], v[200:203], v[102:105]
	v_mfma_f32_16x16x32_bf16 v[98:101], v[238:241], v[200:203], v[98:101]
	v_mfma_f32_16x16x32_bf16 v[86:89], v[230:233], v[214:217], v[86:89]
	v_mfma_f32_16x16x32_bf16 v[82:85], v[238:241], v[214:217], v[82:85]
	v_mfma_f32_16x16x32_bf16 v[70:73], v[230:233], v[222:225], v[70:73]
	v_mfma_f32_16x16x32_bf16 v[66:69], v[238:241], v[222:225], v[66:69]
	s_mov_b32 m0, s46
	v_lshl_add_u64 v[162:163], s[16:17], 0, v[134:135]
	s_barrier
	ds_read_b128 v[188:191], v151 offset:16384
	ds_read_b128 v[192:195], v151 offset:17408
	ds_read_b128 v[196:199], v151 offset:18432
	ds_read_b128 v[200:203], v151 offset:19456
	ds_read_b128 v[204:207], v151 offset:20480
	ds_read_b128 v[214:217], v151 offset:21504
	ds_read_b128 v[218:221], v151 offset:22528
	ds_read_b128 v[222:225], v151 offset:23552
	global_load_lds_dwordx4 v[162:163], off
	s_mov_b32 m0, s47
	v_lshl_add_u64 v[164:165], s[16:17], 0, v[132:133]
	global_load_lds_dwordx4 v[164:165], off
	s_barrier
	s_waitcnt lgkmcnt(0)
	v_mfma_f32_16x16x32_bf16 v[62:65], v[142:145], v[188:191], 0
	v_mfma_f32_16x16x32_bf16 v[58:61], v[180:183], v[188:191], 0
	v_mfma_f32_16x16x32_bf16 v[46:49], v[142:145], v[196:199], 0
	v_mfma_f32_16x16x32_bf16 v[42:45], v[180:183], v[196:199], 0
	v_mfma_f32_16x16x32_bf16 v[30:33], v[142:145], v[204:207], 0
	v_mfma_f32_16x16x32_bf16 v[26:29], v[180:183], v[204:207], 0
	v_mfma_f32_16x16x32_bf16 v[14:17], v[142:145], v[218:221], 0
	v_mfma_f32_16x16x32_bf16 v[10:13], v[180:183], v[218:221], 0
	v_mfma_f32_16x16x32_bf16 v[62:65], v[176:179], v[192:195], v[62:65]
	v_mfma_f32_16x16x32_bf16 v[58:61], v[184:187], v[192:195], v[58:61]
	v_mfma_f32_16x16x32_bf16 v[46:49], v[176:179], v[200:203], v[46:49]
	v_mfma_f32_16x16x32_bf16 v[42:45], v[184:187], v[200:203], v[42:45]
	v_mfma_f32_16x16x32_bf16 v[30:33], v[176:179], v[214:217], v[30:33]
	v_mfma_f32_16x16x32_bf16 v[26:29], v[184:187], v[214:217], v[26:29]
	v_mfma_f32_16x16x32_bf16 v[14:17], v[176:179], v[222:225], v[14:17]
	v_mfma_f32_16x16x32_bf16 v[10:13], v[184:187], v[222:225], v[10:13]
	s_barrier
; #define PG8_STAGE(bufoff, gbase, voff) do { _Pragma("unroll") for (int _i = 0; _i < 2; ++_i) \
;         __builtin_amdgcn_global_load_lds((const unsigned*)((const char*)(gbase) + (voff)[_i]), (LAS unsigned*)(lds + (bufoff) + ldsw + _i * 8192), 16, 0, 0); } while (0)
; #define PG8_LDA(dst, b, h) do { _Pragma("unroll") for (int m = 0; m < 4; ++m) _Pragma("unroll") for (int k = 0; k < 2; ++k) dst[m][k] = *(const LAS bf16x8*)(lds + PG8_SA(b, h) + aoff + m * 2048 + k * 1024); } while (0)
; #define PG8_LDB(dst, b, h) do { _Pragma("unroll") for (int n = 0; n < 2; ++n) _Pragma("unroll") for (int k = 0; k < 2; ++k) dst[n][k] = *(const LAS bf16x8*)(lds + PG8_SB(b, h) + boff + n * 2048 + k * 1024); } while (0)
; #define PG8_MMA(ai, bj, At, Bt) do { __builtin_amdgcn_s_setprio(1); _Pragma("unroll") for (int m = 0; m < 4; ++m) _Pragma("unroll") for (int n = 0; n < 2; ++n) _Pragma("unroll") for (int k = 0; k < 2; ++k) \
;         acc[ai][bj][m][n] = __builtin_amdgcn_mfma_f32_16x16x32_bf16(Bt[n][k], At[m][k], acc[ai][bj][m][n], 0, 0, 0); __builtin_amdgcn_s_setprio(0); } while (0)
; #define PG8_WAIT_V(n) asm volatile("s_waitcnt vmcnt(" #n ")" ::: "memory")
; #define PG8_WAIT_L(n) asm volatile("s_waitcnt lgkmcnt(" #n ")" ::: "memory")
; #define PG8_BAR __builtin_amdgcn_s_barrier()
; #define PG8_SCHED __builtin_amdgcn_sched_barrier(0)
; template <class Epi>
; DEVI void gemm_phase(LAS unsigned char* lds, const Gemm g, const Epi& E) {
;     ...
;             PG8_STAGE(PG8_SB(0, 1), b2 + hstepB, voffB);
;             PG8_WAIT_V(6); PG8_BAR; PG8_MMA(1, 1, At, B1); PG8_BAR;
;             PG8_LDB(B0, 1, 0); PG8_SCHED; PG8_LDA(At, 1, 0); PG8_STAGE(PG8_SA(0, 1), a2 + hstepA, voffA);
;             PG8_WAIT_L(8); PG8_BAR; PG8_WAIT_L(0); PG8_MMA(0, 0, At, B0); PG8_BAR; PG8_SCHED;
;             PG8_LDB(B1, 1, 1); PG8_STAGE(PG8_SB(1, 0), b3, voffB);
	s_add_u32 s10, s14, 0x28000
	s_addc_u32 s11, s15, 0
	s_add_i32 s38, s39, s37
	s_mov_b32 m0, s38
	v_lshl_add_u64 v[142:143], s[10:11], 0, v[8:9]
	global_load_lds_dwordx4 v[142:143], off
	s_add_i32 m0, s38, 0x2000
	v_lshl_add_u64 v[142:143], s[10:11], 0, v[130:131]
	global_load_lds_dwordx4 v[142:143], off
	s_waitcnt vmcnt(6)
	s_barrier
	v_mfma_f32_16x16x32_bf16 v[54:57], v[226:229], v[188:191], 0
	v_mfma_f32_16x16x32_bf16 v[50:53], v[234:237], v[188:191], 0
	v_mfma_f32_16x16x32_bf16 v[38:41], v[226:229], v[196:199], 0
	v_mfma_f32_16x16x32_bf16 v[34:37], v[234:237], v[196:199], 0
	v_mfma_f32_16x16x32_bf16 v[22:25], v[226:229], v[204:207], 0
	v_mfma_f32_16x16x32_bf16 v[18:21], v[234:237], v[204:207], 0
	v_mfma_f32_16x16x32_bf16 v[4:7], v[226:229], v[218:221], 0
	v_mfma_f32_16x16x32_bf16 v[0:3], v[234:237], v[218:221], 0
	v_mfma_f32_16x16x32_bf16 v[54:57], v[230:233], v[192:195], v[54:57]
	v_mfma_f32_16x16x32_bf16 v[50:53], v[238:241], v[192:195], v[50:53]
	v_mfma_f32_16x16x32_bf16 v[38:41], v[230:233], v[200:203], v[38:41]
	v_mfma_f32_16x16x32_bf16 v[34:37], v[238:241], v[200:203], v[34:37]
	v_mfma_f32_16x16x32_bf16 v[22:25], v[230:233], v[214:217], v[22:25]
	v_mfma_f32_16x16x32_bf16 v[18:21], v[238:241], v[214:217], v[18:21]
	v_mfma_f32_16x16x32_bf16 v[4:7], v[230:233], v[222:225], v[4:7]
	v_mfma_f32_16x16x32_bf16 v[0:3], v[238:241], v[222:225], v[0:3]
	s_add_i32 s38, 0, 0x18000
	v_add_u32_e32 v184, s38, v149
	s_barrier
	ds_read_b128 v[142:145], v184
	ds_read_b128 v[176:179], v184 offset:1024
	ds_read_b128 v[180:183], v184 offset:2048
	ds_read_b128 v[184:187], v184 offset:3072
	s_add_u32 s10, s16, 0x28000
	s_addc_u32 s11, s17, 0
	s_mov_b32 m0, s66
	v_lshl_add_u64 v[208:209], s[10:11], 0, v[134:135]
	ds_read_b128 v[188:191], v151 offset:32768
	ds_read_b128 v[192:195], v151 offset:33792
	ds_read_b128 v[196:199], v151 offset:34816
	ds_read_b128 v[200:203], v151 offset:35840
	ds_read_b128 v[204:207], v151 offset:36864
	ds_read_b128 v[214:217], v151 offset:37888
	ds_read_b128 v[218:221], v151 offset:38912
	ds_read_b128 v[222:225], v151 offset:39936
	global_load_lds_dwordx4 v[208:209], off
	s_mov_b32 m0, s68
	v_lshl_add_u64 v[208:209], s[10:11], 0, v[132:133]
	global_load_lds_dwordx4 v[208:209], off
	s_waitcnt lgkmcnt(8)
	s_barrier
	s_waitcnt lgkmcnt(0)
	v_mfma_f32_16x16x32_bf16 v[126:129], v[142:145], v[188:191], v[126:129]
	v_mfma_f32_16x16x32_bf16 v[122:125], v[180:183], v[188:191], v[122:125]
	v_mfma_f32_16x16x32_bf16 v[110:113], v[142:145], v[196:199], v[110:113]
	v_mfma_f32_16x16x32_bf16 v[106:109], v[180:183], v[196:199], v[106:109]
	v_mfma_f32_16x16x32_bf16 v[94:97], v[142:145], v[204:207], v[94:97]
	v_mfma_f32_16x16x32_bf16 v[90:93], v[180:183], v[204:207], v[90:93]
	v_mfma_f32_16x16x32_bf16 v[78:81], v[142:145], v[218:221], v[78:81]
	v_mfma_f32_16x16x32_bf16 v[74:77], v[180:183], v[218:221], v[74:77]
	v_mfma_f32_16x16x32_bf16 v[126:129], v[176:179], v[192:195], v[126:129]
	v_mfma_f32_16x16x32_bf16 v[122:125], v[184:187], v[192:195], v[122:125]
	v_mfma_f32_16x16x32_bf16 v[110:113], v[176:179], v[200:203], v[110:113]
	v_mfma_f32_16x16x32_bf16 v[106:109], v[184:187], v[200:203], v[106:109]
	v_mfma_f32_16x16x32_bf16 v[94:97], v[176:179], v[214:217], v[94:97]
	v_mfma_f32_16x16x32_bf16 v[90:93], v[184:187], v[214:217], v[90:93]
	v_mfma_f32_16x16x32_bf16 v[78:81], v[176:179], v[222:225], v[78:81]
	v_mfma_f32_16x16x32_bf16 v[74:77], v[184:187], v[222:225], v[74:77]
	s_barrier
	s_add_i32 s16, 0, 0x1c000
	s_add_i32 s10, s38, s37
	v_add_u32_e32 v208, s16, v149
	v_lshl_add_u64 v[146:147], v[146:147], 0, s[70:71]
	s_mov_b32 m0, s10
	ds_read_b128 v[226:229], v208
	ds_read_b128 v[230:233], v208 offset:1024
	ds_read_b128 v[234:237], v208 offset:2048
	ds_read_b128 v[238:241], v208 offset:3072
	global_load_lds_dwordx4 v[146:147], off
	s_add_i32 m0, s10, 0x2000
	v_lshl_add_u64 v[146:147], v[152:153], 0, s[70:71]
	global_load_lds_dwordx4 v[146:147], off
	s_barrier
; #define PG8_STAGE(bufoff, gbase, voff) do { _Pragma("unroll") for (int _i = 0; _i < 2; ++_i) \
;         __builtin_amdgcn_global_load_lds((const unsigned*)((const char*)(gbase) + (voff)[_i]), (LAS unsigned*)(lds + (bufoff) + ldsw + _i * 8192), 16, 0, 0); } while (0)
; #define PG8_LDA(dst, b, h) do { _Pragma("unroll") for (int m = 0; m < 4; ++m) _Pragma("unroll") for (int k = 0; k < 2; ++k) dst[m][k] = *(const LAS bf16x8*)(lds + PG8_SA(b, h) + aoff + m * 2048 + k * 1024); } while (0)
; #define PG8_MMA(ai, bj, At, Bt) do { __builtin_amdgcn_s_setprio(1); _Pragma("unroll") for (int m = 0; m < 4; ++m) _Pragma("unroll") for (int n = 0; n < 2; ++n) _Pragma("unroll") for (int k = 0; k < 2; ++k) \
;         acc[ai][bj][m][n] = __builtin_amdgcn_mfma_f32_16x16x32_bf16(Bt[n][k], At[m][k], acc[ai][bj][m][n], 0, 0, 0); __builtin_amdgcn_s_setprio(0); } while (0)
; #define PG8_WAIT_V(n) asm volatile("s_waitcnt vmcnt(" #n ")" ::: "memory")
; #define PG8_WAIT_L(n) asm volatile("s_waitcnt lgkmcnt(" #n ")" ::: "memory")
; #define PG8_BAR __builtin_amdgcn_s_barrier()
; #define PG8_SCHED __builtin_amdgcn_sched_barrier(0)
; template <class Epi>
; DEVI void gemm_phase(LAS unsigned char* lds, const Gemm g, const Epi& E) {
;     ...
;             PG8_BAR; PG8_WAIT_L(0); PG8_MMA(0, 1, At, B1); PG8_BAR;
;             PG8_LDA(At, 1, 1); PG8_STAGE(PG8_SA(1, 0), a3, voffA);
;             PG8_BAR; PG8_WAIT_L(0); PG8_MMA(1, 0, At, B0); PG8_BAR; PG8_SCHED;
;             PG8_STAGE(PG8_SB(1, 1), b3 + hstepB, voffB);
;             PG8_WAIT_V(6); PG8_BAR; PG8_MMA(1, 1, At, B1); PG8_BAR;
;         }
	s_waitcnt lgkmcnt(0)
	v_mfma_f32_16x16x32_bf16 v[118:121], v[226:229], v[188:191], v[118:121]
	v_mfma_f32_16x16x32_bf16 v[114:117], v[234:237], v[188:191], v[114:117]
	v_mfma_f32_16x16x32_bf16 v[102:105], v[226:229], v[196:199], v[102:105]
	v_mfma_f32_16x16x32_bf16 v[98:101], v[234:237], v[196:199], v[98:101]
	v_mfma_f32_16x16x32_bf16 v[86:89], v[226:229], v[204:207], v[86:89]
	v_mfma_f32_16x16x32_bf16 v[82:85], v[234:237], v[204:207], v[82:85]
	v_mfma_f32_16x16x32_bf16 v[70:73], v[226:229], v[218:221], v[70:73]
	v_mfma_f32_16x16x32_bf16 v[66:69], v[234:237], v[218:221], v[66:69]
	v_mfma_f32_16x16x32_bf16 v[118:121], v[230:233], v[192:195], v[118:121]
	v_mfma_f32_16x16x32_bf16 v[114:117], v[238:241], v[192:195], v[114:117]
	v_mfma_f32_16x16x32_bf16 v[102:105], v[230:233], v[200:203], v[102:105]
	v_mfma_f32_16x16x32_bf16 v[98:101], v[238:241], v[200:203], v[98:101]
	v_mfma_f32_16x16x32_bf16 v[86:89], v[230:233], v[214:217], v[86:89]
	v_mfma_f32_16x16x32_bf16 v[82:85], v[238:241], v[214:217], v[82:85]
	v_mfma_f32_16x16x32_bf16 v[70:73], v[230:233], v[222:225], v[70:73]
	v_mfma_f32_16x16x32_bf16 v[66:69], v[238:241], v[222:225], v[66:69]
	s_mov_b32 m0, s69
	v_lshl_add_u64 v[146:147], v[162:163], 0, s[70:71]
	s_barrier
	ds_read_b128 v[188:191], v151 offset:49152
	ds_read_b128 v[192:195], v151 offset:50176
	ds_read_b128 v[196:199], v151 offset:51200
	ds_read_b128 v[200:203], v151 offset:52224
	ds_read_b128 v[204:207], v151 offset:53248
	ds_read_b128 v[214:217], v151 offset:54272
	ds_read_b128 v[218:221], v151 offset:55296
	ds_read_b128 v[222:225], v151 offset:56320
	global_load_lds_dwordx4 v[146:147], off
	s_mov_b32 m0, s80
	v_lshl_add_u64 v[146:147], v[164:165], 0, s[70:71]
	global_load_lds_dwordx4 v[146:147], off
	s_barrier
	s_waitcnt lgkmcnt(0)
	v_mfma_f32_16x16x32_bf16 v[62:65], v[142:145], v[188:191], v[62:65]
	v_mfma_f32_16x16x32_bf16 v[58:61], v[180:183], v[188:191], v[58:61]
	v_mfma_f32_16x16x32_bf16 v[46:49], v[142:145], v[196:199], v[46:49]
	v_mfma_f32_16x16x32_bf16 v[42:45], v[180:183], v[196:199], v[42:45]
	v_mfma_f32_16x16x32_bf16 v[30:33], v[142:145], v[204:207], v[30:33]
	v_mfma_f32_16x16x32_bf16 v[26:29], v[180:183], v[204:207], v[26:29]
	v_mfma_f32_16x16x32_bf16 v[14:17], v[142:145], v[218:221], v[14:17]
	v_mfma_f32_16x16x32_bf16 v[10:13], v[180:183], v[218:221], v[10:13]
	v_mfma_f32_16x16x32_bf16 v[62:65], v[176:179], v[192:195], v[62:65]
	v_mfma_f32_16x16x32_bf16 v[58:61], v[184:187], v[192:195], v[58:61]
	v_mfma_f32_16x16x32_bf16 v[46:49], v[176:179], v[200:203], v[46:49]
	v_mfma_f32_16x16x32_bf16 v[42:45], v[184:187], v[200:203], v[42:45]
	v_mfma_f32_16x16x32_bf16 v[30:33], v[176:179], v[214:217], v[30:33]
	v_mfma_f32_16x16x32_bf16 v[26:29], v[184:187], v[214:217], v[26:29]
	v_mfma_f32_16x16x32_bf16 v[14:17], v[176:179], v[222:225], v[14:17]
	v_mfma_f32_16x16x32_bf16 v[10:13], v[184:187], v[222:225], v[10:13]
	s_barrier
	s_add_u32 s10, s14, 0x28080
	s_addc_u32 s11, s15, 0
	s_add_i32 s14, s16, s37
	s_mov_b32 m0, s14
	v_lshl_add_u64 v[142:143], s[10:11], 0, v[8:9]
	global_load_lds_dwordx4 v[142:143], off
	s_add_i32 m0, s14, 0x2000
	v_lshl_add_u64 v[142:143], s[10:11], 0, v[130:131]
	global_load_lds_dwordx4 v[142:143], off
	s_waitcnt vmcnt(6)
	s_barrier
	v_mfma_f32_16x16x32_bf16 v[54:57], v[226:229], v[188:191], v[54:57]
	v_mfma_f32_16x16x32_bf16 v[50:53], v[234:237], v[188:191], v[50:53]
	v_mfma_f32_16x16x32_bf16 v[38:41], v[226:229], v[196:199], v[38:41]
	v_mfma_f32_16x16x32_bf16 v[34:37], v[234:237], v[196:199], v[34:37]
	v_mfma_f32_16x16x32_bf16 v[22:25], v[226:229], v[204:207], v[22:25]
	v_mfma_f32_16x16x32_bf16 v[18:21], v[234:237], v[204:207], v[18:21]
	v_mfma_f32_16x16x32_bf16 v[4:7], v[226:229], v[218:221], v[4:7]
	v_mfma_f32_16x16x32_bf16 v[0:3], v[234:237], v[218:221], v[0:3]
	v_mfma_f32_16x16x32_bf16 v[54:57], v[230:233], v[192:195], v[54:57]
	v_mfma_f32_16x16x32_bf16 v[50:53], v[238:241], v[192:195], v[50:53]
	v_mfma_f32_16x16x32_bf16 v[38:41], v[230:233], v[200:203], v[38:41]
	v_mfma_f32_16x16x32_bf16 v[34:37], v[238:241], v[200:203], v[34:37]
	v_mfma_f32_16x16x32_bf16 v[22:25], v[230:233], v[214:217], v[22:25]
	v_mfma_f32_16x16x32_bf16 v[18:21], v[238:241], v[214:217], v[18:21]
	v_mfma_f32_16x16x32_bf16 v[4:7], v[230:233], v[222:225], v[4:7]
	v_mfma_f32_16x16x32_bf16 v[0:3], v[238:241], v[222:225], v[0:3]
	s_add_i32 s27, s27, 2
	s_add_u32 s19, s19, 0x100
	s_addc_u32 s26, s26, 0
	s_cmp_gt_u32 s27, 7
	s_mov_b64 s[10:11], s[12:13]
	s_barrier

; DEVI size_t gemm_offB(const Gemm& g, const Unit& u) { return (g.split ? (size_t)(u.b >> 2) * g.sB + (size_t)(u.b & 3) * g.sB_lo : (size_t)u.b * g.sB) + (size_t)(u.pm >> g.pmsh) * g.sBpm; }
; #define PG8_STAGE(bufoff, gbase, voff) do { _Pragma("unroll") for (int _i = 0; _i < 2; ++_i) \
;         __builtin_amdgcn_global_load_lds((const unsigned*)((const char*)(gbase) + (voff)[_i]), (LAS unsigned*)(lds + (bufoff) + ldsw + _i * 8192), 16, 0, 0); } while (0)
; #define PG8_LDA(dst, b, h) do { _Pragma("unroll") for (int m = 0; m < 4; ++m) _Pragma("unroll") for (int k = 0; k < 2; ++k) dst[m][k] = *(const LAS bf16x8*)(lds + PG8_SA(b, h) + aoff + m * 2048 + k * 1024); } while (0)
; #define PG8_LDB(dst, b, h) do { _Pragma("unroll") for (int n = 0; n < 2; ++n) _Pragma("unroll") for (int k = 0; k < 2; ++k) dst[n][k] = *(const LAS bf16x8*)(lds + PG8_SB(b, h) + boff + n * 2048 + k * 1024); } while (0)
; #define PG8_WAIT_L(n) asm volatile("s_waitcnt lgkmcnt(" #n ")" ::: "memory")
; #define PG8_BAR __builtin_amdgcn_s_barrier()
; #define PG8_SCHED __builtin_amdgcn_sched_barrier(0)
; template <class Epi>
; DEVI void gemm_phase(LAS unsigned char* lds, const Gemm g, const Epi& E) {
;     ...
;         const bool has_next = unit_next(g, ui + 1, nxt);
;         const char* nA = has_next ? (const char*)g.A + gemm_offA(g, nxt) * 2 + (size_t)nxt.pm * tstepA : cA;
;         const char* nB = has_next ? (const char*)g.Bt + gemm_offB(g, nxt) * 2 + (size_t)nxt.pn * tstepB : cB;
;         for (int t = 0; t < nt; t += 2) {
;             const bool last = (t == nt - 2);
;             const char* a1 = cA + (size_t)(t + 1) * kstep;
;             const char* a2 = last ? nA : cA + (size_t)(t + 2) * kstep; const char* b2 = last ? nB : cB + (size_t)(t + 2) * kstep;
;             const char* a3 = a2 + kstep; const char* b3 = b2 + kstep;
;             PG8_LDB(B0, 0, 0); PG8_SCHED; PG8_LDA(At, 0, 0); PG8_STAGE(PG8_SA(1, 1), a1 + hstepA, voffA);
;             PG8_WAIT_L(8); PG8_BAR; PG8_WAIT_L(0); PG8_MMA(0, 0, At, B0); PG8_BAR; PG8_SCHED;
;             PG8_LDB(B1, 0, 1); PG8_STAGE(PG8_SB(0, 0), b2, voffB);
;             PG8_BAR; PG8_WAIT_L(0); PG8_MMA(0, 1, At, B1); PG8_BAR;
;             PG8_LDA(At, 0, 1); PG8_STAGE(PG8_SA(0, 0), a2, voffA);
;             PG8_BAR; PG8_WAIT_L(0); PG8_MMA(1, 0, At, B0); PG8_BAR; PG8_SCHED;
.LBB0_1345:
	s_ashr_i32 s3, s2, 31
	v_cmp_lt_i64_e32 vcc, s[6:7], v[168:169]
	s_lshl_b64 s[6:7], s[2:3], 19
	s_add_u32 s6, s24, s6
	s_addc_u32 s7, s25, s7
	s_and_b64 s[8:9], vcc, exec
	s_cselect_b32 s1, s7, s13
	s_cselect_b32 s3, s6, s12
	s_ashr_i32 s5, s4, 31
	s_lshl_b64 s[8:9], s[4:5], 19
	v_readlane_b32 s16, v251, 58
	v_readlane_b32 s17, v251, 59
	s_add_u32 s8, s16, s8
	s_addc_u32 s9, s17, s9
	s_and_b64 s[16:17], vcc, exec
	s_cselect_b32 s5, s9, s15
	s_cselect_b32 s18, s8, s14
	s_add_u32 s12, s12, 0x40080
	s_addc_u32 s13, s13, 0
	s_add_u32 s19, s14, 0x100
	s_mov_b32 s85, s63
	s_mov_b32 s84, s62
	s_mov_b32 s83, s61
	s_mov_b32 s41, s60
	s_mov_b64 s[44:45], s[58:59]
	s_mov_b64 s[42:43], s[56:57]
	s_addc_u32 s26, s15, 0
	s_mov_b32 s27, -2
	s_nop 0
	s_nop 0
	s_nop 0
	s_nop 0
	s_add_u32 s14, s12, 0xfffc0080
	s_addc_u32 s15, s13, -1
	s_add_i32 s38, 0, 0x10000
	v_add_u32_e32 v152, s38, v185
	ds_read_b128 v[114:117], v152
	ds_read_b128 v[126:129], v152 offset:1024
	ds_read_b128 v[130:133], v152 offset:2048
	ds_read_b128 v[176:179], v152 offset:3072
	s_cmp_eq_u32 s27, 12
	s_cselect_b32 s17, s1, s15
	s_cselect_b32 s16, s3, s14
	s_cselect_b32 s15, s5, s26
	s_cselect_b32 s14, s18, s19
	v_lshl_add_u64 v[152:153], s[12:13], 0, v[148:149]
	s_add_i32 m0, s11, 0xc000
	ds_read_b128 v[180:183], v187
	ds_read_b128 v[188:191], v187 offset:1024
	ds_read_b128 v[192:195], v187 offset:2048
	ds_read_b128 v[196:199], v187 offset:3072
	ds_read_b128 v[200:203], v187 offset:4096
	ds_read_b128 v[204:207], v187 offset:5120
	ds_read_b128 v[214:217], v187 offset:6144
	ds_read_b128 v[218:221], v187 offset:7168
	global_load_lds_dwordx4 v[152:153], off
	s_add_i32 m0, s11, 0xe000
	v_lshl_add_u64 v[152:153], s[12:13], 0, v[150:151]
	global_load_lds_dwordx4 v[152:153], off
	s_waitcnt lgkmcnt(8)
	s_barrier
	s_waitcnt lgkmcnt(0)
	v_mfma_f32_16x16x32_bf16 v[138:141], v[114:117], v[180:183], 0
	v_mfma_f32_16x16x32_bf16 v[134:137], v[130:133], v[180:183], 0
	v_mfma_f32_16x16x32_bf16 v[110:113], v[114:117], v[192:195], 0
	v_mfma_f32_16x16x32_bf16 v[106:109], v[130:133], v[192:195], 0
	v_mfma_f32_16x16x32_bf16 v[94:97], v[114:117], v[200:203], 0
	v_mfma_f32_16x16x32_bf16 v[90:93], v[130:133], v[200:203], 0
	v_mfma_f32_16x16x32_bf16 v[78:81], v[114:117], v[214:217], 0
	v_mfma_f32_16x16x32_bf16 v[74:77], v[130:133], v[214:217], 0
	v_mfma_f32_16x16x32_bf16 v[138:141], v[126:129], v[188:191], v[138:141]
	v_mfma_f32_16x16x32_bf16 v[134:137], v[176:179], v[188:191], v[134:137]
	v_mfma_f32_16x16x32_bf16 v[110:113], v[126:129], v[196:199], v[110:113]
	v_mfma_f32_16x16x32_bf16 v[106:109], v[176:179], v[196:199], v[106:109]
	v_mfma_f32_16x16x32_bf16 v[94:97], v[126:129], v[204:207], v[94:97]
	v_mfma_f32_16x16x32_bf16 v[90:93], v[176:179], v[204:207], v[90:93]
	v_mfma_f32_16x16x32_bf16 v[78:81], v[126:129], v[218:221], v[78:81]
	v_mfma_f32_16x16x32_bf16 v[74:77], v[176:179], v[218:221], v[74:77]
	s_barrier
	s_add_i32 s40, 0, 0x14000
	v_add_u32_e32 v152, s40, v185
	s_add_i32 s38, s38, s47
	ds_read_b128 v[222:225], v152
	ds_read_b128 v[226:229], v152 offset:1024
	ds_read_b128 v[230:233], v152 offset:2048
	ds_read_b128 v[234:237], v152 offset:3072
	v_lshl_add_u64 v[152:153], s[14:15], 0, v[8:9]
	s_mov_b32 m0, s38
	v_lshl_add_u64 v[162:163], s[14:15], 0, v[146:147]
	global_load_lds_dwordx4 v[152:153], off
	s_add_i32 m0, s38, 0x2000
	s_nop 0
	global_load_lds_dwordx4 v[162:163], off
	s_barrier
	s_waitcnt lgkmcnt(0)
	v_mfma_f32_16x16x32_bf16 v[122:125], v[222:225], v[180:183], 0
	v_mfma_f32_16x16x32_bf16 v[118:121], v[230:233], v[180:183], 0
	v_mfma_f32_16x16x32_bf16 v[102:105], v[222:225], v[192:195], 0
	v_mfma_f32_16x16x32_bf16 v[98:101], v[230:233], v[192:195], 0
	v_mfma_f32_16x16x32_bf16 v[86:89], v[222:225], v[200:203], 0
	v_mfma_f32_16x16x32_bf16 v[82:85], v[230:233], v[200:203], 0
	v_mfma_f32_16x16x32_bf16 v[70:73], v[222:225], v[214:217], 0
	v_mfma_f32_16x16x32_bf16 v[66:69], v[230:233], v[214:217], 0
	v_mfma_f32_16x16x32_bf16 v[122:125], v[226:229], v[188:191], v[122:125]
	v_mfma_f32_16x16x32_bf16 v[118:121], v[234:237], v[188:191], v[118:121]
	v_mfma_f32_16x16x32_bf16 v[102:105], v[226:229], v[196:199], v[102:105]
	v_mfma_f32_16x16x32_bf16 v[98:101], v[234:237], v[196:199], v[98:101]
	v_mfma_f32_16x16x32_bf16 v[86:89], v[226:229], v[204:207], v[86:89]
	v_mfma_f32_16x16x32_bf16 v[82:85], v[234:237], v[204:207], v[82:85]
	v_mfma_f32_16x16x32_bf16 v[70:73], v[226:229], v[218:221], v[70:73]
	v_mfma_f32_16x16x32_bf16 v[66:69], v[234:237], v[218:221], v[66:69]
	s_mov_b32 m0, s11
	v_lshl_add_u64 v[164:165], s[16:17], 0, v[142:143]
	s_barrier
	ds_read_b128 v[180:183], v187 offset:16384
	ds_read_b128 v[188:191], v187 offset:17408
	ds_read_b128 v[192:195], v187 offset:18432
	ds_read_b128 v[196:199], v187 offset:19456
	ds_read_b128 v[200:203], v187 offset:20480
	ds_read_b128 v[204:207], v187 offset:21504
	ds_read_b128 v[214:217], v187 offset:22528
	ds_read_b128 v[218:221], v187 offset:23552
	global_load_lds_dwordx4 v[164:165], off
	s_mov_b32 m0, s66
	v_lshl_add_u64 v[208:209], s[16:17], 0, v[144:145]
	global_load_lds_dwordx4 v[208:209], off
	s_barrier
	s_waitcnt lgkmcnt(0)
	v_mfma_f32_16x16x32_bf16 v[62:65], v[114:117], v[180:183], 0
	v_mfma_f32_16x16x32_bf16 v[58:61], v[130:133], v[180:183], 0
	v_mfma_f32_16x16x32_bf16 v[46:49], v[114:117], v[192:195], 0
	v_mfma_f32_16x16x32_bf16 v[42:45], v[130:133], v[192:195], 0
	v_mfma_f32_16x16x32_bf16 v[30:33], v[114:117], v[200:203], 0
	v_mfma_f32_16x16x32_bf16 v[26:29], v[130:133], v[200:203], 0
	v_mfma_f32_16x16x32_bf16 v[14:17], v[114:117], v[214:217], 0
	v_mfma_f32_16x16x32_bf16 v[10:13], v[130:133], v[214:217], 0
	v_mfma_f32_16x16x32_bf16 v[62:65], v[126:129], v[188:191], v[62:65]
	v_mfma_f32_16x16x32_bf16 v[58:61], v[176:179], v[188:191], v[58:61]
	v_mfma_f32_16x16x32_bf16 v[46:49], v[126:129], v[196:199], v[46:49]
	v_mfma_f32_16x16x32_bf16 v[42:45], v[176:179], v[196:199], v[42:45]
	v_mfma_f32_16x16x32_bf16 v[30:33], v[126:129], v[204:207], v[30:33]
	v_mfma_f32_16x16x32_bf16 v[26:29], v[176:179], v[204:207], v[26:29]
	v_mfma_f32_16x16x32_bf16 v[14:17], v[126:129], v[218:221], v[14:17]
	v_mfma_f32_16x16x32_bf16 v[10:13], v[176:179], v[218:221], v[10:13]
	s_barrier
; #define PG8_STAGE(bufoff, gbase, voff) do { _Pragma("unroll") for (int _i = 0; _i < 2; ++_i) \
;         __builtin_amdgcn_global_load_lds((const unsigned*)((const char*)(gbase) + (voff)[_i]), (LAS unsigned*)(lds + (bufoff) + ldsw + _i * 8192), 16, 0, 0); } while (0)
; #define PG8_LDA(dst, b, h) do { _Pragma("unroll") for (int m = 0; m < 4; ++m) _Pragma("unroll") for (int k = 0; k < 2; ++k) dst[m][k] = *(const LAS bf16x8*)(lds + PG8_SA(b, h) + aoff + m * 2048 + k * 1024); } while (0)
; #define PG8_LDB(dst, b, h) do { _Pragma("unroll") for (int n = 0; n < 2; ++n) _Pragma("unroll") for (int k = 0; k < 2; ++k) dst[n][k] = *(const LAS bf16x8*)(lds + PG8_SB(b, h) + boff + n * 2048 + k * 1024); } while (0)
; #define PG8_MMA(ai, bj, At, Bt) do { __builtin_amdgcn_s_setprio(1); _Pragma("unroll") for (int m = 0; m < 4; ++m) _Pragma("unroll") for (int n = 0; n < 2; ++n) _Pragma("unroll") for (int k = 0; k < 2; ++k) \
;         acc[ai][bj][m][n] = __builtin_amdgcn_mfma_f32_16x16x32_bf16(Bt[n][k], At[m][k], acc[ai][bj][m][n], 0, 0, 0); __builtin_amdgcn_s_setprio(0); } while (0)
; #define PG8_WAIT_V(n) asm volatile("s_waitcnt vmcnt(" #n ")" ::: "memory")
; #define PG8_WAIT_L(n) asm volatile("s_waitcnt lgkmcnt(" #n ")" ::: "memory")
; #define PG8_BAR __builtin_amdgcn_s_barrier()
; #define PG8_SCHED __builtin_amdgcn_sched_barrier(0)
; template <class Epi>
; DEVI void gemm_phase(LAS unsigned char* lds, const Gemm g, const Epi& E) {
;     ...
;             PG8_STAGE(PG8_SB(0, 1), b2 + hstepB, voffB);
;             PG8_WAIT_V(6); PG8_BAR; PG8_MMA(1, 1, At, B1); PG8_BAR;
;             PG8_LDB(B0, 1, 0); PG8_SCHED; PG8_LDA(At, 1, 0); PG8_STAGE(PG8_SA(0, 1), a2 + hstepA, voffA);
;             PG8_WAIT_L(8); PG8_BAR; PG8_WAIT_L(0); PG8_MMA(0, 0, At, B0); PG8_BAR; PG8_SCHED;
;             PG8_LDB(B1, 1, 1); PG8_STAGE(PG8_SB(1, 0), b3, voffB);
	s_add_u32 s38, s14, 0x40000
	s_addc_u32 s39, s15, 0
	s_add_i32 s40, s40, s47
	s_mov_b32 m0, s40
	v_lshl_add_u64 v[114:115], s[38:39], 0, v[8:9]
	global_load_lds_dwordx4 v[114:115], off
	s_add_i32 m0, s40, 0x2000
	v_lshl_add_u64 v[114:115], s[38:39], 0, v[146:147]
	global_load_lds_dwordx4 v[114:115], off
	s_waitcnt vmcnt(6)
	s_barrier
	v_mfma_f32_16x16x32_bf16 v[54:57], v[222:225], v[180:183], 0
	v_mfma_f32_16x16x32_bf16 v[50:53], v[230:233], v[180:183], 0
	v_mfma_f32_16x16x32_bf16 v[38:41], v[222:225], v[192:195], 0
	v_mfma_f32_16x16x32_bf16 v[34:37], v[230:233], v[192:195], 0
	v_mfma_f32_16x16x32_bf16 v[22:25], v[222:225], v[200:203], 0
	v_mfma_f32_16x16x32_bf16 v[18:21], v[230:233], v[200:203], 0
	v_mfma_f32_16x16x32_bf16 v[4:7], v[222:225], v[214:217], 0
	v_mfma_f32_16x16x32_bf16 v[0:3], v[230:233], v[214:217], 0
	v_mfma_f32_16x16x32_bf16 v[54:57], v[226:229], v[188:191], v[54:57]
	v_mfma_f32_16x16x32_bf16 v[50:53], v[234:237], v[188:191], v[50:53]
	v_mfma_f32_16x16x32_bf16 v[38:41], v[226:229], v[196:199], v[38:41]
	v_mfma_f32_16x16x32_bf16 v[34:37], v[234:237], v[196:199], v[34:37]
	v_mfma_f32_16x16x32_bf16 v[22:25], v[226:229], v[204:207], v[22:25]
	v_mfma_f32_16x16x32_bf16 v[18:21], v[234:237], v[204:207], v[18:21]
	v_mfma_f32_16x16x32_bf16 v[4:7], v[226:229], v[218:221], v[4:7]
	v_mfma_f32_16x16x32_bf16 v[0:3], v[234:237], v[218:221], v[0:3]
	s_add_i32 s38, 0, 0x18000
	v_add_u32_e32 v176, s38, v185
	s_barrier
	ds_read_b128 v[114:117], v176
	ds_read_b128 v[126:129], v176 offset:1024
	ds_read_b128 v[130:133], v176 offset:2048
	ds_read_b128 v[176:179], v176 offset:3072
	s_add_u32 s16, s16, 0x40000
	s_addc_u32 s17, s17, 0
	s_mov_b32 m0, s68
	v_lshl_add_u64 v[222:223], s[16:17], 0, v[142:143]
	ds_read_b128 v[180:183], v187 offset:32768
	ds_read_b128 v[188:191], v187 offset:33792
	ds_read_b128 v[192:195], v187 offset:34816
	ds_read_b128 v[196:199], v187 offset:35840
	ds_read_b128 v[200:203], v187 offset:36864
	ds_read_b128 v[204:207], v187 offset:37888
	ds_read_b128 v[214:217], v187 offset:38912
	ds_read_b128 v[218:221], v187 offset:39936
	global_load_lds_dwordx4 v[222:223], off
	s_mov_b32 m0, s69
	v_lshl_add_u64 v[222:223], s[16:17], 0, v[144:145]
	global_load_lds_dwordx4 v[222:223], off
	s_waitcnt lgkmcnt(8)
	s_barrier
	s_waitcnt lgkmcnt(0)
	v_mfma_f32_16x16x32_bf16 v[138:141], v[114:117], v[180:183], v[138:141]
	v_mfma_f32_16x16x32_bf16 v[134:137], v[130:133], v[180:183], v[134:137]
	v_mfma_f32_16x16x32_bf16 v[110:113], v[114:117], v[192:195], v[110:113]
	v_mfma_f32_16x16x32_bf16 v[106:109], v[130:133], v[192:195], v[106:109]
	v_mfma_f32_16x16x32_bf16 v[94:97], v[114:117], v[200:203], v[94:97]
	v_mfma_f32_16x16x32_bf16 v[90:93], v[130:133], v[200:203], v[90:93]
	v_mfma_f32_16x16x32_bf16 v[78:81], v[114:117], v[214:217], v[78:81]
	v_mfma_f32_16x16x32_bf16 v[74:77], v[130:133], v[214:217], v[74:77]
	v_mfma_f32_16x16x32_bf16 v[138:141], v[126:129], v[188:191], v[138:141]
	v_mfma_f32_16x16x32_bf16 v[134:137], v[176:179], v[188:191], v[134:137]
	v_mfma_f32_16x16x32_bf16 v[110:113], v[126:129], v[196:199], v[110:113]
	v_mfma_f32_16x16x32_bf16 v[106:109], v[176:179], v[196:199], v[106:109]
	v_mfma_f32_16x16x32_bf16 v[94:97], v[126:129], v[204:207], v[94:97]
	v_mfma_f32_16x16x32_bf16 v[90:93], v[176:179], v[204:207], v[90:93]
	v_mfma_f32_16x16x32_bf16 v[78:81], v[126:129], v[218:221], v[78:81]
	v_mfma_f32_16x16x32_bf16 v[74:77], v[176:179], v[218:221], v[74:77]
	s_barrier
	s_add_i32 s16, 0, 0x1c000
	s_add_i32 s17, s38, s47
	v_add_u32_e32 v213, s16, v185
	v_lshl_add_u64 v[152:153], v[152:153], 0, s[70:71]
	s_mov_b32 m0, s17
	ds_read_b128 v[222:225], v213
	ds_read_b128 v[226:229], v213 offset:1024
	ds_read_b128 v[230:233], v213 offset:2048
	ds_read_b128 v[234:237], v213 offset:3072
	global_load_lds_dwordx4 v[152:153], off
	s_add_i32 m0, s17, 0x2000
	v_lshl_add_u64 v[152:153], v[162:163], 0, s[70:71]
	global_load_lds_dwordx4 v[152:153], off
	s_barrier
; #define PG8_STAGE(bufoff, gbase, voff) do { _Pragma("unroll") for (int _i = 0; _i < 2; ++_i) \
;         __builtin_amdgcn_global_load_lds((const unsigned*)((const char*)(gbase) + (voff)[_i]), (LAS unsigned*)(lds + (bufoff) + ldsw + _i * 8192), 16, 0, 0); } while (0)
; #define PG8_LDA(dst, b, h) do { _Pragma("unroll") for (int m = 0; m < 4; ++m) _Pragma("unroll") for (int k = 0; k < 2; ++k) dst[m][k] = *(const LAS bf16x8*)(lds + PG8_SA(b, h) + aoff + m * 2048 + k * 1024); } while (0)
; #define PG8_MMA(ai, bj, At, Bt) do { __builtin_amdgcn_s_setprio(1); _Pragma("unroll") for (int m = 0; m < 4; ++m) _Pragma("unroll") for (int n = 0; n < 2; ++n) _Pragma("unroll") for (int k = 0; k < 2; ++k) \
;         acc[ai][bj][m][n] = __builtin_amdgcn_mfma_f32_16x16x32_bf16(Bt[n][k], At[m][k], acc[ai][bj][m][n], 0, 0, 0); __builtin_amdgcn_s_setprio(0); } while (0)
; #define PG8_WAIT_V(n) asm volatile("s_waitcnt vmcnt(" #n ")" ::: "memory")
; #define PG8_WAIT_L(n) asm volatile("s_waitcnt lgkmcnt(" #n ")" ::: "memory")
; #define PG8_BAR __builtin_amdgcn_s_barrier()
; #define PG8_SCHED __builtin_amdgcn_sched_barrier(0)
; template <class Epi>
; DEVI void gemm_phase(LAS unsigned char* lds, const Gemm g, const Epi& E) {
;     ...
;             PG8_BAR; PG8_WAIT_L(0); PG8_MMA(0, 1, At, B1); PG8_BAR;
;             PG8_LDA(At, 1, 1); PG8_STAGE(PG8_SA(1, 0), a3, voffA);
;             PG8_BAR; PG8_WAIT_L(0); PG8_MMA(1, 0, At, B0); PG8_BAR; PG8_SCHED;
;             PG8_STAGE(PG8_SB(1, 1), b3 + hstepB, voffB);
;             PG8_WAIT_V(6); PG8_BAR; PG8_MMA(1, 1, At, B1); PG8_BAR;
	s_waitcnt lgkmcnt(0)
	v_mfma_f32_16x16x32_bf16 v[122:125], v[222:225], v[180:183], v[122:125]
	v_mfma_f32_16x16x32_bf16 v[118:121], v[230:233], v[180:183], v[118:121]
	v_mfma_f32_16x16x32_bf16 v[102:105], v[222:225], v[192:195], v[102:105]
	v_mfma_f32_16x16x32_bf16 v[98:101], v[230:233], v[192:195], v[98:101]
	v_mfma_f32_16x16x32_bf16 v[86:89], v[222:225], v[200:203], v[86:89]
	v_mfma_f32_16x16x32_bf16 v[82:85], v[230:233], v[200:203], v[82:85]
	v_mfma_f32_16x16x32_bf16 v[70:73], v[222:225], v[214:217], v[70:73]
	v_mfma_f32_16x16x32_bf16 v[66:69], v[230:233], v[214:217], v[66:69]
	v_mfma_f32_16x16x32_bf16 v[122:125], v[226:229], v[188:191], v[122:125]
	v_mfma_f32_16x16x32_bf16 v[118:121], v[234:237], v[188:191], v[118:121]
	v_mfma_f32_16x16x32_bf16 v[102:105], v[226:229], v[196:199], v[102:105]
	v_mfma_f32_16x16x32_bf16 v[98:101], v[234:237], v[196:199], v[98:101]
	v_mfma_f32_16x16x32_bf16 v[86:89], v[226:229], v[204:207], v[86:89]
	v_mfma_f32_16x16x32_bf16 v[82:85], v[234:237], v[204:207], v[82:85]
	v_mfma_f32_16x16x32_bf16 v[70:73], v[226:229], v[218:221], v[70:73]
	v_mfma_f32_16x16x32_bf16 v[66:69], v[234:237], v[218:221], v[66:69]
	s_mov_b32 m0, s80
	v_lshl_add_u64 v[152:153], v[164:165], 0, s[70:71]
	s_barrier
	ds_read_b128 v[180:183], v187 offset:49152
	ds_read_b128 v[188:191], v187 offset:50176
	ds_read_b128 v[192:195], v187 offset:51200
	ds_read_b128 v[196:199], v187 offset:52224
	ds_read_b128 v[200:203], v187 offset:53248
	ds_read_b128 v[204:207], v187 offset:54272
	ds_read_b128 v[214:217], v187 offset:55296
	ds_read_b128 v[218:221], v187 offset:56320
	global_load_lds_dwordx4 v[152:153], off
	s_mov_b32 m0, s81
	v_lshl_add_u64 v[152:153], v[208:209], 0, s[70:71]
	global_load_lds_dwordx4 v[152:153], off
	s_barrier
	s_waitcnt lgkmcnt(0)
	v_mfma_f32_16x16x32_bf16 v[62:65], v[114:117], v[180:183], v[62:65]
	v_mfma_f32_16x16x32_bf16 v[58:61], v[130:133], v[180:183], v[58:61]
	v_mfma_f32_16x16x32_bf16 v[46:49], v[114:117], v[192:195], v[46:49]
	v_mfma_f32_16x16x32_bf16 v[42:45], v[130:133], v[192:195], v[42:45]
	v_mfma_f32_16x16x32_bf16 v[30:33], v[114:117], v[200:203], v[30:33]
	v_mfma_f32_16x16x32_bf16 v[26:29], v[130:133], v[200:203], v[26:29]
	v_mfma_f32_16x16x32_bf16 v[14:17], v[114:117], v[214:217], v[14:17]
	v_mfma_f32_16x16x32_bf16 v[10:13], v[130:133], v[214:217], v[10:13]
	v_mfma_f32_16x16x32_bf16 v[62:65], v[126:129], v[188:191], v[62:65]
	v_mfma_f32_16x16x32_bf16 v[58:61], v[176:179], v[188:191], v[58:61]
	v_mfma_f32_16x16x32_bf16 v[46:49], v[126:129], v[196:199], v[46:49]
	v_mfma_f32_16x16x32_bf16 v[42:45], v[176:179], v[196:199], v[42:45]
	v_mfma_f32_16x16x32_bf16 v[30:33], v[126:129], v[204:207], v[30:33]
	v_mfma_f32_16x16x32_bf16 v[26:29], v[176:179], v[204:207], v[26:29]
	v_mfma_f32_16x16x32_bf16 v[14:17], v[126:129], v[218:221], v[14:17]
	v_mfma_f32_16x16x32_bf16 v[10:13], v[176:179], v[218:221], v[10:13]
	s_barrier
	s_add_u32 s14, s14, 0x40080
	s_addc_u32 s15, s15, 0
	s_add_i32 s16, s16, s47
	s_mov_b32 m0, s16
	v_lshl_add_u64 v[114:115], s[14:15], 0, v[8:9]
	global_load_lds_dwordx4 v[114:115], off
	s_add_i32 m0, s16, 0x2000
	v_lshl_add_u64 v[114:115], s[14:15], 0, v[146:147]
	global_load_lds_dwordx4 v[114:115], off
	s_waitcnt vmcnt(6)
	s_barrier
	v_mfma_f32_16x16x32_bf16 v[54:57], v[222:225], v[180:183], v[54:57]
	v_mfma_f32_16x16x32_bf16 v[50:53], v[230:233], v[180:183], v[50:53]
	v_mfma_f32_16x16x32_bf16 v[38:41], v[222:225], v[192:195], v[38:41]
	v_mfma_f32_16x16x32_bf16 v[34:37], v[230:233], v[192:195], v[34:37]
	v_mfma_f32_16x16x32_bf16 v[22:25], v[222:225], v[200:203], v[22:25]
	v_mfma_f32_16x16x32_bf16 v[18:21], v[230:233], v[200:203], v[18:21]
	v_mfma_f32_16x16x32_bf16 v[4:7], v[222:225], v[214:217], v[4:7]
	v_mfma_f32_16x16x32_bf16 v[0:3], v[230:233], v[214:217], v[0:3]
	v_mfma_f32_16x16x32_bf16 v[54:57], v[226:229], v[188:191], v[54:57]
	v_mfma_f32_16x16x32_bf16 v[50:53], v[234:237], v[188:191], v[50:53]
	v_mfma_f32_16x16x32_bf16 v[38:41], v[226:229], v[196:199], v[38:41]
	v_mfma_f32_16x16x32_bf16 v[34:37], v[234:237], v[196:199], v[34:37]
	v_mfma_f32_16x16x32_bf16 v[22:25], v[226:229], v[204:207], v[22:25]
	v_mfma_f32_16x16x32_bf16 v[18:21], v[234:237], v[204:207], v[18:21]
	v_mfma_f32_16x16x32_bf16 v[4:7], v[226:229], v[218:221], v[4:7]
	v_mfma_f32_16x16x32_bf16 v[0:3], v[234:237], v[218:221], v[0:3]
	s_add_i32 s27, s27, 2
	s_add_u32 s12, s12, 0x100
	s_addc_u32 s13, s13, 0
	s_add_u32 s19, s19, 0x100
	s_addc_u32 s26, s26, 0
	s_cmp_gt_u32 s27, 13
	s_barrier

; DEVI size_t gemm_offB(const Gemm& g, const Unit& u) { return (g.split ? (size_t)(u.b >> 2) * g.sB + (size_t)(u.b & 3) * g.sB_lo : (size_t)u.b * g.sB) + (size_t)(u.pm >> g.pmsh) * g.sBpm; }
; #define PG8_STAGE(bufoff, gbase, voff) do { _Pragma("unroll") for (int _i = 0; _i < 2; ++_i) \
;         __builtin_amdgcn_global_load_lds((const unsigned*)((const char*)(gbase) + (voff)[_i]), (LAS unsigned*)(lds + (bufoff) + ldsw + _i * 8192), 16, 0, 0); } while (0)
; #define PG8_LDA(dst, b, h) do { _Pragma("unroll") for (int m = 0; m < 4; ++m) _Pragma("unroll") for (int k = 0; k < 2; ++k) dst[m][k] = *(const LAS bf16x8*)(lds + PG8_SA(b, h) + aoff + m * 2048 + k * 1024); } while (0)
; #define PG8_LDB(dst, b, h) do { _Pragma("unroll") for (int n = 0; n < 2; ++n) _Pragma("unroll") for (int k = 0; k < 2; ++k) dst[n][k] = *(const LAS bf16x8*)(lds + PG8_SB(b, h) + boff + n * 2048 + k * 1024); } while (0)
; #define PG8_WAIT_L(n) asm volatile("s_waitcnt lgkmcnt(" #n ")" ::: "memory")
; #define PG8_BAR __builtin_amdgcn_s_barrier()
; #define PG8_SCHED __builtin_amdgcn_sched_barrier(0)
; template <class Epi>
; DEVI void gemm_phase(LAS unsigned char* lds, const Gemm g, const Epi& E) {
;     ...
;         const bool has_next = unit_next(g, ui + 1, nxt);
;         const char* nA = has_next ? (const char*)g.A + gemm_offA(g, nxt) * 2 + (size_t)nxt.pm * tstepA : cA;
;         const char* nB = has_next ? (const char*)g.Bt + gemm_offB(g, nxt) * 2 + (size_t)nxt.pn * tstepB : cB;
;         for (int t = 0; t < nt; t += 2) {
;             const bool last = (t == nt - 2);
;             const char* a1 = cA + (size_t)(t + 1) * kstep;
;             const char* a2 = last ? nA : cA + (size_t)(t + 2) * kstep; const char* b2 = last ? nB : cB + (size_t)(t + 2) * kstep;
;             const char* a3 = a2 + kstep; const char* b3 = b2 + kstep;
;             PG8_LDB(B0, 0, 0); PG8_SCHED; PG8_LDA(At, 0, 0); PG8_STAGE(PG8_SA(1, 1), a1 + hstepA, voffA);
;             PG8_WAIT_L(8); PG8_BAR; PG8_WAIT_L(0); PG8_MMA(0, 0, At, B0); PG8_BAR; PG8_SCHED;
;             PG8_LDB(B1, 0, 1); PG8_STAGE(PG8_SB(0, 0), b2, voffB);
;             PG8_BAR; PG8_WAIT_L(0); PG8_MMA(0, 1, At, B1); PG8_BAR;
;             PG8_LDA(At, 0, 1); PG8_STAGE(PG8_SA(0, 0), a2, voffA);
;             PG8_BAR; PG8_WAIT_L(0); PG8_MMA(1, 0, At, B0); PG8_BAR; PG8_SCHED;
.LBB0_1416:
	s_ashr_i32 s13, s12, 31
	s_lshl_b64 s[0:1], s[12:13], 19
	v_cmp_lt_i64_e32 vcc, s[16:17], v[168:169]
	s_add_u32 s16, s64, s0
	s_addc_u32 s17, s65, s1
	s_and_b64 s[0:1], vcc, exec
	s_cselect_b32 s0, s17, s69
	s_cselect_b32 s1, s16, s68
	s_ashr_i32 s15, s14, 31
	s_lshl_b64 s[18:19], s[14:15], 19
	v_readlane_b32 s26, v251, 56
	v_readlane_b32 s27, v251, 57
	s_add_u32 s36, s26, s18
	s_addc_u32 s37, s27, s19
	s_and_b64 s[18:19], vcc, exec
	s_cselect_b32 s9, s37, s81
	s_cselect_b32 s13, s36, s80
	s_add_u32 s68, s68, 0x40080
	s_addc_u32 s69, s69, 0
	s_add_u32 s15, s80, 0x100
	s_addc_u32 s18, s81, 0
	s_mov_b32 s19, -2
	s_waitcnt lgkmcnt(0)
	s_nop 0
	s_nop 0
	s_nop 0
	s_nop 0
	s_nop 0
	s_add_u32 s26, s68, 0xfffc0080
	s_addc_u32 s27, s69, -1
	s_add_i32 s38, 0, 0x10000
	v_add_u32_e32 v142, s38, v193
	ds_read_b128 v[130:133], v142
	ds_read_b128 v[134:137], v142 offset:1024
	ds_read_b128 v[138:141], v142 offset:2048
	ds_read_b128 v[142:145], v142 offset:3072
	s_cmp_eq_u32 s19, 12
	s_cselect_b32 s83, s0, s27
	s_cselect_b32 s82, s1, s26
	s_cselect_b32 s81, s9, s18
	s_cselect_b32 s80, s13, s15
	v_lshl_add_u64 v[162:163], s[68:69], 0, v[178:179]
	s_add_i32 m0, s85, 0xc000
	ds_read_b128 v[146:149], v198
	ds_read_b128 v[182:185], v198 offset:1024
	ds_read_b128 v[186:189], v198 offset:2048
	ds_read_b128 v[200:203], v198 offset:3072
	ds_read_b128 v[204:207], v198 offset:4096
	ds_read_b128 v[214:217], v198 offset:5120
	ds_read_b128 v[218:221], v198 offset:6144
	ds_read_b128 v[222:225], v198 offset:7168
	global_load_lds_dwordx4 v[162:163], off
	s_add_i32 m0, s85, 0xe000
	v_lshl_add_u64 v[162:163], s[68:69], 0, v[180:181]
	global_load_lds_dwordx4 v[162:163], off
	s_waitcnt lgkmcnt(8)
	s_barrier
	s_waitcnt lgkmcnt(0)
	v_mfma_f32_16x16x32_bf16 v[126:129], v[130:133], v[146:149], 0
	v_mfma_f32_16x16x32_bf16 v[122:125], v[138:141], v[146:149], 0
	v_mfma_f32_16x16x32_bf16 v[110:113], v[130:133], v[186:189], 0
	v_mfma_f32_16x16x32_bf16 v[106:109], v[138:141], v[186:189], 0
	v_mfma_f32_16x16x32_bf16 v[94:97], v[130:133], v[204:207], 0
	v_mfma_f32_16x16x32_bf16 v[90:93], v[138:141], v[204:207], 0
	v_mfma_f32_16x16x32_bf16 v[78:81], v[130:133], v[218:221], 0
	v_mfma_f32_16x16x32_bf16 v[74:77], v[138:141], v[218:221], 0
	v_mfma_f32_16x16x32_bf16 v[126:129], v[134:137], v[182:185], v[126:129]
	v_mfma_f32_16x16x32_bf16 v[122:125], v[142:145], v[182:185], v[122:125]
	v_mfma_f32_16x16x32_bf16 v[110:113], v[134:137], v[200:203], v[110:113]
	v_mfma_f32_16x16x32_bf16 v[106:109], v[142:145], v[200:203], v[106:109]
	v_mfma_f32_16x16x32_bf16 v[94:97], v[134:137], v[214:217], v[94:97]
	v_mfma_f32_16x16x32_bf16 v[90:93], v[142:145], v[214:217], v[90:93]
	v_mfma_f32_16x16x32_bf16 v[78:81], v[134:137], v[222:225], v[78:81]
	v_mfma_f32_16x16x32_bf16 v[74:77], v[142:145], v[222:225], v[74:77]
	s_barrier
	s_add_i32 s39, 0, 0x14000
	v_add_u32_e32 v162, s39, v193
	s_add_i32 s26, s38, s84
	ds_read_b128 v[226:229], v162
	ds_read_b128 v[230:233], v162 offset:1024
	ds_read_b128 v[234:237], v162 offset:2048
	ds_read_b128 v[238:241], v162 offset:3072
	v_lshl_add_u64 v[162:163], s[80:81], 0, v[8:9]
	s_mov_b32 m0, s26
	v_lshl_add_u64 v[164:165], s[80:81], 0, v[176:177]
	global_load_lds_dwordx4 v[162:163], off
	s_add_i32 m0, s26, 0x2000
	s_nop 0
	global_load_lds_dwordx4 v[164:165], off
	s_barrier
	s_waitcnt lgkmcnt(0)
	v_mfma_f32_16x16x32_bf16 v[118:121], v[226:229], v[146:149], 0
	v_mfma_f32_16x16x32_bf16 v[114:117], v[234:237], v[146:149], 0
	v_mfma_f32_16x16x32_bf16 v[102:105], v[226:229], v[186:189], 0
	v_mfma_f32_16x16x32_bf16 v[98:101], v[234:237], v[186:189], 0
	v_mfma_f32_16x16x32_bf16 v[86:89], v[226:229], v[204:207], 0
	v_mfma_f32_16x16x32_bf16 v[82:85], v[234:237], v[204:207], 0
	v_mfma_f32_16x16x32_bf16 v[70:73], v[226:229], v[218:221], 0
	v_mfma_f32_16x16x32_bf16 v[66:69], v[234:237], v[218:221], 0
	v_mfma_f32_16x16x32_bf16 v[118:121], v[230:233], v[182:185], v[118:121]
	v_mfma_f32_16x16x32_bf16 v[114:117], v[238:241], v[182:185], v[114:117]
	v_mfma_f32_16x16x32_bf16 v[102:105], v[230:233], v[200:203], v[102:105]
	v_mfma_f32_16x16x32_bf16 v[98:101], v[238:241], v[200:203], v[98:101]
	v_mfma_f32_16x16x32_bf16 v[86:89], v[230:233], v[214:217], v[86:89]
	v_mfma_f32_16x16x32_bf16 v[82:85], v[238:241], v[214:217], v[82:85]
	v_mfma_f32_16x16x32_bf16 v[70:73], v[230:233], v[222:225], v[70:73]
	v_mfma_f32_16x16x32_bf16 v[66:69], v[238:241], v[222:225], v[66:69]
	s_mov_b32 m0, s85
	v_lshl_add_u64 v[190:191], s[82:83], 0, v[150:151]
	s_barrier
	ds_read_b128 v[146:149], v198 offset:16384
	ds_read_b128 v[182:185], v198 offset:17408
	ds_read_b128 v[186:189], v198 offset:18432
	ds_read_b128 v[200:203], v198 offset:19456
	ds_read_b128 v[204:207], v198 offset:20480
	ds_read_b128 v[214:217], v198 offset:21504
	ds_read_b128 v[218:221], v198 offset:22528
	ds_read_b128 v[222:225], v198 offset:23552
	global_load_lds_dwordx4 v[190:191], off
	s_mov_b32 m0, s86
	v_lshl_add_u64 v[208:209], s[82:83], 0, v[152:153]
	global_load_lds_dwordx4 v[208:209], off
	s_barrier
	s_waitcnt lgkmcnt(0)
	v_mfma_f32_16x16x32_bf16 v[62:65], v[130:133], v[146:149], 0
	v_mfma_f32_16x16x32_bf16 v[58:61], v[138:141], v[146:149], 0
	v_mfma_f32_16x16x32_bf16 v[46:49], v[130:133], v[186:189], 0
	v_mfma_f32_16x16x32_bf16 v[42:45], v[138:141], v[186:189], 0
	v_mfma_f32_16x16x32_bf16 v[30:33], v[130:133], v[204:207], 0
	v_mfma_f32_16x16x32_bf16 v[26:29], v[138:141], v[204:207], 0
	v_mfma_f32_16x16x32_bf16 v[14:17], v[130:133], v[218:221], 0
	v_mfma_f32_16x16x32_bf16 v[10:13], v[138:141], v[218:221], 0
	v_mfma_f32_16x16x32_bf16 v[62:65], v[134:137], v[182:185], v[62:65]
	v_mfma_f32_16x16x32_bf16 v[58:61], v[142:145], v[182:185], v[58:61]
	v_mfma_f32_16x16x32_bf16 v[46:49], v[134:137], v[200:203], v[46:49]
	v_mfma_f32_16x16x32_bf16 v[42:45], v[142:145], v[200:203], v[42:45]
	v_mfma_f32_16x16x32_bf16 v[30:33], v[134:137], v[214:217], v[30:33]
	v_mfma_f32_16x16x32_bf16 v[26:29], v[142:145], v[214:217], v[26:29]
	v_mfma_f32_16x16x32_bf16 v[14:17], v[134:137], v[222:225], v[14:17]
	v_mfma_f32_16x16x32_bf16 v[10:13], v[142:145], v[222:225], v[10:13]
	s_barrier
; #define PG8_STAGE(bufoff, gbase, voff) do { _Pragma("unroll") for (int _i = 0; _i < 2; ++_i) \
;         __builtin_amdgcn_global_load_lds((const unsigned*)((const char*)(gbase) + (voff)[_i]), (LAS unsigned*)(lds + (bufoff) + ldsw + _i * 8192), 16, 0, 0); } while (0)
; #define PG8_LDA(dst, b, h) do { _Pragma("unroll") for (int m = 0; m < 4; ++m) _Pragma("unroll") for (int k = 0; k < 2; ++k) dst[m][k] = *(const LAS bf16x8*)(lds + PG8_SA(b, h) + aoff + m * 2048 + k * 1024); } while (0)
; #define PG8_LDB(dst, b, h) do { _Pragma("unroll") for (int n = 0; n < 2; ++n) _Pragma("unroll") for (int k = 0; k < 2; ++k) dst[n][k] = *(const LAS bf16x8*)(lds + PG8_SB(b, h) + boff + n * 2048 + k * 1024); } while (0)
; #define PG8_MMA(ai, bj, At, Bt) do { __builtin_amdgcn_s_setprio(1); _Pragma("unroll") for (int m = 0; m < 4; ++m) _Pragma("unroll") for (int n = 0; n < 2; ++n) _Pragma("unroll") for (int k = 0; k < 2; ++k) \
;         acc[ai][bj][m][n] = __builtin_amdgcn_mfma_f32_16x16x32_bf16(Bt[n][k], At[m][k], acc[ai][bj][m][n], 0, 0, 0); __builtin_amdgcn_s_setprio(0); } while (0)
; #define PG8_WAIT_V(n) asm volatile("s_waitcnt vmcnt(" #n ")" ::: "memory")
; #define PG8_WAIT_L(n) asm volatile("s_waitcnt lgkmcnt(" #n ")" ::: "memory")
; #define PG8_BAR __builtin_amdgcn_s_barrier()
; #define PG8_SCHED __builtin_amdgcn_sched_barrier(0)
; template <class Epi>
; DEVI void gemm_phase(LAS unsigned char* lds, const Gemm g, const Epi& E) {
;     ...
;             PG8_STAGE(PG8_SB(0, 1), b2 + hstepB, voffB);
;             PG8_WAIT_V(6); PG8_BAR; PG8_MMA(1, 1, At, B1); PG8_BAR;
;             PG8_LDB(B0, 1, 0); PG8_SCHED; PG8_LDA(At, 1, 0); PG8_STAGE(PG8_SA(0, 1), a2 + hstepA, voffA);
;             PG8_WAIT_L(8); PG8_BAR; PG8_WAIT_L(0); PG8_MMA(0, 0, At, B0); PG8_BAR; PG8_SCHED;
;             PG8_LDB(B1, 1, 1); PG8_STAGE(PG8_SB(1, 0), b3, voffB);
	s_add_u32 s26, s80, 0x40000
	s_addc_u32 s27, s81, 0
	s_add_i32 s38, s39, s84
	s_mov_b32 m0, s38
	v_lshl_add_u64 v[130:131], s[26:27], 0, v[8:9]
	global_load_lds_dwordx4 v[130:131], off
	s_add_i32 m0, s38, 0x2000
	v_lshl_add_u64 v[130:131], s[26:27], 0, v[176:177]
	global_load_lds_dwordx4 v[130:131], off
	s_waitcnt vmcnt(6)
	s_barrier
	v_mfma_f32_16x16x32_bf16 v[54:57], v[226:229], v[146:149], 0
	v_mfma_f32_16x16x32_bf16 v[50:53], v[234:237], v[146:149], 0
	v_mfma_f32_16x16x32_bf16 v[38:41], v[226:229], v[186:189], 0
	v_mfma_f32_16x16x32_bf16 v[34:37], v[234:237], v[186:189], 0
	v_mfma_f32_16x16x32_bf16 v[22:25], v[226:229], v[204:207], 0
	v_mfma_f32_16x16x32_bf16 v[18:21], v[234:237], v[204:207], 0
	v_mfma_f32_16x16x32_bf16 v[4:7], v[226:229], v[218:221], 0
	v_mfma_f32_16x16x32_bf16 v[0:3], v[234:237], v[218:221], 0
	v_mfma_f32_16x16x32_bf16 v[54:57], v[230:233], v[182:185], v[54:57]
	v_mfma_f32_16x16x32_bf16 v[50:53], v[238:241], v[182:185], v[50:53]
	v_mfma_f32_16x16x32_bf16 v[38:41], v[230:233], v[200:203], v[38:41]
	v_mfma_f32_16x16x32_bf16 v[34:37], v[238:241], v[200:203], v[34:37]
	v_mfma_f32_16x16x32_bf16 v[22:25], v[230:233], v[214:217], v[22:25]
	v_mfma_f32_16x16x32_bf16 v[18:21], v[238:241], v[214:217], v[18:21]
	v_mfma_f32_16x16x32_bf16 v[4:7], v[230:233], v[222:225], v[4:7]
	v_mfma_f32_16x16x32_bf16 v[0:3], v[238:241], v[222:225], v[0:3]
	s_add_i32 s38, 0, 0x18000
	v_add_u32_e32 v142, s38, v193
	s_barrier
	ds_read_b128 v[130:133], v142
	ds_read_b128 v[134:137], v142 offset:1024
	ds_read_b128 v[138:141], v142 offset:2048
	ds_read_b128 v[142:145], v142 offset:3072
	s_add_u32 s26, s82, 0x40000
	s_addc_u32 s27, s83, 0
	s_mov_b32 m0, s87
	v_lshl_add_u64 v[226:227], s[26:27], 0, v[150:151]
	ds_read_b128 v[146:149], v198 offset:32768
	ds_read_b128 v[182:185], v198 offset:33792
	ds_read_b128 v[186:189], v198 offset:34816
	ds_read_b128 v[200:203], v198 offset:35840
	ds_read_b128 v[204:207], v198 offset:36864
	ds_read_b128 v[214:217], v198 offset:37888
	ds_read_b128 v[218:221], v198 offset:38912
	ds_read_b128 v[222:225], v198 offset:39936
	global_load_lds_dwordx4 v[226:227], off
	s_mov_b32 m0, s88
	v_lshl_add_u64 v[226:227], s[26:27], 0, v[152:153]
	global_load_lds_dwordx4 v[226:227], off
	s_waitcnt lgkmcnt(8)
	s_barrier
	s_waitcnt lgkmcnt(0)
	v_mfma_f32_16x16x32_bf16 v[126:129], v[130:133], v[146:149], v[126:129]
	v_mfma_f32_16x16x32_bf16 v[122:125], v[138:141], v[146:149], v[122:125]
	v_mfma_f32_16x16x32_bf16 v[110:113], v[130:133], v[186:189], v[110:113]
	v_mfma_f32_16x16x32_bf16 v[106:109], v[138:141], v[186:189], v[106:109]
	v_mfma_f32_16x16x32_bf16 v[94:97], v[130:133], v[204:207], v[94:97]
	v_mfma_f32_16x16x32_bf16 v[90:93], v[138:141], v[204:207], v[90:93]
	v_mfma_f32_16x16x32_bf16 v[78:81], v[130:133], v[218:221], v[78:81]
	v_mfma_f32_16x16x32_bf16 v[74:77], v[138:141], v[218:221], v[74:77]
	v_mfma_f32_16x16x32_bf16 v[126:129], v[134:137], v[182:185], v[126:129]
	v_mfma_f32_16x16x32_bf16 v[122:125], v[142:145], v[182:185], v[122:125]
	v_mfma_f32_16x16x32_bf16 v[110:113], v[134:137], v[200:203], v[110:113]
	v_mfma_f32_16x16x32_bf16 v[106:109], v[142:145], v[200:203], v[106:109]
	v_mfma_f32_16x16x32_bf16 v[94:97], v[134:137], v[214:217], v[94:97]
	v_mfma_f32_16x16x32_bf16 v[90:93], v[142:145], v[214:217], v[90:93]
	v_mfma_f32_16x16x32_bf16 v[78:81], v[134:137], v[222:225], v[78:81]
	v_mfma_f32_16x16x32_bf16 v[74:77], v[142:145], v[222:225], v[74:77]
	s_barrier
	s_add_i32 s39, 0, 0x1c000
	s_add_i32 s26, s38, s84
	v_add_u32_e32 v199, s39, v193
	v_lshl_add_u64 v[162:163], v[162:163], 0, s[70:71]
	s_mov_b32 m0, s26
	ds_read_b128 v[226:229], v199
	ds_read_b128 v[230:233], v199 offset:1024
	ds_read_b128 v[234:237], v199 offset:2048
	ds_read_b128 v[238:241], v199 offset:3072
	global_load_lds_dwordx4 v[162:163], off
	s_add_i32 m0, s26, 0x2000
	v_lshl_add_u64 v[162:163], v[164:165], 0, s[70:71]
	global_load_lds_dwordx4 v[162:163], off
	s_barrier
; #define PG8_STAGE(bufoff, gbase, voff) do { _Pragma("unroll") for (int _i = 0; _i < 2; ++_i) \
;         __builtin_amdgcn_global_load_lds((const unsigned*)((const char*)(gbase) + (voff)[_i]), (LAS unsigned*)(lds + (bufoff) + ldsw + _i * 8192), 16, 0, 0); } while (0)
; #define PG8_LDA(dst, b, h) do { _Pragma("unroll") for (int m = 0; m < 4; ++m) _Pragma("unroll") for (int k = 0; k < 2; ++k) dst[m][k] = *(const LAS bf16x8*)(lds + PG8_SA(b, h) + aoff + m * 2048 + k * 1024); } while (0)
; #define PG8_MMA(ai, bj, At, Bt) do { __builtin_amdgcn_s_setprio(1); _Pragma("unroll") for (int m = 0; m < 4; ++m) _Pragma("unroll") for (int n = 0; n < 2; ++n) _Pragma("unroll") for (int k = 0; k < 2; ++k) \
;         acc[ai][bj][m][n] = __builtin_amdgcn_mfma_f32_16x16x32_bf16(Bt[n][k], At[m][k], acc[ai][bj][m][n], 0, 0, 0); __builtin_amdgcn_s_setprio(0); } while (0)
; #define PG8_WAIT_V(n) asm volatile("s_waitcnt vmcnt(" #n ")" ::: "memory")
; #define PG8_WAIT_L(n) asm volatile("s_waitcnt lgkmcnt(" #n ")" ::: "memory")
; #define PG8_BAR __builtin_amdgcn_s_barrier()
; #define PG8_SCHED __builtin_amdgcn_sched_barrier(0)
; template <class Epi>
; DEVI void gemm_phase(LAS unsigned char* lds, const Gemm g, const Epi& E) {
;     ...
;             PG8_BAR; PG8_WAIT_L(0); PG8_MMA(0, 1, At, B1); PG8_BAR;
;             PG8_LDA(At, 1, 1); PG8_STAGE(PG8_SA(1, 0), a3, voffA);
;             PG8_BAR; PG8_WAIT_L(0); PG8_MMA(1, 0, At, B0); PG8_BAR; PG8_SCHED;
;             PG8_STAGE(PG8_SB(1, 1), b3 + hstepB, voffB);
;             PG8_WAIT_V(6); PG8_BAR; PG8_MMA(1, 1, At, B1); PG8_BAR;
	s_waitcnt lgkmcnt(0)
	v_mfma_f32_16x16x32_bf16 v[118:121], v[226:229], v[146:149], v[118:121]
	v_mfma_f32_16x16x32_bf16 v[114:117], v[234:237], v[146:149], v[114:117]
	v_mfma_f32_16x16x32_bf16 v[102:105], v[226:229], v[186:189], v[102:105]
	v_mfma_f32_16x16x32_bf16 v[98:101], v[234:237], v[186:189], v[98:101]
	v_mfma_f32_16x16x32_bf16 v[86:89], v[226:229], v[204:207], v[86:89]
	v_mfma_f32_16x16x32_bf16 v[82:85], v[234:237], v[204:207], v[82:85]
	v_mfma_f32_16x16x32_bf16 v[70:73], v[226:229], v[218:221], v[70:73]
	v_mfma_f32_16x16x32_bf16 v[66:69], v[234:237], v[218:221], v[66:69]
	v_mfma_f32_16x16x32_bf16 v[118:121], v[230:233], v[182:185], v[118:121]
	v_mfma_f32_16x16x32_bf16 v[114:117], v[238:241], v[182:185], v[114:117]
	v_mfma_f32_16x16x32_bf16 v[102:105], v[230:233], v[200:203], v[102:105]
	v_mfma_f32_16x16x32_bf16 v[98:101], v[238:241], v[200:203], v[98:101]
	v_mfma_f32_16x16x32_bf16 v[86:89], v[230:233], v[214:217], v[86:89]
	v_mfma_f32_16x16x32_bf16 v[82:85], v[238:241], v[214:217], v[82:85]
	v_mfma_f32_16x16x32_bf16 v[70:73], v[230:233], v[222:225], v[70:73]
	v_mfma_f32_16x16x32_bf16 v[66:69], v[238:241], v[222:225], v[66:69]
	s_mov_b32 m0, s89
	v_lshl_add_u64 v[162:163], v[190:191], 0, s[70:71]
	s_barrier
	ds_read_b128 v[146:149], v198 offset:49152
	ds_read_b128 v[182:185], v198 offset:50176
	ds_read_b128 v[186:189], v198 offset:51200
	ds_read_b128 v[200:203], v198 offset:52224
	ds_read_b128 v[204:207], v198 offset:53248
	ds_read_b128 v[214:217], v198 offset:54272
	ds_read_b128 v[218:221], v198 offset:55296
	ds_read_b128 v[222:225], v198 offset:56320
	global_load_lds_dwordx4 v[162:163], off
	s_mov_b32 m0, s90
	v_lshl_add_u64 v[162:163], v[208:209], 0, s[70:71]
	global_load_lds_dwordx4 v[162:163], off
	s_barrier
	s_waitcnt lgkmcnt(0)
	v_mfma_f32_16x16x32_bf16 v[62:65], v[130:133], v[146:149], v[62:65]
	v_mfma_f32_16x16x32_bf16 v[58:61], v[138:141], v[146:149], v[58:61]
	v_mfma_f32_16x16x32_bf16 v[46:49], v[130:133], v[186:189], v[46:49]
	v_mfma_f32_16x16x32_bf16 v[42:45], v[138:141], v[186:189], v[42:45]
	v_mfma_f32_16x16x32_bf16 v[30:33], v[130:133], v[204:207], v[30:33]
	v_mfma_f32_16x16x32_bf16 v[26:29], v[138:141], v[204:207], v[26:29]
	v_mfma_f32_16x16x32_bf16 v[14:17], v[130:133], v[218:221], v[14:17]
	v_mfma_f32_16x16x32_bf16 v[10:13], v[138:141], v[218:221], v[10:13]
	v_mfma_f32_16x16x32_bf16 v[62:65], v[134:137], v[182:185], v[62:65]
	v_mfma_f32_16x16x32_bf16 v[58:61], v[142:145], v[182:185], v[58:61]
	v_mfma_f32_16x16x32_bf16 v[46:49], v[134:137], v[200:203], v[46:49]
	v_mfma_f32_16x16x32_bf16 v[42:45], v[142:145], v[200:203], v[42:45]
	v_mfma_f32_16x16x32_bf16 v[30:33], v[134:137], v[214:217], v[30:33]
	v_mfma_f32_16x16x32_bf16 v[26:29], v[142:145], v[214:217], v[26:29]
	v_mfma_f32_16x16x32_bf16 v[14:17], v[134:137], v[222:225], v[14:17]
	v_mfma_f32_16x16x32_bf16 v[10:13], v[142:145], v[222:225], v[10:13]
	s_barrier
	s_add_u32 s26, s80, 0x40080
	s_addc_u32 s27, s81, 0
	s_add_i32 s38, s39, s84
	s_mov_b32 m0, s38
	v_lshl_add_u64 v[130:131], s[26:27], 0, v[8:9]
	global_load_lds_dwordx4 v[130:131], off
	s_add_i32 m0, s38, 0x2000
	v_lshl_add_u64 v[130:131], s[26:27], 0, v[176:177]
	global_load_lds_dwordx4 v[130:131], off
	s_waitcnt vmcnt(6)
	s_barrier
	v_mfma_f32_16x16x32_bf16 v[54:57], v[226:229], v[146:149], v[54:57]
	v_mfma_f32_16x16x32_bf16 v[50:53], v[234:237], v[146:149], v[50:53]
	v_mfma_f32_16x16x32_bf16 v[38:41], v[226:229], v[186:189], v[38:41]
	v_mfma_f32_16x16x32_bf16 v[34:37], v[234:237], v[186:189], v[34:37]
	v_mfma_f32_16x16x32_bf16 v[22:25], v[226:229], v[204:207], v[22:25]
	v_mfma_f32_16x16x32_bf16 v[18:21], v[234:237], v[204:207], v[18:21]
	v_mfma_f32_16x16x32_bf16 v[4:7], v[226:229], v[218:221], v[4:7]
	v_mfma_f32_16x16x32_bf16 v[0:3], v[234:237], v[218:221], v[0:3]
	v_mfma_f32_16x16x32_bf16 v[54:57], v[230:233], v[182:185], v[54:57]
	v_mfma_f32_16x16x32_bf16 v[50:53], v[238:241], v[182:185], v[50:53]
	v_mfma_f32_16x16x32_bf16 v[38:41], v[230:233], v[200:203], v[38:41]
	v_mfma_f32_16x16x32_bf16 v[34:37], v[238:241], v[200:203], v[34:37]
	v_mfma_f32_16x16x32_bf16 v[22:25], v[230:233], v[214:217], v[22:25]
	v_mfma_f32_16x16x32_bf16 v[18:21], v[238:241], v[214:217], v[18:21]
	v_mfma_f32_16x16x32_bf16 v[4:7], v[230:233], v[222:225], v[4:7]
	v_mfma_f32_16x16x32_bf16 v[0:3], v[238:241], v[222:225], v[0:3]
	s_add_i32 s19, s19, 2
	s_add_u32 s68, s68, 0x100
	s_addc_u32 s69, s69, 0
	s_add_u32 s15, s15, 0x100
	s_addc_u32 s18, s18, 0
	s_cmp_gt_u32 s19, 13
	s_barrier

; DEVI size_t gemm_offB(const Gemm& g, const Unit& u) { return (g.split ? (size_t)(u.b >> 2) * g.sB + (size_t)(u.b & 3) * g.sB_lo : (size_t)u.b * g.sB) + (size_t)(u.pm >> g.pmsh) * g.sBpm; }
; #define PG8_STAGE(bufoff, gbase, voff) do { _Pragma("unroll") for (int _i = 0; _i < 2; ++_i) \
;         __builtin_amdgcn_global_load_lds((const unsigned*)((const char*)(gbase) + (voff)[_i]), (LAS unsigned*)(lds + (bufoff) + ldsw + _i * 8192), 16, 0, 0); } while (0)
; #define PG8_LDA(dst, b, h) do { _Pragma("unroll") for (int m = 0; m < 4; ++m) _Pragma("unroll") for (int k = 0; k < 2; ++k) dst[m][k] = *(const LAS bf16x8*)(lds + PG8_SA(b, h) + aoff + m * 2048 + k * 1024); } while (0)
; #define PG8_LDB(dst, b, h) do { _Pragma("unroll") for (int n = 0; n < 2; ++n) _Pragma("unroll") for (int k = 0; k < 2; ++k) dst[n][k] = *(const LAS bf16x8*)(lds + PG8_SB(b, h) + boff + n * 2048 + k * 1024); } while (0)
; #define PG8_WAIT_L(n) asm volatile("s_waitcnt lgkmcnt(" #n ")" ::: "memory")
; #define PG8_BAR __builtin_amdgcn_s_barrier()
; #define PG8_SCHED __builtin_amdgcn_sched_barrier(0)
; template <class Epi>
; DEVI void gemm_phase(LAS unsigned char* lds, const Gemm g, const Epi& E) {
;     ...
;         const bool has_next = unit_next(g, ui + 1, nxt);
;         const char* nA = has_next ? (const char*)g.A + gemm_offA(g, nxt) * 2 + (size_t)nxt.pm * tstepA : cA;
;         const char* nB = has_next ? (const char*)g.Bt + gemm_offB(g, nxt) * 2 + (size_t)nxt.pn * tstepB : cB;
;         for (int t = 0; t < nt; t += 2) {
;             const bool last = (t == nt - 2);
;             const char* a1 = cA + (size_t)(t + 1) * kstep;
;             const char* a2 = last ? nA : cA + (size_t)(t + 2) * kstep; const char* b2 = last ? nB : cB + (size_t)(t + 2) * kstep;
;             const char* a3 = a2 + kstep; const char* b3 = b2 + kstep;
;             PG8_LDB(B0, 0, 0); PG8_SCHED; PG8_LDA(At, 0, 0); PG8_STAGE(PG8_SA(1, 1), a1 + hstepA, voffA);
;             PG8_WAIT_L(8); PG8_BAR; PG8_WAIT_L(0); PG8_MMA(0, 0, At, B0); PG8_BAR; PG8_SCHED;
;             PG8_LDB(B1, 0, 1); PG8_STAGE(PG8_SB(0, 0), b2, voffB);
;             PG8_BAR; PG8_WAIT_L(0); PG8_MMA(0, 1, At, B1); PG8_BAR;
;             PG8_LDA(At, 0, 1); PG8_STAGE(PG8_SA(0, 0), a2, voffA);
;             PG8_BAR; PG8_WAIT_L(0); PG8_MMA(1, 0, At, B0); PG8_BAR; PG8_SCHED;
.LBB0_1506:
	s_ashr_i32 s13, s12, 31
	s_lshl_b64 s[0:1], s[12:13], 19
	s_add_u32 s16, s28, s0
	s_addc_u32 s17, s29, s1
	s_and_b64 s[0:1], s[6:7], exec
	s_cselect_b32 s0, s17, s69
	s_cselect_b32 s1, s16, s68
	s_add_u32 s6, s68, 0x40080
	s_addc_u32 s7, s69, 0
	s_add_u32 s11, s78, 0x100
	s_addc_u32 s13, s79, 0
	s_mov_b32 s18, -2
	s_nop 0
	s_nop 0
	s_nop 0
	s_nop 0
	s_nop 0
	s_nop 0
	s_nop 0
	s_nop 0
	s_nop 0
	s_nop 0
	s_nop 0
	s_nop 0
	s_nop 0
	s_add_u32 s19, s6, 0xfffc0080
	s_addc_u32 s26, s7, -1
	s_add_i32 s27, 0, 0x10000
	v_add_u32_e32 v142, s27, v199
	ds_read_b128 v[130:133], v142
	ds_read_b128 v[134:137], v142 offset:1024
	ds_read_b128 v[138:141], v142 offset:2048
	ds_read_b128 v[142:145], v142 offset:3072
	s_cmp_eq_u32 s18, 12
	s_cselect_b32 s79, s0, s26
	s_cselect_b32 s78, s1, s19
	s_cselect_b32 s69, s15, s13
	s_cselect_b32 s68, s14, s11
	v_lshl_add_u64 v[162:163], s[6:7], 0, v[182:183]
	s_add_i32 m0, s37, 0xc000
	ds_read_b128 v[146:149], v202
	ds_read_b128 v[150:153], v202 offset:1024
	ds_read_b128 v[186:189], v202 offset:2048
	ds_read_b128 v[190:193], v202 offset:3072
	ds_read_b128 v[194:197], v202 offset:4096
	ds_read_b128 v[204:207], v202 offset:5120
	ds_read_b128 v[214:217], v202 offset:6144
	ds_read_b128 v[218:221], v202 offset:7168
	global_load_lds_dwordx4 v[162:163], off
	s_add_i32 m0, s37, 0xe000
	v_lshl_add_u64 v[162:163], s[6:7], 0, v[184:185]
	global_load_lds_dwordx4 v[162:163], off
	s_waitcnt lgkmcnt(8)
	s_barrier
	s_waitcnt lgkmcnt(0)
	v_mfma_f32_16x16x32_bf16 v[126:129], v[130:133], v[146:149], 0
	v_mfma_f32_16x16x32_bf16 v[122:125], v[138:141], v[146:149], 0
	v_mfma_f32_16x16x32_bf16 v[110:113], v[130:133], v[186:189], 0
	v_mfma_f32_16x16x32_bf16 v[106:109], v[138:141], v[186:189], 0
	v_mfma_f32_16x16x32_bf16 v[94:97], v[130:133], v[194:197], 0
	v_mfma_f32_16x16x32_bf16 v[90:93], v[138:141], v[194:197], 0
	v_mfma_f32_16x16x32_bf16 v[78:81], v[130:133], v[214:217], 0
	v_mfma_f32_16x16x32_bf16 v[74:77], v[138:141], v[214:217], 0
	v_mfma_f32_16x16x32_bf16 v[126:129], v[134:137], v[150:153], v[126:129]
	v_mfma_f32_16x16x32_bf16 v[122:125], v[142:145], v[150:153], v[122:125]
	v_mfma_f32_16x16x32_bf16 v[110:113], v[134:137], v[190:193], v[110:113]
	v_mfma_f32_16x16x32_bf16 v[106:109], v[142:145], v[190:193], v[106:109]
	v_mfma_f32_16x16x32_bf16 v[94:97], v[134:137], v[204:207], v[94:97]
	v_mfma_f32_16x16x32_bf16 v[90:93], v[142:145], v[204:207], v[90:93]
	v_mfma_f32_16x16x32_bf16 v[78:81], v[134:137], v[218:221], v[78:81]
	v_mfma_f32_16x16x32_bf16 v[74:77], v[142:145], v[218:221], v[74:77]
	s_barrier
	s_add_i32 s19, 0, 0x14000
	v_add_u32_e32 v162, s19, v199
	s_add_i32 s26, s27, s80
	ds_read_b128 v[222:225], v162
	ds_read_b128 v[226:229], v162 offset:1024
	ds_read_b128 v[230:233], v162 offset:2048
	ds_read_b128 v[234:237], v162 offset:3072
	v_lshl_add_u64 v[162:163], s[68:69], 0, v[8:9]
	s_mov_b32 m0, s26
	v_lshl_add_u64 v[164:165], s[68:69], 0, v[180:181]
	global_load_lds_dwordx4 v[162:163], off
	s_add_i32 m0, s26, 0x2000
	s_nop 0
	global_load_lds_dwordx4 v[164:165], off
	s_barrier
	s_waitcnt lgkmcnt(0)
	v_mfma_f32_16x16x32_bf16 v[118:121], v[222:225], v[146:149], 0
	v_mfma_f32_16x16x32_bf16 v[114:117], v[230:233], v[146:149], 0
	v_mfma_f32_16x16x32_bf16 v[102:105], v[222:225], v[186:189], 0
	v_mfma_f32_16x16x32_bf16 v[98:101], v[230:233], v[186:189], 0
	v_mfma_f32_16x16x32_bf16 v[86:89], v[222:225], v[194:197], 0
	v_mfma_f32_16x16x32_bf16 v[82:85], v[230:233], v[194:197], 0
	v_mfma_f32_16x16x32_bf16 v[70:73], v[222:225], v[214:217], 0
	v_mfma_f32_16x16x32_bf16 v[62:65], v[230:233], v[214:217], 0
	v_mfma_f32_16x16x32_bf16 v[118:121], v[226:229], v[150:153], v[118:121]
	v_mfma_f32_16x16x32_bf16 v[114:117], v[234:237], v[150:153], v[114:117]
	v_mfma_f32_16x16x32_bf16 v[102:105], v[226:229], v[190:193], v[102:105]
	v_mfma_f32_16x16x32_bf16 v[98:101], v[234:237], v[190:193], v[98:101]
	v_mfma_f32_16x16x32_bf16 v[86:89], v[226:229], v[204:207], v[86:89]
	v_mfma_f32_16x16x32_bf16 v[82:85], v[234:237], v[204:207], v[82:85]
	v_mfma_f32_16x16x32_bf16 v[70:73], v[226:229], v[218:221], v[70:73]
	v_mfma_f32_16x16x32_bf16 v[62:65], v[234:237], v[218:221], v[62:65]
	s_mov_b32 m0, s37
	v_lshl_add_u64 v[208:209], s[78:79], 0, v[176:177]
	s_barrier
	ds_read_b128 v[146:149], v202 offset:16384
	ds_read_b128 v[150:153], v202 offset:17408
	ds_read_b128 v[186:189], v202 offset:18432
	ds_read_b128 v[190:193], v202 offset:19456
	ds_read_b128 v[194:197], v202 offset:20480
	ds_read_b128 v[204:207], v202 offset:21504
	ds_read_b128 v[214:217], v202 offset:22528
	ds_read_b128 v[218:221], v202 offset:23552
	global_load_lds_dwordx4 v[208:209], off
	s_mov_b32 m0, s47
	v_lshl_add_u64 v[238:239], s[78:79], 0, v[178:179]
	global_load_lds_dwordx4 v[238:239], off
	s_barrier
	s_waitcnt lgkmcnt(0)
	v_mfma_f32_16x16x32_bf16 v[66:69], v[130:133], v[146:149], 0
	v_mfma_f32_16x16x32_bf16 v[54:57], v[138:141], v[146:149], 0
	v_mfma_f32_16x16x32_bf16 v[46:49], v[130:133], v[186:189], 0
	v_mfma_f32_16x16x32_bf16 v[38:41], v[138:141], v[186:189], 0
	v_mfma_f32_16x16x32_bf16 v[30:33], v[130:133], v[194:197], 0
	v_mfma_f32_16x16x32_bf16 v[22:25], v[138:141], v[194:197], 0
	v_mfma_f32_16x16x32_bf16 v[14:17], v[130:133], v[214:217], 0
	v_mfma_f32_16x16x32_bf16 v[4:7], v[138:141], v[214:217], 0
	v_mfma_f32_16x16x32_bf16 v[66:69], v[134:137], v[150:153], v[66:69]
	v_mfma_f32_16x16x32_bf16 v[54:57], v[142:145], v[150:153], v[54:57]
	v_mfma_f32_16x16x32_bf16 v[46:49], v[134:137], v[190:193], v[46:49]
	v_mfma_f32_16x16x32_bf16 v[38:41], v[142:145], v[190:193], v[38:41]
	v_mfma_f32_16x16x32_bf16 v[30:33], v[134:137], v[204:207], v[30:33]
	v_mfma_f32_16x16x32_bf16 v[22:25], v[142:145], v[204:207], v[22:25]
	v_mfma_f32_16x16x32_bf16 v[14:17], v[134:137], v[218:221], v[14:17]
	v_mfma_f32_16x16x32_bf16 v[4:7], v[142:145], v[218:221], v[4:7]
	s_barrier
; #define PG8_STAGE(bufoff, gbase, voff) do { _Pragma("unroll") for (int _i = 0; _i < 2; ++_i) \
;         __builtin_amdgcn_global_load_lds((const unsigned*)((const char*)(gbase) + (voff)[_i]), (LAS unsigned*)(lds + (bufoff) + ldsw + _i * 8192), 16, 0, 0); } while (0)
; #define PG8_LDA(dst, b, h) do { _Pragma("unroll") for (int m = 0; m < 4; ++m) _Pragma("unroll") for (int k = 0; k < 2; ++k) dst[m][k] = *(const LAS bf16x8*)(lds + PG8_SA(b, h) + aoff + m * 2048 + k * 1024); } while (0)
; #define PG8_LDB(dst, b, h) do { _Pragma("unroll") for (int n = 0; n < 2; ++n) _Pragma("unroll") for (int k = 0; k < 2; ++k) dst[n][k] = *(const LAS bf16x8*)(lds + PG8_SB(b, h) + boff + n * 2048 + k * 1024); } while (0)
; #define PG8_MMA(ai, bj, At, Bt) do { __builtin_amdgcn_s_setprio(1); _Pragma("unroll") for (int m = 0; m < 4; ++m) _Pragma("unroll") for (int n = 0; n < 2; ++n) _Pragma("unroll") for (int k = 0; k < 2; ++k) \
;         acc[ai][bj][m][n] = __builtin_amdgcn_mfma_f32_16x16x32_bf16(Bt[n][k], At[m][k], acc[ai][bj][m][n], 0, 0, 0); __builtin_amdgcn_s_setprio(0); } while (0)
; #define PG8_WAIT_V(n) asm volatile("s_waitcnt vmcnt(" #n ")" ::: "memory")
; #define PG8_WAIT_L(n) asm volatile("s_waitcnt lgkmcnt(" #n ")" ::: "memory")
; #define PG8_BAR __builtin_amdgcn_s_barrier()
; #define PG8_SCHED __builtin_amdgcn_sched_barrier(0)
; template <class Epi>
; DEVI void gemm_phase(LAS unsigned char* lds, const Gemm g, const Epi& E) {
;     ...
;             PG8_STAGE(PG8_SB(0, 1), b2 + hstepB, voffB);
;             PG8_WAIT_V(6); PG8_BAR; PG8_MMA(1, 1, At, B1); PG8_BAR;
;             PG8_LDB(B0, 1, 0); PG8_SCHED; PG8_LDA(At, 1, 0); PG8_STAGE(PG8_SA(0, 1), a2 + hstepA, voffA);
;             PG8_WAIT_L(8); PG8_BAR; PG8_WAIT_L(0); PG8_MMA(0, 0, At, B0); PG8_BAR; PG8_SCHED;
;             PG8_LDB(B1, 1, 1); PG8_STAGE(PG8_SB(1, 0), b3, voffB);
	s_add_u32 s26, s68, 0x40000
	s_addc_u32 s27, s69, 0
	s_add_i32 s19, s19, s80
	s_mov_b32 m0, s19
	v_lshl_add_u64 v[130:131], s[26:27], 0, v[8:9]
	global_load_lds_dwordx4 v[130:131], off
	s_add_i32 m0, s19, 0x2000
	v_lshl_add_u64 v[130:131], s[26:27], 0, v[180:181]
	global_load_lds_dwordx4 v[130:131], off
	s_waitcnt vmcnt(6)
	s_barrier
	v_mfma_f32_16x16x32_bf16 v[58:61], v[222:225], v[146:149], 0
	v_mfma_f32_16x16x32_bf16 v[50:53], v[230:233], v[146:149], 0
	v_mfma_f32_16x16x32_bf16 v[42:45], v[222:225], v[186:189], 0
	v_mfma_f32_16x16x32_bf16 v[34:37], v[230:233], v[186:189], 0
	v_mfma_f32_16x16x32_bf16 v[26:29], v[222:225], v[194:197], 0
	v_mfma_f32_16x16x32_bf16 v[18:21], v[230:233], v[194:197], 0
	v_mfma_f32_16x16x32_bf16 v[10:13], v[222:225], v[214:217], 0
	v_mfma_f32_16x16x32_bf16 v[0:3], v[230:233], v[214:217], 0
	v_mfma_f32_16x16x32_bf16 v[58:61], v[226:229], v[150:153], v[58:61]
	v_mfma_f32_16x16x32_bf16 v[50:53], v[234:237], v[150:153], v[50:53]
	v_mfma_f32_16x16x32_bf16 v[42:45], v[226:229], v[190:193], v[42:45]
	v_mfma_f32_16x16x32_bf16 v[34:37], v[234:237], v[190:193], v[34:37]
	v_mfma_f32_16x16x32_bf16 v[26:29], v[226:229], v[204:207], v[26:29]
	v_mfma_f32_16x16x32_bf16 v[18:21], v[234:237], v[204:207], v[18:21]
	v_mfma_f32_16x16x32_bf16 v[10:13], v[226:229], v[218:221], v[10:13]
	v_mfma_f32_16x16x32_bf16 v[0:3], v[234:237], v[218:221], v[0:3]
	s_add_i32 s19, 0, 0x18000
	v_add_u32_e32 v142, s19, v199
	s_barrier
	ds_read_b128 v[130:133], v142
	ds_read_b128 v[134:137], v142 offset:1024
	ds_read_b128 v[138:141], v142 offset:2048
	ds_read_b128 v[142:145], v142 offset:3072
	s_add_u32 s26, s78, 0x40000
	s_addc_u32 s27, s79, 0
	s_mov_b32 m0, s81
	v_lshl_add_u64 v[222:223], s[26:27], 0, v[176:177]
	ds_read_b128 v[146:149], v202 offset:32768
	ds_read_b128 v[150:153], v202 offset:33792
	ds_read_b128 v[186:189], v202 offset:34816
	ds_read_b128 v[190:193], v202 offset:35840
	ds_read_b128 v[194:197], v202 offset:36864
	ds_read_b128 v[204:207], v202 offset:37888
	ds_read_b128 v[214:217], v202 offset:38912
	ds_read_b128 v[218:221], v202 offset:39936
	global_load_lds_dwordx4 v[222:223], off
	s_mov_b32 m0, s82
	v_lshl_add_u64 v[222:223], s[26:27], 0, v[178:179]
	global_load_lds_dwordx4 v[222:223], off
	s_waitcnt lgkmcnt(8)
	s_barrier
	s_waitcnt lgkmcnt(0)
	v_mfma_f32_16x16x32_bf16 v[126:129], v[130:133], v[146:149], v[126:129]
	v_mfma_f32_16x16x32_bf16 v[122:125], v[138:141], v[146:149], v[122:125]
	v_mfma_f32_16x16x32_bf16 v[110:113], v[130:133], v[186:189], v[110:113]
	v_mfma_f32_16x16x32_bf16 v[106:109], v[138:141], v[186:189], v[106:109]
	v_mfma_f32_16x16x32_bf16 v[94:97], v[130:133], v[194:197], v[94:97]
	v_mfma_f32_16x16x32_bf16 v[90:93], v[138:141], v[194:197], v[90:93]
	v_mfma_f32_16x16x32_bf16 v[78:81], v[130:133], v[214:217], v[78:81]
	v_mfma_f32_16x16x32_bf16 v[74:77], v[138:141], v[214:217], v[74:77]
	v_mfma_f32_16x16x32_bf16 v[126:129], v[134:137], v[150:153], v[126:129]
	v_mfma_f32_16x16x32_bf16 v[122:125], v[142:145], v[150:153], v[122:125]
	v_mfma_f32_16x16x32_bf16 v[110:113], v[134:137], v[190:193], v[110:113]
	v_mfma_f32_16x16x32_bf16 v[106:109], v[142:145], v[190:193], v[106:109]
	v_mfma_f32_16x16x32_bf16 v[94:97], v[134:137], v[204:207], v[94:97]
	v_mfma_f32_16x16x32_bf16 v[90:93], v[142:145], v[204:207], v[90:93]
	v_mfma_f32_16x16x32_bf16 v[78:81], v[134:137], v[218:221], v[78:81]
	v_mfma_f32_16x16x32_bf16 v[74:77], v[142:145], v[218:221], v[74:77]
	s_barrier
	s_add_i32 s38, 0, 0x1c000
	s_add_i32 s19, s19, s80
	v_add_u32_e32 v213, s38, v199
	v_lshl_add_u64 v[162:163], v[162:163], 0, s[70:71]
	s_mov_b32 m0, s19
	ds_read_b128 v[222:225], v213
	ds_read_b128 v[226:229], v213 offset:1024
	ds_read_b128 v[230:233], v213 offset:2048
	ds_read_b128 v[234:237], v213 offset:3072
	global_load_lds_dwordx4 v[162:163], off
	s_add_i32 m0, s19, 0x2000
	v_lshl_add_u64 v[162:163], v[164:165], 0, s[70:71]
	global_load_lds_dwordx4 v[162:163], off
	s_barrier
; #define PG8_STAGE(bufoff, gbase, voff) do { _Pragma("unroll") for (int _i = 0; _i < 2; ++_i) \
;         __builtin_amdgcn_global_load_lds((const unsigned*)((const char*)(gbase) + (voff)[_i]), (LAS unsigned*)(lds + (bufoff) + ldsw + _i * 8192), 16, 0, 0); } while (0)
; #define PG8_LDA(dst, b, h) do { _Pragma("unroll") for (int m = 0; m < 4; ++m) _Pragma("unroll") for (int k = 0; k < 2; ++k) dst[m][k] = *(const LAS bf16x8*)(lds + PG8_SA(b, h) + aoff + m * 2048 + k * 1024); } while (0)
; #define PG8_MMA(ai, bj, At, Bt) do { __builtin_amdgcn_s_setprio(1); _Pragma("unroll") for (int m = 0; m < 4; ++m) _Pragma("unroll") for (int n = 0; n < 2; ++n) _Pragma("unroll") for (int k = 0; k < 2; ++k) \
;         acc[ai][bj][m][n] = __builtin_amdgcn_mfma_f32_16x16x32_bf16(Bt[n][k], At[m][k], acc[ai][bj][m][n], 0, 0, 0); __builtin_amdgcn_s_setprio(0); } while (0)
; #define PG8_WAIT_V(n) asm volatile("s_waitcnt vmcnt(" #n ")" ::: "memory")
; #define PG8_WAIT_L(n) asm volatile("s_waitcnt lgkmcnt(" #n ")" ::: "memory")
; #define PG8_BAR __builtin_amdgcn_s_barrier()
; #define PG8_SCHED __builtin_amdgcn_sched_barrier(0)
; template <class Epi>
; DEVI void gemm_phase(LAS unsigned char* lds, const Gemm g, const Epi& E) {
;     ...
;             PG8_BAR; PG8_WAIT_L(0); PG8_MMA(0, 1, At, B1); PG8_BAR;
;             PG8_LDA(At, 1, 1); PG8_STAGE(PG8_SA(1, 0), a3, voffA);
;             PG8_BAR; PG8_WAIT_L(0); PG8_MMA(1, 0, At, B0); PG8_BAR; PG8_SCHED;
;             PG8_STAGE(PG8_SB(1, 1), b3 + hstepB, voffB);
;             PG8_WAIT_V(6); PG8_BAR; PG8_MMA(1, 1, At, B1); PG8_BAR;
	s_waitcnt lgkmcnt(0)
	v_mfma_f32_16x16x32_bf16 v[118:121], v[222:225], v[146:149], v[118:121]
	v_mfma_f32_16x16x32_bf16 v[114:117], v[230:233], v[146:149], v[114:117]
	v_mfma_f32_16x16x32_bf16 v[102:105], v[222:225], v[186:189], v[102:105]
	v_mfma_f32_16x16x32_bf16 v[98:101], v[230:233], v[186:189], v[98:101]
	v_mfma_f32_16x16x32_bf16 v[86:89], v[222:225], v[194:197], v[86:89]
	v_mfma_f32_16x16x32_bf16 v[82:85], v[230:233], v[194:197], v[82:85]
	v_mfma_f32_16x16x32_bf16 v[70:73], v[222:225], v[214:217], v[70:73]
	v_mfma_f32_16x16x32_bf16 v[62:65], v[230:233], v[214:217], v[62:65]
	v_mfma_f32_16x16x32_bf16 v[118:121], v[226:229], v[150:153], v[118:121]
	v_mfma_f32_16x16x32_bf16 v[114:117], v[234:237], v[150:153], v[114:117]
	v_mfma_f32_16x16x32_bf16 v[102:105], v[226:229], v[190:193], v[102:105]
	v_mfma_f32_16x16x32_bf16 v[98:101], v[234:237], v[190:193], v[98:101]
	v_mfma_f32_16x16x32_bf16 v[86:89], v[226:229], v[204:207], v[86:89]
	v_mfma_f32_16x16x32_bf16 v[82:85], v[234:237], v[204:207], v[82:85]
	v_mfma_f32_16x16x32_bf16 v[70:73], v[226:229], v[218:221], v[70:73]
	v_mfma_f32_16x16x32_bf16 v[62:65], v[234:237], v[218:221], v[62:65]
	s_mov_b32 m0, s83
	v_lshl_add_u64 v[162:163], v[208:209], 0, s[70:71]
	s_barrier
	ds_read_b128 v[146:149], v202 offset:49152
	ds_read_b128 v[150:153], v202 offset:50176
	ds_read_b128 v[186:189], v202 offset:51200
	ds_read_b128 v[190:193], v202 offset:52224
	ds_read_b128 v[194:197], v202 offset:53248
	ds_read_b128 v[204:207], v202 offset:54272
	ds_read_b128 v[214:217], v202 offset:55296
	ds_read_b128 v[218:221], v202 offset:56320
	global_load_lds_dwordx4 v[162:163], off
	s_mov_b32 m0, s84
	v_lshl_add_u64 v[162:163], v[238:239], 0, s[70:71]
	global_load_lds_dwordx4 v[162:163], off
	s_barrier
	s_waitcnt lgkmcnt(0)
	v_mfma_f32_16x16x32_bf16 v[66:69], v[130:133], v[146:149], v[66:69]
	v_mfma_f32_16x16x32_bf16 v[54:57], v[138:141], v[146:149], v[54:57]
	v_mfma_f32_16x16x32_bf16 v[46:49], v[130:133], v[186:189], v[46:49]
	v_mfma_f32_16x16x32_bf16 v[38:41], v[138:141], v[186:189], v[38:41]
	v_mfma_f32_16x16x32_bf16 v[30:33], v[130:133], v[194:197], v[30:33]
	v_mfma_f32_16x16x32_bf16 v[22:25], v[138:141], v[194:197], v[22:25]
	v_mfma_f32_16x16x32_bf16 v[14:17], v[130:133], v[214:217], v[14:17]
	v_mfma_f32_16x16x32_bf16 v[4:7], v[138:141], v[214:217], v[4:7]
	v_mfma_f32_16x16x32_bf16 v[66:69], v[134:137], v[150:153], v[66:69]
	v_mfma_f32_16x16x32_bf16 v[54:57], v[142:145], v[150:153], v[54:57]
	v_mfma_f32_16x16x32_bf16 v[46:49], v[134:137], v[190:193], v[46:49]
	v_mfma_f32_16x16x32_bf16 v[38:41], v[142:145], v[190:193], v[38:41]
	v_mfma_f32_16x16x32_bf16 v[30:33], v[134:137], v[204:207], v[30:33]
	v_mfma_f32_16x16x32_bf16 v[22:25], v[142:145], v[204:207], v[22:25]
	v_mfma_f32_16x16x32_bf16 v[14:17], v[134:137], v[218:221], v[14:17]
	v_mfma_f32_16x16x32_bf16 v[4:7], v[142:145], v[218:221], v[4:7]
	s_barrier
	s_add_u32 s26, s68, 0x40080
	s_addc_u32 s27, s69, 0
	s_add_i32 s19, s38, s80
	s_mov_b32 m0, s19
	v_lshl_add_u64 v[130:131], s[26:27], 0, v[8:9]
	global_load_lds_dwordx4 v[130:131], off
	s_add_i32 m0, s19, 0x2000
	v_lshl_add_u64 v[130:131], s[26:27], 0, v[180:181]
	global_load_lds_dwordx4 v[130:131], off
	s_waitcnt vmcnt(6)
	s_barrier
	v_mfma_f32_16x16x32_bf16 v[58:61], v[222:225], v[146:149], v[58:61]
	v_mfma_f32_16x16x32_bf16 v[50:53], v[230:233], v[146:149], v[50:53]
	v_mfma_f32_16x16x32_bf16 v[42:45], v[222:225], v[186:189], v[42:45]
	v_mfma_f32_16x16x32_bf16 v[34:37], v[230:233], v[186:189], v[34:37]
	v_mfma_f32_16x16x32_bf16 v[26:29], v[222:225], v[194:197], v[26:29]
	v_mfma_f32_16x16x32_bf16 v[18:21], v[230:233], v[194:197], v[18:21]
	v_mfma_f32_16x16x32_bf16 v[10:13], v[222:225], v[214:217], v[10:13]
	v_mfma_f32_16x16x32_bf16 v[0:3], v[230:233], v[214:217], v[0:3]
	v_mfma_f32_16x16x32_bf16 v[58:61], v[226:229], v[150:153], v[58:61]
	v_mfma_f32_16x16x32_bf16 v[50:53], v[234:237], v[150:153], v[50:53]
	v_mfma_f32_16x16x32_bf16 v[42:45], v[226:229], v[190:193], v[42:45]
	v_mfma_f32_16x16x32_bf16 v[34:37], v[234:237], v[190:193], v[34:37]
	v_mfma_f32_16x16x32_bf16 v[26:29], v[226:229], v[204:207], v[26:29]
	v_mfma_f32_16x16x32_bf16 v[18:21], v[234:237], v[204:207], v[18:21]
	v_mfma_f32_16x16x32_bf16 v[10:13], v[226:229], v[218:221], v[10:13]
	v_mfma_f32_16x16x32_bf16 v[0:3], v[234:237], v[218:221], v[0:3]
	s_add_i32 s18, s18, 2
	s_add_u32 s6, s6, 0x100
	s_addc_u32 s7, s7, 0
	s_add_u32 s11, s11, 0x100
	s_addc_u32 s13, s13, 0
	s_cmp_gt_u32 s18, 13
	s_barrier

; DEVI size_t gemm_offB(const Gemm& g, const Unit& u) { return (g.split ? (size_t)(u.b >> 2) * g.sB + (size_t)(u.b & 3) * g.sB_lo : (size_t)u.b * g.sB) + (size_t)(u.pm >> g.pmsh) * g.sBpm; }
; #define PG8_STAGE(bufoff, gbase, voff) do { _Pragma("unroll") for (int _i = 0; _i < 2; ++_i) \
;         __builtin_amdgcn_global_load_lds((const unsigned*)((const char*)(gbase) + (voff)[_i]), (LAS unsigned*)(lds + (bufoff) + ldsw + _i * 8192), 16, 0, 0); } while (0)
; #define PG8_LDA(dst, b, h) do { _Pragma("unroll") for (int m = 0; m < 4; ++m) _Pragma("unroll") for (int k = 0; k < 2; ++k) dst[m][k] = *(const LAS bf16x8*)(lds + PG8_SA(b, h) + aoff + m * 2048 + k * 1024); } while (0)
; #define PG8_LDB(dst, b, h) do { _Pragma("unroll") for (int n = 0; n < 2; ++n) _Pragma("unroll") for (int k = 0; k < 2; ++k) dst[n][k] = *(const LAS bf16x8*)(lds + PG8_SB(b, h) + boff + n * 2048 + k * 1024); } while (0)
; #define PG8_WAIT_L(n) asm volatile("s_waitcnt lgkmcnt(" #n ")" ::: "memory")
; #define PG8_BAR __builtin_amdgcn_s_barrier()
; #define PG8_SCHED __builtin_amdgcn_sched_barrier(0)
; template <class Epi>
; DEVI void gemm_phase(LAS unsigned char* lds, const Gemm g, const Epi& E) {
;     ...
;         const bool has_next = unit_next(g, ui + 1, nxt);
;         const char* nA = has_next ? (const char*)g.A + gemm_offA(g, nxt) * 2 + (size_t)nxt.pm * tstepA : cA;
;         const char* nB = has_next ? (const char*)g.Bt + gemm_offB(g, nxt) * 2 + (size_t)nxt.pn * tstepB : cB;
;         for (int t = 0; t < nt; t += 2) {
;             const bool last = (t == nt - 2);
;             const char* a1 = cA + (size_t)(t + 1) * kstep;
;             const char* a2 = last ? nA : cA + (size_t)(t + 2) * kstep; const char* b2 = last ? nB : cB + (size_t)(t + 2) * kstep;
;             const char* a3 = a2 + kstep; const char* b3 = b2 + kstep;
;             PG8_LDB(B0, 0, 0); PG8_SCHED; PG8_LDA(At, 0, 0); PG8_STAGE(PG8_SA(1, 1), a1 + hstepA, voffA);
;             PG8_WAIT_L(8); PG8_BAR; PG8_WAIT_L(0); PG8_MMA(0, 0, At, B0); PG8_BAR; PG8_SCHED;
;             PG8_LDB(B1, 0, 1); PG8_STAGE(PG8_SB(0, 0), b2, voffB);
;             PG8_BAR; PG8_WAIT_L(0); PG8_MMA(0, 1, At, B1); PG8_BAR;
;             PG8_LDA(At, 0, 1); PG8_STAGE(PG8_SA(0, 0), a2, voffA);
;             PG8_BAR; PG8_WAIT_L(0); PG8_MMA(1, 0, At, B0); PG8_BAR; PG8_SCHED;
.LBB0_1594:
	s_ashr_i32 s17, s16, 31
	s_lshl_b64 s[0:1], s[16:17], 19
	v_readlane_b32 s18, v251, 2
	v_readlane_b32 s19, v251, 3
	s_add_u32 s46, s18, s0
	s_addc_u32 s47, s19, s1
	s_and_b64 s[0:1], s[8:9], exec
	s_cselect_b32 s0, s47, s79
	s_cselect_b32 s1, s46, s78
	s_add_u32 s8, s78, 0x40080
	s_addc_u32 s9, s79, 0
	s_add_u32 s13, s80, 0x100
	s_addc_u32 s15, s81, 0
	s_mov_b32 s17, -2
	s_waitcnt lgkmcnt(0)
	s_nop 0
	s_nop 0
	s_nop 0
	s_nop 0
	s_nop 0
	s_nop 0
	s_nop 0
	s_nop 0
	s_nop 0
	s_nop 0
	s_nop 0
	s_add_u32 s18, s8, 0xfffc0080
	s_addc_u32 s19, s9, -1
	s_add_i32 s26, 0, 0x10000
	v_add_u32_e32 v142, s26, v191
	ds_read_b128 v[130:133], v142
	ds_read_b128 v[134:137], v142 offset:1024
	ds_read_b128 v[138:141], v142 offset:2048
	ds_read_b128 v[142:145], v142 offset:3072
	s_cmp_eq_u32 s17, 12
	s_cselect_b32 s81, s0, s19
	s_cselect_b32 s80, s1, s18
	s_cselect_b32 s79, s37, s15
	s_cselect_b32 s78, s36, s13
	v_lshl_add_u64 v[162:163], s[8:9], 0, v[152:153]
	s_add_i32 m0, s69, 0xc000
	ds_read_b128 v[178:181], v196
	ds_read_b128 v[182:185], v196 offset:1024
	ds_read_b128 v[186:189], v196 offset:2048
	ds_read_b128 v[198:201], v196 offset:3072
	ds_read_b128 v[202:205], v196 offset:4096
	ds_read_b128 v[206:209], v196 offset:5120
	ds_read_b128 v[214:217], v196 offset:6144
	ds_read_b128 v[218:221], v196 offset:7168
	global_load_lds_dwordx4 v[162:163], off
	s_add_i32 m0, s69, 0xe000
	v_lshl_add_u64 v[162:163], s[8:9], 0, v[176:177]
	global_load_lds_dwordx4 v[162:163], off
	s_waitcnt lgkmcnt(8)
	s_barrier
	s_waitcnt lgkmcnt(0)
	v_mfma_f32_16x16x32_bf16 v[126:129], v[130:133], v[178:181], 0
	v_mfma_f32_16x16x32_bf16 v[122:125], v[138:141], v[178:181], 0
	v_mfma_f32_16x16x32_bf16 v[110:113], v[130:133], v[186:189], 0
	v_mfma_f32_16x16x32_bf16 v[106:109], v[138:141], v[186:189], 0
	v_mfma_f32_16x16x32_bf16 v[94:97], v[130:133], v[202:205], 0
	v_mfma_f32_16x16x32_bf16 v[90:93], v[138:141], v[202:205], 0
	v_mfma_f32_16x16x32_bf16 v[78:81], v[130:133], v[214:217], 0
	v_mfma_f32_16x16x32_bf16 v[74:77], v[138:141], v[214:217], 0
	v_mfma_f32_16x16x32_bf16 v[126:129], v[134:137], v[182:185], v[126:129]
	v_mfma_f32_16x16x32_bf16 v[122:125], v[142:145], v[182:185], v[122:125]
	v_mfma_f32_16x16x32_bf16 v[110:113], v[134:137], v[198:201], v[110:113]
	v_mfma_f32_16x16x32_bf16 v[106:109], v[142:145], v[198:201], v[106:109]
	v_mfma_f32_16x16x32_bf16 v[94:97], v[134:137], v[206:209], v[94:97]
	v_mfma_f32_16x16x32_bf16 v[90:93], v[142:145], v[206:209], v[90:93]
	v_mfma_f32_16x16x32_bf16 v[78:81], v[134:137], v[218:221], v[78:81]
	v_mfma_f32_16x16x32_bf16 v[74:77], v[142:145], v[218:221], v[74:77]
	s_barrier
	s_add_i32 s27, 0, 0x14000
	v_add_u32_e32 v162, s27, v191
	s_add_i32 s18, s26, s82
	ds_read_b128 v[222:225], v162
	ds_read_b128 v[226:229], v162 offset:1024
	ds_read_b128 v[230:233], v162 offset:2048
	ds_read_b128 v[234:237], v162 offset:3072
	v_lshl_add_u64 v[162:163], s[78:79], 0, v[8:9]
	s_mov_b32 m0, s18
	v_lshl_add_u64 v[164:165], s[78:79], 0, v[150:151]
	global_load_lds_dwordx4 v[162:163], off
	s_add_i32 m0, s18, 0x2000
	s_nop 0
	global_load_lds_dwordx4 v[164:165], off
	s_barrier
	s_waitcnt lgkmcnt(0)
	v_mfma_f32_16x16x32_bf16 v[118:121], v[222:225], v[178:181], 0
	v_mfma_f32_16x16x32_bf16 v[114:117], v[230:233], v[178:181], 0
	v_mfma_f32_16x16x32_bf16 v[102:105], v[222:225], v[186:189], 0
	v_mfma_f32_16x16x32_bf16 v[98:101], v[230:233], v[186:189], 0
	v_mfma_f32_16x16x32_bf16 v[86:89], v[222:225], v[202:205], 0
	v_mfma_f32_16x16x32_bf16 v[82:85], v[230:233], v[202:205], 0
	v_mfma_f32_16x16x32_bf16 v[70:73], v[222:225], v[214:217], 0
	v_mfma_f32_16x16x32_bf16 v[66:69], v[230:233], v[214:217], 0
	v_mfma_f32_16x16x32_bf16 v[118:121], v[226:229], v[182:185], v[118:121]
	v_mfma_f32_16x16x32_bf16 v[114:117], v[234:237], v[182:185], v[114:117]
	v_mfma_f32_16x16x32_bf16 v[102:105], v[226:229], v[198:201], v[102:105]
	v_mfma_f32_16x16x32_bf16 v[98:101], v[234:237], v[198:201], v[98:101]
	v_mfma_f32_16x16x32_bf16 v[86:89], v[226:229], v[206:209], v[86:89]
	v_mfma_f32_16x16x32_bf16 v[82:85], v[234:237], v[206:209], v[82:85]
	v_mfma_f32_16x16x32_bf16 v[70:73], v[226:229], v[218:221], v[70:73]
	v_mfma_f32_16x16x32_bf16 v[66:69], v[234:237], v[218:221], v[66:69]
	s_mov_b32 m0, s69
	v_lshl_add_u64 v[238:239], s[80:81], 0, v[146:147]
	s_barrier
	ds_read_b128 v[178:181], v196 offset:16384
	ds_read_b128 v[182:185], v196 offset:17408
	ds_read_b128 v[186:189], v196 offset:18432
	ds_read_b128 v[198:201], v196 offset:19456
	ds_read_b128 v[202:205], v196 offset:20480
	ds_read_b128 v[206:209], v196 offset:21504
	ds_read_b128 v[214:217], v196 offset:22528
	ds_read_b128 v[218:221], v196 offset:23552
	global_load_lds_dwordx4 v[238:239], off
	s_mov_b32 m0, s83
	v_lshl_add_u64 v[240:241], s[80:81], 0, v[148:149]
	global_load_lds_dwordx4 v[240:241], off
	s_barrier
	s_waitcnt lgkmcnt(0)
	v_mfma_f32_16x16x32_bf16 v[62:65], v[130:133], v[178:181], 0
	v_mfma_f32_16x16x32_bf16 v[58:61], v[138:141], v[178:181], 0
	v_mfma_f32_16x16x32_bf16 v[46:49], v[130:133], v[186:189], 0
	v_mfma_f32_16x16x32_bf16 v[42:45], v[138:141], v[186:189], 0
	v_mfma_f32_16x16x32_bf16 v[30:33], v[130:133], v[202:205], 0
	v_mfma_f32_16x16x32_bf16 v[26:29], v[138:141], v[202:205], 0
	v_mfma_f32_16x16x32_bf16 v[14:17], v[130:133], v[214:217], 0
	v_mfma_f32_16x16x32_bf16 v[10:13], v[138:141], v[214:217], 0
	v_mfma_f32_16x16x32_bf16 v[62:65], v[134:137], v[182:185], v[62:65]
	v_mfma_f32_16x16x32_bf16 v[58:61], v[142:145], v[182:185], v[58:61]
	v_mfma_f32_16x16x32_bf16 v[46:49], v[134:137], v[198:201], v[46:49]
	v_mfma_f32_16x16x32_bf16 v[42:45], v[142:145], v[198:201], v[42:45]
	v_mfma_f32_16x16x32_bf16 v[30:33], v[134:137], v[206:209], v[30:33]
	v_mfma_f32_16x16x32_bf16 v[26:29], v[142:145], v[206:209], v[26:29]
	v_mfma_f32_16x16x32_bf16 v[14:17], v[134:137], v[218:221], v[14:17]
	v_mfma_f32_16x16x32_bf16 v[10:13], v[142:145], v[218:221], v[10:13]
	s_barrier
; #define PG8_STAGE(bufoff, gbase, voff) do { _Pragma("unroll") for (int _i = 0; _i < 2; ++_i) \
;         __builtin_amdgcn_global_load_lds((const unsigned*)((const char*)(gbase) + (voff)[_i]), (LAS unsigned*)(lds + (bufoff) + ldsw + _i * 8192), 16, 0, 0); } while (0)
; #define PG8_LDA(dst, b, h) do { _Pragma("unroll") for (int m = 0; m < 4; ++m) _Pragma("unroll") for (int k = 0; k < 2; ++k) dst[m][k] = *(const LAS bf16x8*)(lds + PG8_SA(b, h) + aoff + m * 2048 + k * 1024); } while (0)
; #define PG8_LDB(dst, b, h) do { _Pragma("unroll") for (int n = 0; n < 2; ++n) _Pragma("unroll") for (int k = 0; k < 2; ++k) dst[n][k] = *(const LAS bf16x8*)(lds + PG8_SB(b, h) + boff + n * 2048 + k * 1024); } while (0)
; #define PG8_MMA(ai, bj, At, Bt) do { __builtin_amdgcn_s_setprio(1); _Pragma("unroll") for (int m = 0; m < 4; ++m) _Pragma("unroll") for (int n = 0; n < 2; ++n) _Pragma("unroll") for (int k = 0; k < 2; ++k) \
;         acc[ai][bj][m][n] = __builtin_amdgcn_mfma_f32_16x16x32_bf16(Bt[n][k], At[m][k], acc[ai][bj][m][n], 0, 0, 0); __builtin_amdgcn_s_setprio(0); } while (0)
; #define PG8_WAIT_V(n) asm volatile("s_waitcnt vmcnt(" #n ")" ::: "memory")
; #define PG8_WAIT_L(n) asm volatile("s_waitcnt lgkmcnt(" #n ")" ::: "memory")
; #define PG8_BAR __builtin_amdgcn_s_barrier()
; #define PG8_SCHED __builtin_amdgcn_sched_barrier(0)
; template <class Epi>
; DEVI void gemm_phase(LAS unsigned char* lds, const Gemm g, const Epi& E) {
;     ...
;             PG8_STAGE(PG8_SB(0, 1), b2 + hstepB, voffB);
;             PG8_WAIT_V(6); PG8_BAR; PG8_MMA(1, 1, At, B1); PG8_BAR;
;             PG8_LDB(B0, 1, 0); PG8_SCHED; PG8_LDA(At, 1, 0); PG8_STAGE(PG8_SA(0, 1), a2 + hstepA, voffA);
;             PG8_WAIT_L(8); PG8_BAR; PG8_WAIT_L(0); PG8_MMA(0, 0, At, B0); PG8_BAR; PG8_SCHED;
;             PG8_LDB(B1, 1, 1); PG8_STAGE(PG8_SB(1, 0), b3, voffB);
	s_add_u32 s18, s78, 0x40000
	s_addc_u32 s19, s79, 0
	s_add_i32 s26, s27, s82
	s_mov_b32 m0, s26
	v_lshl_add_u64 v[130:131], s[18:19], 0, v[8:9]
	global_load_lds_dwordx4 v[130:131], off
	s_add_i32 m0, s26, 0x2000
	v_lshl_add_u64 v[130:131], s[18:19], 0, v[150:151]
	global_load_lds_dwordx4 v[130:131], off
	s_waitcnt vmcnt(6)
	s_barrier
	v_mfma_f32_16x16x32_bf16 v[54:57], v[222:225], v[178:181], 0
	v_mfma_f32_16x16x32_bf16 v[50:53], v[230:233], v[178:181], 0
	v_mfma_f32_16x16x32_bf16 v[38:41], v[222:225], v[186:189], 0
	v_mfma_f32_16x16x32_bf16 v[34:37], v[230:233], v[186:189], 0
	v_mfma_f32_16x16x32_bf16 v[22:25], v[222:225], v[202:205], 0
	v_mfma_f32_16x16x32_bf16 v[18:21], v[230:233], v[202:205], 0
	v_mfma_f32_16x16x32_bf16 v[4:7], v[222:225], v[214:217], 0
	v_mfma_f32_16x16x32_bf16 v[0:3], v[230:233], v[214:217], 0
	v_mfma_f32_16x16x32_bf16 v[54:57], v[226:229], v[182:185], v[54:57]
	v_mfma_f32_16x16x32_bf16 v[50:53], v[234:237], v[182:185], v[50:53]
	v_mfma_f32_16x16x32_bf16 v[38:41], v[226:229], v[198:201], v[38:41]
	v_mfma_f32_16x16x32_bf16 v[34:37], v[234:237], v[198:201], v[34:37]
	v_mfma_f32_16x16x32_bf16 v[22:25], v[226:229], v[206:209], v[22:25]
	v_mfma_f32_16x16x32_bf16 v[18:21], v[234:237], v[206:209], v[18:21]
	v_mfma_f32_16x16x32_bf16 v[4:7], v[226:229], v[218:221], v[4:7]
	v_mfma_f32_16x16x32_bf16 v[0:3], v[234:237], v[218:221], v[0:3]
	s_add_i32 s26, 0, 0x18000
	v_add_u32_e32 v142, s26, v191
	s_barrier
	ds_read_b128 v[130:133], v142
	ds_read_b128 v[134:137], v142 offset:1024
	ds_read_b128 v[138:141], v142 offset:2048
	ds_read_b128 v[142:145], v142 offset:3072
	s_add_u32 s18, s80, 0x40000
	s_addc_u32 s19, s81, 0
	s_mov_b32 m0, s84
	v_lshl_add_u64 v[222:223], s[18:19], 0, v[146:147]
	ds_read_b128 v[178:181], v196 offset:32768
	ds_read_b128 v[182:185], v196 offset:33792
	ds_read_b128 v[186:189], v196 offset:34816
	ds_read_b128 v[198:201], v196 offset:35840
	ds_read_b128 v[202:205], v196 offset:36864
	ds_read_b128 v[206:209], v196 offset:37888
	ds_read_b128 v[214:217], v196 offset:38912
	ds_read_b128 v[218:221], v196 offset:39936
	global_load_lds_dwordx4 v[222:223], off
	s_mov_b32 m0, s85
	v_lshl_add_u64 v[222:223], s[18:19], 0, v[148:149]
	global_load_lds_dwordx4 v[222:223], off
	s_waitcnt lgkmcnt(8)
	s_barrier
	s_waitcnt lgkmcnt(0)
	v_mfma_f32_16x16x32_bf16 v[126:129], v[130:133], v[178:181], v[126:129]
	v_mfma_f32_16x16x32_bf16 v[122:125], v[138:141], v[178:181], v[122:125]
	v_mfma_f32_16x16x32_bf16 v[110:113], v[130:133], v[186:189], v[110:113]
	v_mfma_f32_16x16x32_bf16 v[106:109], v[138:141], v[186:189], v[106:109]
	v_mfma_f32_16x16x32_bf16 v[94:97], v[130:133], v[202:205], v[94:97]
	v_mfma_f32_16x16x32_bf16 v[90:93], v[138:141], v[202:205], v[90:93]
	v_mfma_f32_16x16x32_bf16 v[78:81], v[130:133], v[214:217], v[78:81]
	v_mfma_f32_16x16x32_bf16 v[74:77], v[138:141], v[214:217], v[74:77]
	v_mfma_f32_16x16x32_bf16 v[126:129], v[134:137], v[182:185], v[126:129]
	v_mfma_f32_16x16x32_bf16 v[122:125], v[142:145], v[182:185], v[122:125]
	v_mfma_f32_16x16x32_bf16 v[110:113], v[134:137], v[198:201], v[110:113]
	v_mfma_f32_16x16x32_bf16 v[106:109], v[142:145], v[198:201], v[106:109]
	v_mfma_f32_16x16x32_bf16 v[94:97], v[134:137], v[206:209], v[94:97]
	v_mfma_f32_16x16x32_bf16 v[90:93], v[142:145], v[206:209], v[90:93]
	v_mfma_f32_16x16x32_bf16 v[78:81], v[134:137], v[218:221], v[78:81]
	v_mfma_f32_16x16x32_bf16 v[74:77], v[142:145], v[218:221], v[74:77]
	s_barrier
	s_add_i32 s27, 0, 0x1c000
	s_add_i32 s18, s26, s82
	v_add_u32_e32 v197, s27, v191
	v_lshl_add_u64 v[162:163], v[162:163], 0, s[70:71]
	s_mov_b32 m0, s18
	ds_read_b128 v[222:225], v197
	ds_read_b128 v[226:229], v197 offset:1024
	ds_read_b128 v[230:233], v197 offset:2048
	ds_read_b128 v[234:237], v197 offset:3072
	global_load_lds_dwordx4 v[162:163], off
	s_add_i32 m0, s18, 0x2000
	v_lshl_add_u64 v[162:163], v[164:165], 0, s[70:71]
	global_load_lds_dwordx4 v[162:163], off
	s_barrier
; #define PG8_STAGE(bufoff, gbase, voff) do { _Pragma("unroll") for (int _i = 0; _i < 2; ++_i) \
;         __builtin_amdgcn_global_load_lds((const unsigned*)((const char*)(gbase) + (voff)[_i]), (LAS unsigned*)(lds + (bufoff) + ldsw + _i * 8192), 16, 0, 0); } while (0)
; #define PG8_LDA(dst, b, h) do { _Pragma("unroll") for (int m = 0; m < 4; ++m) _Pragma("unroll") for (int k = 0; k < 2; ++k) dst[m][k] = *(const LAS bf16x8*)(lds + PG8_SA(b, h) + aoff + m * 2048 + k * 1024); } while (0)
; #define PG8_MMA(ai, bj, At, Bt) do { __builtin_amdgcn_s_setprio(1); _Pragma("unroll") for (int m = 0; m < 4; ++m) _Pragma("unroll") for (int n = 0; n < 2; ++n) _Pragma("unroll") for (int k = 0; k < 2; ++k) \
;         acc[ai][bj][m][n] = __builtin_amdgcn_mfma_f32_16x16x32_bf16(Bt[n][k], At[m][k], acc[ai][bj][m][n], 0, 0, 0); __builtin_amdgcn_s_setprio(0); } while (0)
; #define PG8_WAIT_V(n) asm volatile("s_waitcnt vmcnt(" #n ")" ::: "memory")
; #define PG8_WAIT_L(n) asm volatile("s_waitcnt lgkmcnt(" #n ")" ::: "memory")
; #define PG8_BAR __builtin_amdgcn_s_barrier()
; #define PG8_SCHED __builtin_amdgcn_sched_barrier(0)
; template <class Epi>
; DEVI void gemm_phase(LAS unsigned char* lds, const Gemm g, const Epi& E) {
;     ...
;             PG8_BAR; PG8_WAIT_L(0); PG8_MMA(0, 1, At, B1); PG8_BAR;
;             PG8_LDA(At, 1, 1); PG8_STAGE(PG8_SA(1, 0), a3, voffA);
;             PG8_BAR; PG8_WAIT_L(0); PG8_MMA(1, 0, At, B0); PG8_BAR; PG8_SCHED;
;             PG8_STAGE(PG8_SB(1, 1), b3 + hstepB, voffB);
;             PG8_WAIT_V(6); PG8_BAR; PG8_MMA(1, 1, At, B1); PG8_BAR;
	s_waitcnt lgkmcnt(0)
	v_mfma_f32_16x16x32_bf16 v[118:121], v[222:225], v[178:181], v[118:121]
	v_mfma_f32_16x16x32_bf16 v[114:117], v[230:233], v[178:181], v[114:117]
	v_mfma_f32_16x16x32_bf16 v[102:105], v[222:225], v[186:189], v[102:105]
	v_mfma_f32_16x16x32_bf16 v[98:101], v[230:233], v[186:189], v[98:101]
	v_mfma_f32_16x16x32_bf16 v[86:89], v[222:225], v[202:205], v[86:89]
	v_mfma_f32_16x16x32_bf16 v[82:85], v[230:233], v[202:205], v[82:85]
	v_mfma_f32_16x16x32_bf16 v[70:73], v[222:225], v[214:217], v[70:73]
	v_mfma_f32_16x16x32_bf16 v[66:69], v[230:233], v[214:217], v[66:69]
	v_mfma_f32_16x16x32_bf16 v[118:121], v[226:229], v[182:185], v[118:121]
	v_mfma_f32_16x16x32_bf16 v[114:117], v[234:237], v[182:185], v[114:117]
	v_mfma_f32_16x16x32_bf16 v[102:105], v[226:229], v[198:201], v[102:105]
	v_mfma_f32_16x16x32_bf16 v[98:101], v[234:237], v[198:201], v[98:101]
	v_mfma_f32_16x16x32_bf16 v[86:89], v[226:229], v[206:209], v[86:89]
	v_mfma_f32_16x16x32_bf16 v[82:85], v[234:237], v[206:209], v[82:85]
	v_mfma_f32_16x16x32_bf16 v[70:73], v[226:229], v[218:221], v[70:73]
	v_mfma_f32_16x16x32_bf16 v[66:69], v[234:237], v[218:221], v[66:69]
	s_mov_b32 m0, s86
	v_lshl_add_u64 v[162:163], v[238:239], 0, s[70:71]
	s_barrier
	ds_read_b128 v[178:181], v196 offset:49152
	ds_read_b128 v[182:185], v196 offset:50176
	ds_read_b128 v[186:189], v196 offset:51200
	ds_read_b128 v[198:201], v196 offset:52224
	ds_read_b128 v[202:205], v196 offset:53248
	ds_read_b128 v[206:209], v196 offset:54272
	ds_read_b128 v[214:217], v196 offset:55296
	ds_read_b128 v[218:221], v196 offset:56320
	global_load_lds_dwordx4 v[162:163], off
	s_mov_b32 m0, s87
	v_lshl_add_u64 v[162:163], v[240:241], 0, s[70:71]
	global_load_lds_dwordx4 v[162:163], off
	s_barrier
	s_waitcnt lgkmcnt(0)
	v_mfma_f32_16x16x32_bf16 v[62:65], v[130:133], v[178:181], v[62:65]
	v_mfma_f32_16x16x32_bf16 v[58:61], v[138:141], v[178:181], v[58:61]
	v_mfma_f32_16x16x32_bf16 v[46:49], v[130:133], v[186:189], v[46:49]
	v_mfma_f32_16x16x32_bf16 v[42:45], v[138:141], v[186:189], v[42:45]
	v_mfma_f32_16x16x32_bf16 v[30:33], v[130:133], v[202:205], v[30:33]
	v_mfma_f32_16x16x32_bf16 v[26:29], v[138:141], v[202:205], v[26:29]
	v_mfma_f32_16x16x32_bf16 v[14:17], v[130:133], v[214:217], v[14:17]
	v_mfma_f32_16x16x32_bf16 v[10:13], v[138:141], v[214:217], v[10:13]
	v_mfma_f32_16x16x32_bf16 v[62:65], v[134:137], v[182:185], v[62:65]
	v_mfma_f32_16x16x32_bf16 v[58:61], v[142:145], v[182:185], v[58:61]
	v_mfma_f32_16x16x32_bf16 v[46:49], v[134:137], v[198:201], v[46:49]
	v_mfma_f32_16x16x32_bf16 v[42:45], v[142:145], v[198:201], v[42:45]
	v_mfma_f32_16x16x32_bf16 v[30:33], v[134:137], v[206:209], v[30:33]
	v_mfma_f32_16x16x32_bf16 v[26:29], v[142:145], v[206:209], v[26:29]
	v_mfma_f32_16x16x32_bf16 v[14:17], v[134:137], v[218:221], v[14:17]
	v_mfma_f32_16x16x32_bf16 v[10:13], v[142:145], v[218:221], v[10:13]
	s_barrier
	s_add_u32 s18, s78, 0x40080
	s_addc_u32 s19, s79, 0
	s_add_i32 s26, s27, s82
	s_mov_b32 m0, s26
	v_lshl_add_u64 v[130:131], s[18:19], 0, v[8:9]
	global_load_lds_dwordx4 v[130:131], off
	s_add_i32 m0, s26, 0x2000
	v_lshl_add_u64 v[130:131], s[18:19], 0, v[150:151]
	global_load_lds_dwordx4 v[130:131], off
	s_waitcnt vmcnt(6)
	s_barrier
	v_mfma_f32_16x16x32_bf16 v[54:57], v[222:225], v[178:181], v[54:57]
	v_mfma_f32_16x16x32_bf16 v[50:53], v[230:233], v[178:181], v[50:53]
	v_mfma_f32_16x16x32_bf16 v[38:41], v[222:225], v[186:189], v[38:41]
	v_mfma_f32_16x16x32_bf16 v[34:37], v[230:233], v[186:189], v[34:37]
	v_mfma_f32_16x16x32_bf16 v[22:25], v[222:225], v[202:205], v[22:25]
	v_mfma_f32_16x16x32_bf16 v[18:21], v[230:233], v[202:205], v[18:21]
	v_mfma_f32_16x16x32_bf16 v[4:7], v[222:225], v[214:217], v[4:7]
	v_mfma_f32_16x16x32_bf16 v[0:3], v[230:233], v[214:217], v[0:3]
	v_mfma_f32_16x16x32_bf16 v[54:57], v[226:229], v[182:185], v[54:57]
	v_mfma_f32_16x16x32_bf16 v[50:53], v[234:237], v[182:185], v[50:53]
	v_mfma_f32_16x16x32_bf16 v[38:41], v[226:229], v[198:201], v[38:41]
	v_mfma_f32_16x16x32_bf16 v[34:37], v[234:237], v[198:201], v[34:37]
	v_mfma_f32_16x16x32_bf16 v[22:25], v[226:229], v[206:209], v[22:25]
	v_mfma_f32_16x16x32_bf16 v[18:21], v[234:237], v[206:209], v[18:21]
	v_mfma_f32_16x16x32_bf16 v[4:7], v[226:229], v[218:221], v[4:7]
	v_mfma_f32_16x16x32_bf16 v[0:3], v[234:237], v[218:221], v[0:3]
	s_add_i32 s17, s17, 2
	s_add_u32 s8, s8, 0x100
	s_addc_u32 s9, s9, 0
	s_add_u32 s13, s13, 0x100
	s_addc_u32 s15, s15, 0
	s_cmp_gt_u32 s17, 13
	s_barrier

; DEVI size_t gemm_offB(const Gemm& g, const Unit& u) { return (g.split ? (size_t)(u.b >> 2) * g.sB + (size_t)(u.b & 3) * g.sB_lo : (size_t)u.b * g.sB) + (size_t)(u.pm >> g.pmsh) * g.sBpm; }
; #define PG8_STAGE(bufoff, gbase, voff) do { _Pragma("unroll") for (int _i = 0; _i < 2; ++_i) \
;         __builtin_amdgcn_global_load_lds((const unsigned*)((const char*)(gbase) + (voff)[_i]), (LAS unsigned*)(lds + (bufoff) + ldsw + _i * 8192), 16, 0, 0); } while (0)
; #define PG8_LDA(dst, b, h) do { _Pragma("unroll") for (int m = 0; m < 4; ++m) _Pragma("unroll") for (int k = 0; k < 2; ++k) dst[m][k] = *(const LAS bf16x8*)(lds + PG8_SA(b, h) + aoff + m * 2048 + k * 1024); } while (0)
; #define PG8_LDB(dst, b, h) do { _Pragma("unroll") for (int n = 0; n < 2; ++n) _Pragma("unroll") for (int k = 0; k < 2; ++k) dst[n][k] = *(const LAS bf16x8*)(lds + PG8_SB(b, h) + boff + n * 2048 + k * 1024); } while (0)
; #define PG8_WAIT_L(n) asm volatile("s_waitcnt lgkmcnt(" #n ")" ::: "memory")
; #define PG8_BAR __builtin_amdgcn_s_barrier()
; #define PG8_SCHED __builtin_amdgcn_sched_barrier(0)
; template <class Epi>
; DEVI void gemm_phase(LAS unsigned char* lds, const Gemm g, const Epi& E) {
;     ...
;         const bool has_next = unit_next(g, ui + 1, nxt);
;         const char* nA = has_next ? (const char*)g.A + gemm_offA(g, nxt) * 2 + (size_t)nxt.pm * tstepA : cA;
;         const char* nB = has_next ? (const char*)g.Bt + gemm_offB(g, nxt) * 2 + (size_t)nxt.pn * tstepB : cB;
;         for (int t = 0; t < nt; t += 2) {
;             const bool last = (t == nt - 2);
;             const char* a1 = cA + (size_t)(t + 1) * kstep;
;             const char* a2 = last ? nA : cA + (size_t)(t + 2) * kstep; const char* b2 = last ? nB : cB + (size_t)(t + 2) * kstep;
;             const char* a3 = a2 + kstep; const char* b3 = b2 + kstep;
;             PG8_LDB(B0, 0, 0); PG8_SCHED; PG8_LDA(At, 0, 0); PG8_STAGE(PG8_SA(1, 1), a1 + hstepA, voffA);
;             PG8_WAIT_L(8); PG8_BAR; PG8_WAIT_L(0); PG8_MMA(0, 0, At, B0); PG8_BAR; PG8_SCHED;
;             PG8_LDB(B1, 0, 1); PG8_STAGE(PG8_SB(0, 0), b2, voffB);
;             PG8_BAR; PG8_WAIT_L(0); PG8_MMA(0, 1, At, B1); PG8_BAR;
;             PG8_LDA(At, 0, 1); PG8_STAGE(PG8_SA(0, 0), a2, voffA);
.LBB0_1671:
	s_ashr_i32 s7, s6, 31
	s_lshl_b64 s[0:1], s[6:7], 19
	v_cmp_lt_i64_e32 vcc, s[12:13], v[174:175]
	s_add_u32 s12, s24, s0
	s_addc_u32 s13, s25, s1
	s_and_b64 s[0:1], vcc, exec
	s_cselect_b32 s0, s13, s17
	s_cselect_b32 s1, s12, s16
	s_ashr_i32 s9, s8, 31
	s_lshl_b64 s[14:15], s[8:9], 19
	s_add_u32 s14, s68, s14
	s_addc_u32 s15, s69, s15
	s_and_b64 s[18:19], vcc, exec
	s_cselect_b32 s5, s15, s37
	s_cselect_b32 s7, s14, s36
	s_add_u32 s16, s16, 0x40080
	s_addc_u32 s17, s17, 0
	s_add_u32 s9, s36, 0x100
	s_addc_u32 s18, s37, 0
	s_mov_b32 s19, -2
	v_and_b32_e32 v248, 0xff, v154
	v_lshlrev_b32_e32 v248, 4, v248
	v_add_u32_e32 v249, 0x21000, v248
	v_lshl_add_u32 v248, s4, 12, v248
	global_load_dwordx4 v[244:247], v248, s[10:11]
	s_nop 0
	s_nop 0
	s_nop 0
	s_nop 0
	s_nop 0
	s_nop 0
	s_nop 0
	s_nop 0
	s_add_u32 s26, s16, 0xfffc0080
	s_addc_u32 s27, s17, -1
	s_add_i32 s38, 0, 0x10000
	v_add_u32_e32 v142, s38, v197
	ds_read_b128 v[130:133], v142
	ds_read_b128 v[134:137], v142 offset:1024
	ds_read_b128 v[138:141], v142 offset:2048
	ds_read_b128 v[142:145], v142 offset:3072
	s_cmp_eq_u32 s19, 12
	s_cselect_b32 s47, s0, s27
	s_cselect_b32 s46, s1, s26
	s_cselect_b32 s37, s5, s18
	s_cselect_b32 s36, s7, s9
	v_lshl_add_u64 v[162:163], s[16:17], 0, v[152:153]
	s_add_i32 m0, s79, 0xc000
	ds_read_b128 v[178:181], v201
	ds_read_b128 v[182:185], v201 offset:1024
	ds_read_b128 v[186:189], v201 offset:2048
	ds_read_b128 v[202:205], v201 offset:3072
	ds_read_b128 v[206:209], v201 offset:4096
	ds_read_b128 v[214:217], v201 offset:5120
	ds_read_b128 v[218:221], v201 offset:6144
	ds_read_b128 v[222:225], v201 offset:7168
	global_load_lds_dwordx4 v[162:163], off
	s_add_i32 m0, s79, 0xe000
	v_lshl_add_u64 v[162:163], s[16:17], 0, v[176:177]
	global_load_lds_dwordx4 v[162:163], off
	s_waitcnt lgkmcnt(8)
	s_barrier
	s_waitcnt lgkmcnt(0)
	v_mfma_f32_16x16x32_bf16 v[126:129], v[130:133], v[178:181], 0
	v_mfma_f32_16x16x32_bf16 v[122:125], v[138:141], v[178:181], 0
	v_mfma_f32_16x16x32_bf16 v[110:113], v[130:133], v[186:189], 0
	v_mfma_f32_16x16x32_bf16 v[106:109], v[138:141], v[186:189], 0
	v_mfma_f32_16x16x32_bf16 v[94:97], v[130:133], v[206:209], 0
	v_mfma_f32_16x16x32_bf16 v[90:93], v[138:141], v[206:209], 0
	v_mfma_f32_16x16x32_bf16 v[78:81], v[130:133], v[218:221], 0
	v_mfma_f32_16x16x32_bf16 v[74:77], v[138:141], v[218:221], 0
	v_mfma_f32_16x16x32_bf16 v[126:129], v[134:137], v[182:185], v[126:129]
	v_mfma_f32_16x16x32_bf16 v[122:125], v[142:145], v[182:185], v[122:125]
	v_mfma_f32_16x16x32_bf16 v[110:113], v[134:137], v[202:205], v[110:113]
	v_mfma_f32_16x16x32_bf16 v[106:109], v[142:145], v[202:205], v[106:109]
	v_mfma_f32_16x16x32_bf16 v[94:97], v[134:137], v[214:217], v[94:97]
	v_mfma_f32_16x16x32_bf16 v[90:93], v[142:145], v[214:217], v[90:93]
	v_mfma_f32_16x16x32_bf16 v[78:81], v[134:137], v[222:225], v[78:81]
	v_mfma_f32_16x16x32_bf16 v[74:77], v[142:145], v[222:225], v[74:77]
	s_barrier
	s_add_i32 s39, 0, 0x14000
	v_add_u32_e32 v162, s39, v197
	s_add_i32 s26, s38, s78
	ds_read_b128 v[226:229], v162
	ds_read_b128 v[230:233], v162 offset:1024
	ds_read_b128 v[234:237], v162 offset:2048
	ds_read_b128 v[238:241], v162 offset:3072
	v_lshl_add_u64 v[162:163], s[36:37], 0, v[8:9]
	s_mov_b32 m0, s26
	v_lshl_add_u64 v[164:165], s[36:37], 0, v[146:147]
	global_load_lds_dwordx4 v[162:163], off
	s_add_i32 m0, s26, 0x2000
	s_nop 0
	global_load_lds_dwordx4 v[164:165], off
	s_barrier
	s_waitcnt lgkmcnt(0)
	v_mfma_f32_16x16x32_bf16 v[118:121], v[226:229], v[178:181], 0
	v_mfma_f32_16x16x32_bf16 v[114:117], v[234:237], v[178:181], 0
	v_mfma_f32_16x16x32_bf16 v[102:105], v[226:229], v[186:189], 0
	v_mfma_f32_16x16x32_bf16 v[98:101], v[234:237], v[186:189], 0
	v_mfma_f32_16x16x32_bf16 v[86:89], v[226:229], v[206:209], 0
	v_mfma_f32_16x16x32_bf16 v[82:85], v[234:237], v[206:209], 0
	v_mfma_f32_16x16x32_bf16 v[70:73], v[226:229], v[218:221], 0
	v_mfma_f32_16x16x32_bf16 v[66:69], v[234:237], v[218:221], 0
	v_mfma_f32_16x16x32_bf16 v[118:121], v[230:233], v[182:185], v[118:121]
	v_mfma_f32_16x16x32_bf16 v[114:117], v[238:241], v[182:185], v[114:117]
	v_mfma_f32_16x16x32_bf16 v[102:105], v[230:233], v[202:205], v[102:105]
	v_mfma_f32_16x16x32_bf16 v[98:101], v[238:241], v[202:205], v[98:101]
	v_mfma_f32_16x16x32_bf16 v[86:89], v[230:233], v[214:217], v[86:89]
	v_mfma_f32_16x16x32_bf16 v[82:85], v[238:241], v[214:217], v[82:85]
	v_mfma_f32_16x16x32_bf16 v[70:73], v[230:233], v[222:225], v[70:73]
	v_mfma_f32_16x16x32_bf16 v[66:69], v[238:241], v[222:225], v[66:69]
	s_mov_b32 m0, s79
	v_lshl_add_u64 v[190:191], s[46:47], 0, v[150:151]
	s_barrier
	ds_read_b128 v[178:181], v201 offset:16384
	ds_read_b128 v[182:185], v201 offset:17408
	ds_read_b128 v[186:189], v201 offset:18432
	ds_read_b128 v[202:205], v201 offset:19456
	ds_read_b128 v[206:209], v201 offset:20480
	ds_read_b128 v[214:217], v201 offset:21504
	ds_read_b128 v[218:221], v201 offset:22528
	ds_read_b128 v[222:225], v201 offset:23552
	global_load_lds_dwordx4 v[190:191], off
	s_mov_b32 m0, s80
	v_lshl_add_u64 v[194:195], s[46:47], 0, v[148:149]
	global_load_lds_dwordx4 v[194:195], off
	s_barrier
; #define PG8_STAGE(bufoff, gbase, voff) do { _Pragma("unroll") for (int _i = 0; _i < 2; ++_i) \
;         __builtin_amdgcn_global_load_lds((const unsigned*)((const char*)(gbase) + (voff)[_i]), (LAS unsigned*)(lds + (bufoff) + ldsw + _i * 8192), 16, 0, 0); } while (0)
; #define PG8_LDA(dst, b, h) do { _Pragma("unroll") for (int m = 0; m < 4; ++m) _Pragma("unroll") for (int k = 0; k < 2; ++k) dst[m][k] = *(const LAS bf16x8*)(lds + PG8_SA(b, h) + aoff + m * 2048 + k * 1024); } while (0)
; #define PG8_LDB(dst, b, h) do { _Pragma("unroll") for (int n = 0; n < 2; ++n) _Pragma("unroll") for (int k = 0; k < 2; ++k) dst[n][k] = *(const LAS bf16x8*)(lds + PG8_SB(b, h) + boff + n * 2048 + k * 1024); } while (0)
; #define PG8_MMA(ai, bj, At, Bt) do { __builtin_amdgcn_s_setprio(1); _Pragma("unroll") for (int m = 0; m < 4; ++m) _Pragma("unroll") for (int n = 0; n < 2; ++n) _Pragma("unroll") for (int k = 0; k < 2; ++k) \
;         acc[ai][bj][m][n] = __builtin_amdgcn_mfma_f32_16x16x32_bf16(Bt[n][k], At[m][k], acc[ai][bj][m][n], 0, 0, 0); __builtin_amdgcn_s_setprio(0); } while (0)
; #define PG8_WAIT_V(n) asm volatile("s_waitcnt vmcnt(" #n ")" ::: "memory")
; #define PG8_WAIT_L(n) asm volatile("s_waitcnt lgkmcnt(" #n ")" ::: "memory")
; #define PG8_BAR __builtin_amdgcn_s_barrier()
; #define PG8_SCHED __builtin_amdgcn_sched_barrier(0)
; template <class Epi>
; DEVI void gemm_phase(LAS unsigned char* lds, const Gemm g, const Epi& E) {
;     ...
;             PG8_BAR; PG8_WAIT_L(0); PG8_MMA(1, 0, At, B0); PG8_BAR; PG8_SCHED;
;             PG8_STAGE(PG8_SB(0, 1), b2 + hstepB, voffB);
;             PG8_WAIT_V(6); PG8_BAR; PG8_MMA(1, 1, At, B1); PG8_BAR;
;             PG8_LDB(B0, 1, 0); PG8_SCHED; PG8_LDA(At, 1, 0); PG8_STAGE(PG8_SA(0, 1), a2 + hstepA, voffA);
;             PG8_WAIT_L(8); PG8_BAR; PG8_WAIT_L(0); PG8_MMA(0, 0, At, B0); PG8_BAR; PG8_SCHED;
	s_waitcnt lgkmcnt(0)
	v_mfma_f32_16x16x32_bf16 v[50:53], v[130:133], v[178:181], 0
	v_mfma_f32_16x16x32_bf16 v[54:57], v[138:141], v[178:181], 0
	v_mfma_f32_16x16x32_bf16 v[34:37], v[130:133], v[186:189], 0
	v_mfma_f32_16x16x32_bf16 v[38:41], v[138:141], v[186:189], 0
	v_mfma_f32_16x16x32_bf16 v[18:21], v[130:133], v[206:209], 0
	v_mfma_f32_16x16x32_bf16 v[22:25], v[138:141], v[206:209], 0
	v_mfma_f32_16x16x32_bf16 v[0:3], v[130:133], v[218:221], 0
	v_mfma_f32_16x16x32_bf16 v[4:7], v[138:141], v[218:221], 0
	v_mfma_f32_16x16x32_bf16 v[50:53], v[134:137], v[182:185], v[50:53]
	v_mfma_f32_16x16x32_bf16 v[54:57], v[142:145], v[182:185], v[54:57]
	v_mfma_f32_16x16x32_bf16 v[34:37], v[134:137], v[202:205], v[34:37]
	v_mfma_f32_16x16x32_bf16 v[38:41], v[142:145], v[202:205], v[38:41]
	v_mfma_f32_16x16x32_bf16 v[18:21], v[134:137], v[214:217], v[18:21]
	v_mfma_f32_16x16x32_bf16 v[22:25], v[142:145], v[214:217], v[22:25]
	v_mfma_f32_16x16x32_bf16 v[0:3], v[134:137], v[222:225], v[0:3]
	v_mfma_f32_16x16x32_bf16 v[4:7], v[142:145], v[222:225], v[4:7]
	s_barrier
	s_add_u32 s26, s36, 0x40000
	s_addc_u32 s27, s37, 0
	s_add_i32 s38, s39, s78
	s_mov_b32 m0, s38
	v_lshl_add_u64 v[130:131], s[26:27], 0, v[8:9]
	global_load_lds_dwordx4 v[130:131], off
	s_add_i32 m0, s38, 0x2000
	v_lshl_add_u64 v[130:131], s[26:27], 0, v[146:147]
	global_load_lds_dwordx4 v[130:131], off
	s_waitcnt vmcnt(6)
	ds_write_b128 v249, v[244:247]
	s_barrier
	v_mfma_f32_16x16x32_bf16 v[58:61], v[226:229], v[178:181], 0
	v_mfma_f32_16x16x32_bf16 v[62:65], v[234:237], v[178:181], 0
	v_mfma_f32_16x16x32_bf16 v[42:45], v[226:229], v[186:189], 0
	v_mfma_f32_16x16x32_bf16 v[46:49], v[234:237], v[186:189], 0
	v_mfma_f32_16x16x32_bf16 v[26:29], v[226:229], v[206:209], 0
	v_mfma_f32_16x16x32_bf16 v[30:33], v[234:237], v[206:209], 0
	v_mfma_f32_16x16x32_bf16 v[10:13], v[226:229], v[218:221], 0
	v_mfma_f32_16x16x32_bf16 v[14:17], v[234:237], v[218:221], 0
	v_mfma_f32_16x16x32_bf16 v[58:61], v[230:233], v[182:185], v[58:61]
	v_mfma_f32_16x16x32_bf16 v[62:65], v[238:241], v[182:185], v[62:65]
	v_mfma_f32_16x16x32_bf16 v[42:45], v[230:233], v[202:205], v[42:45]
	v_mfma_f32_16x16x32_bf16 v[46:49], v[238:241], v[202:205], v[46:49]
	v_mfma_f32_16x16x32_bf16 v[26:29], v[230:233], v[214:217], v[26:29]
	v_mfma_f32_16x16x32_bf16 v[30:33], v[238:241], v[214:217], v[30:33]
	v_mfma_f32_16x16x32_bf16 v[10:13], v[230:233], v[222:225], v[10:13]
	v_mfma_f32_16x16x32_bf16 v[14:17], v[238:241], v[222:225], v[14:17]
	s_add_i32 s38, 0, 0x18000
	v_add_u32_e32 v142, s38, v197
	s_barrier
	ds_read_b128 v[130:133], v142
	ds_read_b128 v[134:137], v142 offset:1024
	ds_read_b128 v[138:141], v142 offset:2048
	ds_read_b128 v[142:145], v142 offset:3072
	s_add_u32 s26, s46, 0x40000
	s_addc_u32 s27, s47, 0
	s_mov_b32 m0, s81
	v_lshl_add_u64 v[226:227], s[26:27], 0, v[150:151]
	ds_read_b128 v[178:181], v201 offset:32768
	ds_read_b128 v[182:185], v201 offset:33792
	ds_read_b128 v[186:189], v201 offset:34816
	ds_read_b128 v[202:205], v201 offset:35840
	ds_read_b128 v[206:209], v201 offset:36864
	ds_read_b128 v[214:217], v201 offset:37888
	ds_read_b128 v[218:221], v201 offset:38912
	ds_read_b128 v[222:225], v201 offset:39936
	global_load_lds_dwordx4 v[226:227], off
	s_mov_b32 m0, s82
	v_lshl_add_u64 v[226:227], s[26:27], 0, v[148:149]
	global_load_lds_dwordx4 v[226:227], off
	s_waitcnt lgkmcnt(8)
	s_barrier
	s_waitcnt lgkmcnt(0)
	v_mfma_f32_16x16x32_bf16 v[126:129], v[130:133], v[178:181], v[126:129]
	v_mfma_f32_16x16x32_bf16 v[122:125], v[138:141], v[178:181], v[122:125]
	v_mfma_f32_16x16x32_bf16 v[110:113], v[130:133], v[186:189], v[110:113]
	v_mfma_f32_16x16x32_bf16 v[106:109], v[138:141], v[186:189], v[106:109]
	v_mfma_f32_16x16x32_bf16 v[94:97], v[130:133], v[206:209], v[94:97]
	v_mfma_f32_16x16x32_bf16 v[90:93], v[138:141], v[206:209], v[90:93]
	v_mfma_f32_16x16x32_bf16 v[78:81], v[130:133], v[218:221], v[78:81]
	v_mfma_f32_16x16x32_bf16 v[74:77], v[138:141], v[218:221], v[74:77]
	v_mfma_f32_16x16x32_bf16 v[126:129], v[134:137], v[182:185], v[126:129]
	v_mfma_f32_16x16x32_bf16 v[122:125], v[142:145], v[182:185], v[122:125]
	v_mfma_f32_16x16x32_bf16 v[110:113], v[134:137], v[202:205], v[110:113]
	v_mfma_f32_16x16x32_bf16 v[106:109], v[142:145], v[202:205], v[106:109]
	v_mfma_f32_16x16x32_bf16 v[94:97], v[134:137], v[214:217], v[94:97]
	v_mfma_f32_16x16x32_bf16 v[90:93], v[142:145], v[214:217], v[90:93]
	v_mfma_f32_16x16x32_bf16 v[78:81], v[134:137], v[222:225], v[78:81]
	v_mfma_f32_16x16x32_bf16 v[74:77], v[142:145], v[222:225], v[74:77]
	s_barrier
; #define PG8_STAGE(bufoff, gbase, voff) do { _Pragma("unroll") for (int _i = 0; _i < 2; ++_i) \
;         __builtin_amdgcn_global_load_lds((const unsigned*)((const char*)(gbase) + (voff)[_i]), (LAS unsigned*)(lds + (bufoff) + ldsw + _i * 8192), 16, 0, 0); } while (0)
; #define PG8_LDA(dst, b, h) do { _Pragma("unroll") for (int m = 0; m < 4; ++m) _Pragma("unroll") for (int k = 0; k < 2; ++k) dst[m][k] = *(const LAS bf16x8*)(lds + PG8_SA(b, h) + aoff + m * 2048 + k * 1024); } while (0)
; #define PG8_LDB(dst, b, h) do { _Pragma("unroll") for (int n = 0; n < 2; ++n) _Pragma("unroll") for (int k = 0; k < 2; ++k) dst[n][k] = *(const LAS bf16x8*)(lds + PG8_SB(b, h) + boff + n * 2048 + k * 1024); } while (0)
; #define PG8_MMA(ai, bj, At, Bt) do { __builtin_amdgcn_s_setprio(1); _Pragma("unroll") for (int m = 0; m < 4; ++m) _Pragma("unroll") for (int n = 0; n < 2; ++n) _Pragma("unroll") for (int k = 0; k < 2; ++k) \
;         acc[ai][bj][m][n] = __builtin_amdgcn_mfma_f32_16x16x32_bf16(Bt[n][k], At[m][k], acc[ai][bj][m][n], 0, 0, 0); __builtin_amdgcn_s_setprio(0); } while (0)
; #define PG8_WAIT_V(n) asm volatile("s_waitcnt vmcnt(" #n ")" ::: "memory")
; #define PG8_WAIT_L(n) asm volatile("s_waitcnt lgkmcnt(" #n ")" ::: "memory")
; #define PG8_BAR __builtin_amdgcn_s_barrier()
; #define PG8_SCHED __builtin_amdgcn_sched_barrier(0)
; template <class Epi>
; DEVI void gemm_phase(LAS unsigned char* lds, const Gemm g, const Epi& E) {
;     ...
;             PG8_LDB(B1, 1, 1); PG8_STAGE(PG8_SB(1, 0), b3, voffB);
;             PG8_BAR; PG8_WAIT_L(0); PG8_MMA(0, 1, At, B1); PG8_BAR;
;             PG8_LDA(At, 1, 1); PG8_STAGE(PG8_SA(1, 0), a3, voffA);
;             PG8_BAR; PG8_WAIT_L(0); PG8_MMA(1, 0, At, B0); PG8_BAR; PG8_SCHED;
;             PG8_STAGE(PG8_SB(1, 1), b3 + hstepB, voffB);
;             PG8_WAIT_V(6); PG8_BAR; PG8_MMA(1, 1, At, B1); PG8_BAR;
	s_add_i32 s39, 0, 0x1c000
	s_add_i32 s26, s38, s78
	v_add_u32_e32 v192, s39, v197
	v_lshl_add_u64 v[162:163], v[162:163], 0, s[70:71]
	s_mov_b32 m0, s26
	ds_read_b128 v[226:229], v192
	ds_read_b128 v[230:233], v192 offset:1024
	ds_read_b128 v[234:237], v192 offset:2048
	ds_read_b128 v[238:241], v192 offset:3072
	global_load_lds_dwordx4 v[162:163], off
	s_add_i32 m0, s26, 0x2000
	v_lshl_add_u64 v[162:163], v[164:165], 0, s[70:71]
	global_load_lds_dwordx4 v[162:163], off
	s_barrier
	s_waitcnt lgkmcnt(0)
	v_mfma_f32_16x16x32_bf16 v[118:121], v[226:229], v[178:181], v[118:121]
	v_mfma_f32_16x16x32_bf16 v[114:117], v[234:237], v[178:181], v[114:117]
	v_mfma_f32_16x16x32_bf16 v[102:105], v[226:229], v[186:189], v[102:105]
	v_mfma_f32_16x16x32_bf16 v[98:101], v[234:237], v[186:189], v[98:101]
	v_mfma_f32_16x16x32_bf16 v[86:89], v[226:229], v[206:209], v[86:89]
	v_mfma_f32_16x16x32_bf16 v[82:85], v[234:237], v[206:209], v[82:85]
	v_mfma_f32_16x16x32_bf16 v[70:73], v[226:229], v[218:221], v[70:73]
	v_mfma_f32_16x16x32_bf16 v[66:69], v[234:237], v[218:221], v[66:69]
	v_mfma_f32_16x16x32_bf16 v[118:121], v[230:233], v[182:185], v[118:121]
	v_mfma_f32_16x16x32_bf16 v[114:117], v[238:241], v[182:185], v[114:117]
	v_mfma_f32_16x16x32_bf16 v[102:105], v[230:233], v[202:205], v[102:105]
	v_mfma_f32_16x16x32_bf16 v[98:101], v[238:241], v[202:205], v[98:101]
	v_mfma_f32_16x16x32_bf16 v[86:89], v[230:233], v[214:217], v[86:89]
	v_mfma_f32_16x16x32_bf16 v[82:85], v[238:241], v[214:217], v[82:85]
	v_mfma_f32_16x16x32_bf16 v[70:73], v[230:233], v[222:225], v[70:73]
	v_mfma_f32_16x16x32_bf16 v[66:69], v[238:241], v[222:225], v[66:69]
	s_mov_b32 m0, s83
	v_lshl_add_u64 v[162:163], v[190:191], 0, s[70:71]
	s_barrier
	ds_read_b128 v[178:181], v201 offset:49152
	ds_read_b128 v[182:185], v201 offset:50176
	ds_read_b128 v[186:189], v201 offset:51200
	ds_read_b128 v[202:205], v201 offset:52224
	ds_read_b128 v[206:209], v201 offset:53248
	ds_read_b128 v[214:217], v201 offset:54272
	ds_read_b128 v[218:221], v201 offset:55296
	ds_read_b128 v[222:225], v201 offset:56320
	global_load_lds_dwordx4 v[162:163], off
	s_mov_b32 m0, s84
	v_lshl_add_u64 v[162:163], v[194:195], 0, s[70:71]
	global_load_lds_dwordx4 v[162:163], off
	s_barrier
	s_waitcnt lgkmcnt(0)
	v_mfma_f32_16x16x32_bf16 v[50:53], v[130:133], v[178:181], v[50:53]
	v_mfma_f32_16x16x32_bf16 v[54:57], v[138:141], v[178:181], v[54:57]
	v_mfma_f32_16x16x32_bf16 v[34:37], v[130:133], v[186:189], v[34:37]
	v_mfma_f32_16x16x32_bf16 v[38:41], v[138:141], v[186:189], v[38:41]
	v_mfma_f32_16x16x32_bf16 v[18:21], v[130:133], v[206:209], v[18:21]
	v_mfma_f32_16x16x32_bf16 v[22:25], v[138:141], v[206:209], v[22:25]
	v_mfma_f32_16x16x32_bf16 v[0:3], v[130:133], v[218:221], v[0:3]
	v_mfma_f32_16x16x32_bf16 v[4:7], v[138:141], v[218:221], v[4:7]
	v_mfma_f32_16x16x32_bf16 v[50:53], v[134:137], v[182:185], v[50:53]
	v_mfma_f32_16x16x32_bf16 v[54:57], v[142:145], v[182:185], v[54:57]
	v_mfma_f32_16x16x32_bf16 v[34:37], v[134:137], v[202:205], v[34:37]
	v_mfma_f32_16x16x32_bf16 v[38:41], v[142:145], v[202:205], v[38:41]
	v_mfma_f32_16x16x32_bf16 v[18:21], v[134:137], v[214:217], v[18:21]
	v_mfma_f32_16x16x32_bf16 v[22:25], v[142:145], v[214:217], v[22:25]
	v_mfma_f32_16x16x32_bf16 v[0:3], v[134:137], v[222:225], v[0:3]
	v_mfma_f32_16x16x32_bf16 v[4:7], v[142:145], v[222:225], v[4:7]
	s_barrier
	s_add_u32 s26, s36, 0x40080
	s_addc_u32 s27, s37, 0
	s_add_i32 s36, s39, s78
	s_mov_b32 m0, s36
	v_lshl_add_u64 v[130:131], s[26:27], 0, v[8:9]
	global_load_lds_dwordx4 v[130:131], off
	s_add_i32 m0, s36, 0x2000
	v_lshl_add_u64 v[130:131], s[26:27], 0, v[146:147]
	global_load_lds_dwordx4 v[130:131], off
	s_waitcnt vmcnt(6)
	s_barrier
	v_mfma_f32_16x16x32_bf16 v[58:61], v[226:229], v[178:181], v[58:61]
	v_mfma_f32_16x16x32_bf16 v[62:65], v[234:237], v[178:181], v[62:65]
	v_mfma_f32_16x16x32_bf16 v[42:45], v[226:229], v[186:189], v[42:45]
	v_mfma_f32_16x16x32_bf16 v[46:49], v[234:237], v[186:189], v[46:49]
	v_mfma_f32_16x16x32_bf16 v[26:29], v[226:229], v[206:209], v[26:29]
	v_mfma_f32_16x16x32_bf16 v[30:33], v[234:237], v[206:209], v[30:33]
	v_mfma_f32_16x16x32_bf16 v[10:13], v[226:229], v[218:221], v[10:13]
	v_mfma_f32_16x16x32_bf16 v[14:17], v[234:237], v[218:221], v[14:17]
	v_mfma_f32_16x16x32_bf16 v[58:61], v[230:233], v[182:185], v[58:61]
	v_mfma_f32_16x16x32_bf16 v[62:65], v[238:241], v[182:185], v[62:65]
	v_mfma_f32_16x16x32_bf16 v[42:45], v[230:233], v[202:205], v[42:45]
	v_mfma_f32_16x16x32_bf16 v[46:49], v[238:241], v[202:205], v[46:49]
	v_mfma_f32_16x16x32_bf16 v[26:29], v[230:233], v[214:217], v[26:29]
	v_mfma_f32_16x16x32_bf16 v[30:33], v[238:241], v[214:217], v[30:33]
	v_mfma_f32_16x16x32_bf16 v[10:13], v[230:233], v[222:225], v[10:13]
	v_mfma_f32_16x16x32_bf16 v[14:17], v[238:241], v[222:225], v[14:17]
	s_add_i32 s19, s19, 2
	s_add_u32 s16, s16, 0x100
	s_addc_u32 s17, s17, 0
	s_add_u32 s9, s9, 0x100
	s_addc_u32 s18, s18, 0
	s_cmp_gt_u32 s19, 13
	s_barrier

; DEVI size_t gemm_offB(const Gemm& g, const Unit& u) { return (g.split ? (size_t)(u.b >> 2) * g.sB + (size_t)(u.b & 3) * g.sB_lo : (size_t)u.b * g.sB) + (size_t)(u.pm >> g.pmsh) * g.sBpm; }
; #define PG8_STAGE(bufoff, gbase, voff) do { _Pragma("unroll") for (int _i = 0; _i < 2; ++_i) \
;         __builtin_amdgcn_global_load_lds((const unsigned*)((const char*)(gbase) + (voff)[_i]), (LAS unsigned*)(lds + (bufoff) + ldsw + _i * 8192), 16, 0, 0); } while (0)
; #define PG8_LDA(dst, b, h) do { _Pragma("unroll") for (int m = 0; m < 4; ++m) _Pragma("unroll") for (int k = 0; k < 2; ++k) dst[m][k] = *(const LAS bf16x8*)(lds + PG8_SA(b, h) + aoff + m * 2048 + k * 1024); } while (0)
; #define PG8_LDB(dst, b, h) do { _Pragma("unroll") for (int n = 0; n < 2; ++n) _Pragma("unroll") for (int k = 0; k < 2; ++k) dst[n][k] = *(const LAS bf16x8*)(lds + PG8_SB(b, h) + boff + n * 2048 + k * 1024); } while (0)
; #define PG8_WAIT_L(n) asm volatile("s_waitcnt lgkmcnt(" #n ")" ::: "memory")
; #define PG8_BAR __builtin_amdgcn_s_barrier()
; #define PG8_SCHED __builtin_amdgcn_sched_barrier(0)
; template <class Epi>
; DEVI void gemm_phase(LAS unsigned char* lds, const Gemm g, const Epi& E) {
;     ...
;         const bool has_next = unit_next(g, ui + 1, nxt);
;         const char* nA = has_next ? (const char*)g.A + gemm_offA(g, nxt) * 2 + (size_t)nxt.pm * tstepA : cA;
;         const char* nB = has_next ? (const char*)g.Bt + gemm_offB(g, nxt) * 2 + (size_t)nxt.pn * tstepB : cB;
;         for (int t = 0; t < nt; t += 2) {
;             const bool last = (t == nt - 2);
;             const char* a1 = cA + (size_t)(t + 1) * kstep;
;             const char* a2 = last ? nA : cA + (size_t)(t + 2) * kstep; const char* b2 = last ? nB : cB + (size_t)(t + 2) * kstep;
;             const char* a3 = a2 + kstep; const char* b3 = b2 + kstep;
;             PG8_LDB(B0, 0, 0); PG8_SCHED; PG8_LDA(At, 0, 0); PG8_STAGE(PG8_SA(1, 1), a1 + hstepA, voffA);
;             PG8_WAIT_L(8); PG8_BAR; PG8_WAIT_L(0); PG8_MMA(0, 0, At, B0); PG8_BAR; PG8_SCHED;
;             PG8_LDB(B1, 0, 1); PG8_STAGE(PG8_SB(0, 0), b2, voffB);
;             PG8_BAR; PG8_WAIT_L(0); PG8_MMA(0, 1, At, B1); PG8_BAR;
;             PG8_LDA(At, 0, 1); PG8_STAGE(PG8_SA(0, 0), a2, voffA);
;             PG8_BAR; PG8_WAIT_L(0); PG8_MMA(1, 0, At, B0); PG8_BAR; PG8_SCHED;
.LBB0_1746:
	s_add_u32 s1, s36, 0x100
	s_addc_u32 s13, s37, 0
	s_mov_b32 s18, -2
	s_waitcnt lgkmcnt(0)
	s_nop 0
	s_nop 0
	s_nop 0
	s_nop 0
	s_nop 0
	s_add_u32 s36, s16, 0x100
	s_addc_u32 s37, s17, 0
	s_add_i32 s19, 0, 0x10000
	v_add_u32_e32 v142, s19, v191
	ds_read_b128 v[130:133], v142
	ds_read_b128 v[134:137], v142 offset:1024
	ds_read_b128 v[138:141], v142 offset:2048
	ds_read_b128 v[142:145], v142 offset:3072
	s_cmp_eq_u32 s18, 40
	s_cselect_b32 s69, s9, s37
	s_cselect_b32 s68, s8, s36
	s_cselect_b32 s47, s11, s13
	s_cselect_b32 s46, s10, s1
	v_lshl_add_u64 v[162:163], s[16:17], 0, v[152:153]
	s_add_i32 m0, s81, 0xc000
	ds_read_b128 v[178:181], v196
	ds_read_b128 v[182:185], v196 offset:1024
	ds_read_b128 v[186:189], v196 offset:2048
	ds_read_b128 v[198:201], v196 offset:3072
	ds_read_b128 v[202:205], v196 offset:4096
	ds_read_b128 v[206:209], v196 offset:5120
	ds_read_b128 v[214:217], v196 offset:6144
	ds_read_b128 v[218:221], v196 offset:7168
	global_load_lds_dwordx4 v[162:163], off
	s_add_i32 m0, s81, 0xe000
	v_lshl_add_u64 v[162:163], s[16:17], 0, v[176:177]
	global_load_lds_dwordx4 v[162:163], off
	s_waitcnt lgkmcnt(8)
	s_barrier
	s_waitcnt lgkmcnt(0)
	v_mfma_f32_16x16x32_bf16 v[126:129], v[130:133], v[178:181], 0
	v_mfma_f32_16x16x32_bf16 v[122:125], v[138:141], v[178:181], 0
	v_mfma_f32_16x16x32_bf16 v[110:113], v[130:133], v[186:189], 0
	v_mfma_f32_16x16x32_bf16 v[106:109], v[138:141], v[186:189], 0
	v_mfma_f32_16x16x32_bf16 v[94:97], v[130:133], v[202:205], 0
	v_mfma_f32_16x16x32_bf16 v[90:93], v[138:141], v[202:205], 0
	v_mfma_f32_16x16x32_bf16 v[78:81], v[130:133], v[214:217], 0
	v_mfma_f32_16x16x32_bf16 v[74:77], v[138:141], v[214:217], 0
	v_mfma_f32_16x16x32_bf16 v[126:129], v[134:137], v[182:185], v[126:129]
	v_mfma_f32_16x16x32_bf16 v[122:125], v[142:145], v[182:185], v[122:125]
	v_mfma_f32_16x16x32_bf16 v[110:113], v[134:137], v[198:201], v[110:113]
	v_mfma_f32_16x16x32_bf16 v[106:109], v[142:145], v[198:201], v[106:109]
	v_mfma_f32_16x16x32_bf16 v[94:97], v[134:137], v[206:209], v[94:97]
	v_mfma_f32_16x16x32_bf16 v[90:93], v[142:145], v[206:209], v[90:93]
	v_mfma_f32_16x16x32_bf16 v[78:81], v[134:137], v[218:221], v[78:81]
	v_mfma_f32_16x16x32_bf16 v[74:77], v[142:145], v[218:221], v[74:77]
	s_barrier
	s_add_i32 s26, 0, 0x14000
	v_add_u32_e32 v162, s26, v191
	s_add_i32 s16, s19, s80
	ds_read_b128 v[222:225], v162
	ds_read_b128 v[226:229], v162 offset:1024
	ds_read_b128 v[230:233], v162 offset:2048
	ds_read_b128 v[234:237], v162 offset:3072
	v_lshl_add_u64 v[162:163], s[46:47], 0, v[8:9]
	s_mov_b32 m0, s16
	v_lshl_add_u64 v[164:165], s[46:47], 0, v[150:151]
	global_load_lds_dwordx4 v[162:163], off
	s_add_i32 m0, s16, 0x2000
	s_nop 0
	global_load_lds_dwordx4 v[164:165], off
	s_barrier
	s_waitcnt lgkmcnt(0)
	v_mfma_f32_16x16x32_bf16 v[118:121], v[222:225], v[178:181], 0
	v_mfma_f32_16x16x32_bf16 v[114:117], v[230:233], v[178:181], 0
	v_mfma_f32_16x16x32_bf16 v[102:105], v[222:225], v[186:189], 0
	v_mfma_f32_16x16x32_bf16 v[98:101], v[230:233], v[186:189], 0
	v_mfma_f32_16x16x32_bf16 v[86:89], v[222:225], v[202:205], 0
	v_mfma_f32_16x16x32_bf16 v[82:85], v[230:233], v[202:205], 0
	v_mfma_f32_16x16x32_bf16 v[70:73], v[222:225], v[214:217], 0
	v_mfma_f32_16x16x32_bf16 v[66:69], v[230:233], v[214:217], 0
	v_mfma_f32_16x16x32_bf16 v[118:121], v[226:229], v[182:185], v[118:121]
	v_mfma_f32_16x16x32_bf16 v[114:117], v[234:237], v[182:185], v[114:117]
	v_mfma_f32_16x16x32_bf16 v[102:105], v[226:229], v[198:201], v[102:105]
	v_mfma_f32_16x16x32_bf16 v[98:101], v[234:237], v[198:201], v[98:101]
	v_mfma_f32_16x16x32_bf16 v[86:89], v[226:229], v[206:209], v[86:89]
	v_mfma_f32_16x16x32_bf16 v[82:85], v[234:237], v[206:209], v[82:85]
	v_mfma_f32_16x16x32_bf16 v[70:73], v[226:229], v[218:221], v[70:73]
	v_mfma_f32_16x16x32_bf16 v[66:69], v[234:237], v[218:221], v[66:69]
	s_mov_b32 m0, s81
	v_lshl_add_u64 v[238:239], s[68:69], 0, v[146:147]
	s_barrier
	ds_read_b128 v[178:181], v196 offset:16384
	ds_read_b128 v[182:185], v196 offset:17408
	ds_read_b128 v[186:189], v196 offset:18432
	ds_read_b128 v[198:201], v196 offset:19456
	ds_read_b128 v[202:205], v196 offset:20480
	ds_read_b128 v[206:209], v196 offset:21504
	ds_read_b128 v[214:217], v196 offset:22528
	ds_read_b128 v[218:221], v196 offset:23552
	global_load_lds_dwordx4 v[238:239], off
	s_mov_b32 m0, s82
	v_lshl_add_u64 v[240:241], s[68:69], 0, v[148:149]
	global_load_lds_dwordx4 v[240:241], off
	s_barrier
	s_waitcnt lgkmcnt(0)
	v_mfma_f32_16x16x32_bf16 v[62:65], v[130:133], v[178:181], 0
	v_mfma_f32_16x16x32_bf16 v[58:61], v[138:141], v[178:181], 0
	v_mfma_f32_16x16x32_bf16 v[46:49], v[130:133], v[186:189], 0
	v_mfma_f32_16x16x32_bf16 v[42:45], v[138:141], v[186:189], 0
	v_mfma_f32_16x16x32_bf16 v[30:33], v[130:133], v[202:205], 0
	v_mfma_f32_16x16x32_bf16 v[26:29], v[138:141], v[202:205], 0
	v_mfma_f32_16x16x32_bf16 v[14:17], v[130:133], v[214:217], 0
	v_mfma_f32_16x16x32_bf16 v[10:13], v[138:141], v[214:217], 0
	v_mfma_f32_16x16x32_bf16 v[62:65], v[134:137], v[182:185], v[62:65]
	v_mfma_f32_16x16x32_bf16 v[58:61], v[142:145], v[182:185], v[58:61]
	v_mfma_f32_16x16x32_bf16 v[46:49], v[134:137], v[198:201], v[46:49]
	v_mfma_f32_16x16x32_bf16 v[42:45], v[142:145], v[198:201], v[42:45]
	v_mfma_f32_16x16x32_bf16 v[30:33], v[134:137], v[206:209], v[30:33]
	v_mfma_f32_16x16x32_bf16 v[26:29], v[142:145], v[206:209], v[26:29]
	v_mfma_f32_16x16x32_bf16 v[14:17], v[134:137], v[218:221], v[14:17]
	v_mfma_f32_16x16x32_bf16 v[10:13], v[142:145], v[218:221], v[10:13]
	s_barrier
; #define PG8_STAGE(bufoff, gbase, voff) do { _Pragma("unroll") for (int _i = 0; _i < 2; ++_i) \
;         __builtin_amdgcn_global_load_lds((const unsigned*)((const char*)(gbase) + (voff)[_i]), (LAS unsigned*)(lds + (bufoff) + ldsw + _i * 8192), 16, 0, 0); } while (0)
; #define PG8_LDA(dst, b, h) do { _Pragma("unroll") for (int m = 0; m < 4; ++m) _Pragma("unroll") for (int k = 0; k < 2; ++k) dst[m][k] = *(const LAS bf16x8*)(lds + PG8_SA(b, h) + aoff + m * 2048 + k * 1024); } while (0)
; #define PG8_LDB(dst, b, h) do { _Pragma("unroll") for (int n = 0; n < 2; ++n) _Pragma("unroll") for (int k = 0; k < 2; ++k) dst[n][k] = *(const LAS bf16x8*)(lds + PG8_SB(b, h) + boff + n * 2048 + k * 1024); } while (0)
; #define PG8_MMA(ai, bj, At, Bt) do { __builtin_amdgcn_s_setprio(1); _Pragma("unroll") for (int m = 0; m < 4; ++m) _Pragma("unroll") for (int n = 0; n < 2; ++n) _Pragma("unroll") for (int k = 0; k < 2; ++k) \
;         acc[ai][bj][m][n] = __builtin_amdgcn_mfma_f32_16x16x32_bf16(Bt[n][k], At[m][k], acc[ai][bj][m][n], 0, 0, 0); __builtin_amdgcn_s_setprio(0); } while (0)
; #define PG8_WAIT_V(n) asm volatile("s_waitcnt vmcnt(" #n ")" ::: "memory")
; #define PG8_WAIT_L(n) asm volatile("s_waitcnt lgkmcnt(" #n ")" ::: "memory")
; #define PG8_BAR __builtin_amdgcn_s_barrier()
; #define PG8_SCHED __builtin_amdgcn_sched_barrier(0)
; template <class Epi>
; DEVI void gemm_phase(LAS unsigned char* lds, const Gemm g, const Epi& E) {
;     ...
;             PG8_STAGE(PG8_SB(0, 1), b2 + hstepB, voffB);
;             PG8_WAIT_V(6); PG8_BAR; PG8_MMA(1, 1, At, B1); PG8_BAR;
;             PG8_LDB(B0, 1, 0); PG8_SCHED; PG8_LDA(At, 1, 0); PG8_STAGE(PG8_SA(0, 1), a2 + hstepA, voffA);
;             PG8_WAIT_L(8); PG8_BAR; PG8_WAIT_L(0); PG8_MMA(0, 0, At, B0); PG8_BAR; PG8_SCHED;
;             PG8_LDB(B1, 1, 1); PG8_STAGE(PG8_SB(1, 0), b3, voffB);
	s_add_u32 s16, s46, 0xb0000
	s_addc_u32 s17, s47, 0
	s_add_i32 s19, s26, s80
	s_mov_b32 m0, s19
	v_lshl_add_u64 v[130:131], s[16:17], 0, v[8:9]
	global_load_lds_dwordx4 v[130:131], off
	s_add_i32 m0, s19, 0x2000
	v_lshl_add_u64 v[130:131], s[16:17], 0, v[150:151]
	global_load_lds_dwordx4 v[130:131], off
	s_waitcnt vmcnt(6)
	s_barrier
	v_mfma_f32_16x16x32_bf16 v[54:57], v[222:225], v[178:181], 0
	v_mfma_f32_16x16x32_bf16 v[50:53], v[230:233], v[178:181], 0
	v_mfma_f32_16x16x32_bf16 v[38:41], v[222:225], v[186:189], 0
	v_mfma_f32_16x16x32_bf16 v[34:37], v[230:233], v[186:189], 0
	v_mfma_f32_16x16x32_bf16 v[22:25], v[222:225], v[202:205], 0
	v_mfma_f32_16x16x32_bf16 v[18:21], v[230:233], v[202:205], 0
	v_mfma_f32_16x16x32_bf16 v[4:7], v[222:225], v[214:217], 0
	v_mfma_f32_16x16x32_bf16 v[0:3], v[230:233], v[214:217], 0
	v_mfma_f32_16x16x32_bf16 v[54:57], v[226:229], v[182:185], v[54:57]
	v_mfma_f32_16x16x32_bf16 v[50:53], v[234:237], v[182:185], v[50:53]
	v_mfma_f32_16x16x32_bf16 v[38:41], v[226:229], v[198:201], v[38:41]
	v_mfma_f32_16x16x32_bf16 v[34:37], v[234:237], v[198:201], v[34:37]
	v_mfma_f32_16x16x32_bf16 v[22:25], v[226:229], v[206:209], v[22:25]
	v_mfma_f32_16x16x32_bf16 v[18:21], v[234:237], v[206:209], v[18:21]
	v_mfma_f32_16x16x32_bf16 v[4:7], v[226:229], v[218:221], v[4:7]
	v_mfma_f32_16x16x32_bf16 v[0:3], v[234:237], v[218:221], v[0:3]
	s_add_i32 s19, 0, 0x18000
	v_add_u32_e32 v142, s19, v191
	s_barrier
	ds_read_b128 v[130:133], v142
	ds_read_b128 v[134:137], v142 offset:1024
	ds_read_b128 v[138:141], v142 offset:2048
	ds_read_b128 v[142:145], v142 offset:3072
	s_add_u32 s16, s68, 0xb0000
	s_addc_u32 s17, s69, 0
	s_mov_b32 m0, s83
	v_lshl_add_u64 v[222:223], s[16:17], 0, v[146:147]
	ds_read_b128 v[178:181], v196 offset:32768
	ds_read_b128 v[182:185], v196 offset:33792
	ds_read_b128 v[186:189], v196 offset:34816
	ds_read_b128 v[198:201], v196 offset:35840
	ds_read_b128 v[202:205], v196 offset:36864
	ds_read_b128 v[206:209], v196 offset:37888
	ds_read_b128 v[214:217], v196 offset:38912
	ds_read_b128 v[218:221], v196 offset:39936
	global_load_lds_dwordx4 v[222:223], off
	s_mov_b32 m0, s84
	v_lshl_add_u64 v[222:223], s[16:17], 0, v[148:149]
	global_load_lds_dwordx4 v[222:223], off
	s_waitcnt lgkmcnt(8)
	s_barrier
	s_waitcnt lgkmcnt(0)
	v_mfma_f32_16x16x32_bf16 v[126:129], v[130:133], v[178:181], v[126:129]
	v_mfma_f32_16x16x32_bf16 v[122:125], v[138:141], v[178:181], v[122:125]
	v_mfma_f32_16x16x32_bf16 v[110:113], v[130:133], v[186:189], v[110:113]
	v_mfma_f32_16x16x32_bf16 v[106:109], v[138:141], v[186:189], v[106:109]
	v_mfma_f32_16x16x32_bf16 v[94:97], v[130:133], v[202:205], v[94:97]
	v_mfma_f32_16x16x32_bf16 v[90:93], v[138:141], v[202:205], v[90:93]
	v_mfma_f32_16x16x32_bf16 v[78:81], v[130:133], v[214:217], v[78:81]
	v_mfma_f32_16x16x32_bf16 v[74:77], v[138:141], v[214:217], v[74:77]
	v_mfma_f32_16x16x32_bf16 v[126:129], v[134:137], v[182:185], v[126:129]
	v_mfma_f32_16x16x32_bf16 v[122:125], v[142:145], v[182:185], v[122:125]
	v_mfma_f32_16x16x32_bf16 v[110:113], v[134:137], v[198:201], v[110:113]
	v_mfma_f32_16x16x32_bf16 v[106:109], v[142:145], v[198:201], v[106:109]
	v_mfma_f32_16x16x32_bf16 v[94:97], v[134:137], v[206:209], v[94:97]
	v_mfma_f32_16x16x32_bf16 v[90:93], v[142:145], v[206:209], v[90:93]
	v_mfma_f32_16x16x32_bf16 v[78:81], v[134:137], v[218:221], v[78:81]
	v_mfma_f32_16x16x32_bf16 v[74:77], v[142:145], v[218:221], v[74:77]
	s_barrier
	s_add_i32 s26, 0, 0x1c000
	s_add_i32 s16, s19, s80
	v_add_u32_e32 v197, s26, v191
	v_lshl_add_u64 v[162:163], v[162:163], 0, s[70:71]
	s_mov_b32 m0, s16
	ds_read_b128 v[222:225], v197
	ds_read_b128 v[226:229], v197 offset:1024
	ds_read_b128 v[230:233], v197 offset:2048
	ds_read_b128 v[234:237], v197 offset:3072
	global_load_lds_dwordx4 v[162:163], off
	s_add_i32 m0, s16, 0x2000
	v_lshl_add_u64 v[162:163], v[164:165], 0, s[70:71]
	global_load_lds_dwordx4 v[162:163], off
	s_barrier
; #define PG8_STAGE(bufoff, gbase, voff) do { _Pragma("unroll") for (int _i = 0; _i < 2; ++_i) \
;         __builtin_amdgcn_global_load_lds((const unsigned*)((const char*)(gbase) + (voff)[_i]), (LAS unsigned*)(lds + (bufoff) + ldsw + _i * 8192), 16, 0, 0); } while (0)
; #define PG8_LDA(dst, b, h) do { _Pragma("unroll") for (int m = 0; m < 4; ++m) _Pragma("unroll") for (int k = 0; k < 2; ++k) dst[m][k] = *(const LAS bf16x8*)(lds + PG8_SA(b, h) + aoff + m * 2048 + k * 1024); } while (0)
; #define PG8_MMA(ai, bj, At, Bt) do { __builtin_amdgcn_s_setprio(1); _Pragma("unroll") for (int m = 0; m < 4; ++m) _Pragma("unroll") for (int n = 0; n < 2; ++n) _Pragma("unroll") for (int k = 0; k < 2; ++k) \
;         acc[ai][bj][m][n] = __builtin_amdgcn_mfma_f32_16x16x32_bf16(Bt[n][k], At[m][k], acc[ai][bj][m][n], 0, 0, 0); __builtin_amdgcn_s_setprio(0); } while (0)
; #define PG8_WAIT_V(n) asm volatile("s_waitcnt vmcnt(" #n ")" ::: "memory")
; #define PG8_WAIT_L(n) asm volatile("s_waitcnt lgkmcnt(" #n ")" ::: "memory")
; #define PG8_BAR __builtin_amdgcn_s_barrier()
; #define PG8_SCHED __builtin_amdgcn_sched_barrier(0)
; template <class Epi>
; DEVI void gemm_phase(LAS unsigned char* lds, const Gemm g, const Epi& E) {
;     ...
;             PG8_BAR; PG8_WAIT_L(0); PG8_MMA(0, 1, At, B1); PG8_BAR;
;             PG8_LDA(At, 1, 1); PG8_STAGE(PG8_SA(1, 0), a3, voffA);
;             PG8_BAR; PG8_WAIT_L(0); PG8_MMA(1, 0, At, B0); PG8_BAR; PG8_SCHED;
;             PG8_STAGE(PG8_SB(1, 1), b3 + hstepB, voffB);
;             PG8_WAIT_V(6); PG8_BAR; PG8_MMA(1, 1, At, B1); PG8_BAR;
	s_waitcnt lgkmcnt(0)
	v_mfma_f32_16x16x32_bf16 v[118:121], v[222:225], v[178:181], v[118:121]
	v_mfma_f32_16x16x32_bf16 v[114:117], v[230:233], v[178:181], v[114:117]
	v_mfma_f32_16x16x32_bf16 v[102:105], v[222:225], v[186:189], v[102:105]
	v_mfma_f32_16x16x32_bf16 v[98:101], v[230:233], v[186:189], v[98:101]
	v_mfma_f32_16x16x32_bf16 v[86:89], v[222:225], v[202:205], v[86:89]
	v_mfma_f32_16x16x32_bf16 v[82:85], v[230:233], v[202:205], v[82:85]
	v_mfma_f32_16x16x32_bf16 v[70:73], v[222:225], v[214:217], v[70:73]
	v_mfma_f32_16x16x32_bf16 v[66:69], v[230:233], v[214:217], v[66:69]
	v_mfma_f32_16x16x32_bf16 v[118:121], v[226:229], v[182:185], v[118:121]
	v_mfma_f32_16x16x32_bf16 v[114:117], v[234:237], v[182:185], v[114:117]
	v_mfma_f32_16x16x32_bf16 v[102:105], v[226:229], v[198:201], v[102:105]
	v_mfma_f32_16x16x32_bf16 v[98:101], v[234:237], v[198:201], v[98:101]
	v_mfma_f32_16x16x32_bf16 v[86:89], v[226:229], v[206:209], v[86:89]
	v_mfma_f32_16x16x32_bf16 v[82:85], v[234:237], v[206:209], v[82:85]
	v_mfma_f32_16x16x32_bf16 v[70:73], v[226:229], v[218:221], v[70:73]
	v_mfma_f32_16x16x32_bf16 v[66:69], v[234:237], v[218:221], v[66:69]
	s_mov_b32 m0, s76
	v_lshl_add_u64 v[162:163], v[238:239], 0, s[70:71]
	s_barrier
	ds_read_b128 v[178:181], v196 offset:49152
	ds_read_b128 v[182:185], v196 offset:50176
	ds_read_b128 v[186:189], v196 offset:51200
	ds_read_b128 v[198:201], v196 offset:52224
	ds_read_b128 v[202:205], v196 offset:53248
	ds_read_b128 v[206:209], v196 offset:54272
	ds_read_b128 v[214:217], v196 offset:55296
	ds_read_b128 v[218:221], v196 offset:56320
	global_load_lds_dwordx4 v[162:163], off
	s_mov_b32 m0, s77
	v_lshl_add_u64 v[162:163], v[240:241], 0, s[70:71]
	global_load_lds_dwordx4 v[162:163], off
	s_barrier
	s_waitcnt lgkmcnt(0)
	v_mfma_f32_16x16x32_bf16 v[62:65], v[130:133], v[178:181], v[62:65]
	v_mfma_f32_16x16x32_bf16 v[58:61], v[138:141], v[178:181], v[58:61]
	v_mfma_f32_16x16x32_bf16 v[46:49], v[130:133], v[186:189], v[46:49]
	v_mfma_f32_16x16x32_bf16 v[42:45], v[138:141], v[186:189], v[42:45]
	v_mfma_f32_16x16x32_bf16 v[30:33], v[130:133], v[202:205], v[30:33]
	v_mfma_f32_16x16x32_bf16 v[26:29], v[138:141], v[202:205], v[26:29]
	v_mfma_f32_16x16x32_bf16 v[14:17], v[130:133], v[214:217], v[14:17]
	v_mfma_f32_16x16x32_bf16 v[10:13], v[138:141], v[214:217], v[10:13]
	v_mfma_f32_16x16x32_bf16 v[62:65], v[134:137], v[182:185], v[62:65]
	v_mfma_f32_16x16x32_bf16 v[58:61], v[142:145], v[182:185], v[58:61]
	v_mfma_f32_16x16x32_bf16 v[46:49], v[134:137], v[198:201], v[46:49]
	v_mfma_f32_16x16x32_bf16 v[42:45], v[142:145], v[198:201], v[42:45]
	v_mfma_f32_16x16x32_bf16 v[30:33], v[134:137], v[206:209], v[30:33]
	v_mfma_f32_16x16x32_bf16 v[26:29], v[142:145], v[206:209], v[26:29]
	v_mfma_f32_16x16x32_bf16 v[14:17], v[134:137], v[218:221], v[14:17]
	v_mfma_f32_16x16x32_bf16 v[10:13], v[142:145], v[218:221], v[10:13]
	s_barrier
	s_add_u32 s16, s46, 0xb0080
	s_addc_u32 s17, s47, 0
	s_add_i32 s19, s26, s80
	s_mov_b32 m0, s19
	v_lshl_add_u64 v[130:131], s[16:17], 0, v[8:9]
	global_load_lds_dwordx4 v[130:131], off
	s_add_i32 m0, s19, 0x2000
	v_lshl_add_u64 v[130:131], s[16:17], 0, v[150:151]
	global_load_lds_dwordx4 v[130:131], off
	s_waitcnt vmcnt(6)
	s_barrier
	v_mfma_f32_16x16x32_bf16 v[54:57], v[222:225], v[178:181], v[54:57]
	v_mfma_f32_16x16x32_bf16 v[50:53], v[230:233], v[178:181], v[50:53]
	v_mfma_f32_16x16x32_bf16 v[38:41], v[222:225], v[186:189], v[38:41]
	v_mfma_f32_16x16x32_bf16 v[34:37], v[230:233], v[186:189], v[34:37]
	v_mfma_f32_16x16x32_bf16 v[22:25], v[222:225], v[202:205], v[22:25]
	v_mfma_f32_16x16x32_bf16 v[18:21], v[230:233], v[202:205], v[18:21]
	v_mfma_f32_16x16x32_bf16 v[4:7], v[222:225], v[214:217], v[4:7]
	v_mfma_f32_16x16x32_bf16 v[0:3], v[230:233], v[214:217], v[0:3]
	v_mfma_f32_16x16x32_bf16 v[54:57], v[226:229], v[182:185], v[54:57]
	v_mfma_f32_16x16x32_bf16 v[50:53], v[234:237], v[182:185], v[50:53]
	v_mfma_f32_16x16x32_bf16 v[38:41], v[226:229], v[198:201], v[38:41]
	v_mfma_f32_16x16x32_bf16 v[34:37], v[234:237], v[198:201], v[34:37]
	v_mfma_f32_16x16x32_bf16 v[22:25], v[226:229], v[206:209], v[22:25]
	v_mfma_f32_16x16x32_bf16 v[18:21], v[234:237], v[206:209], v[18:21]
	v_mfma_f32_16x16x32_bf16 v[4:7], v[226:229], v[218:221], v[4:7]
	v_mfma_f32_16x16x32_bf16 v[0:3], v[234:237], v[218:221], v[0:3]
	s_add_i32 s18, s18, 2
	s_add_u32 s1, s1, 0x100
	s_addc_u32 s13, s13, 0
	s_cmp_gt_u32 s18, 41
	s_mov_b64 s[16:17], s[36:37]
	s_barrier
